# LN phase: the four modulation pieces of a row loaded together (all three LN instances), on top of previous LN/epilogue/r2/attention changes
# speedup vs baseline: 1.0237x; 1.0167x over previous
.LBB0_51:
	global_load_dwordx4 v[154:157], v[74:75], off
	global_load_dwordx4 v[158:161], v[76:77], off
	global_load_dwordx4 v[162:165], v[74:75], off offset:1024
	global_load_dwordx4 v[166:169], v[76:77], off offset:1024
	global_load_dwordx4 v[170:173], v[74:75], off offset:2048
	global_load_dwordx4 v[174:177], v[76:77], off offset:2048
	global_load_dwordx4 v[178:181], v[74:75], off offset:3072
	global_load_dwordx4 v[182:185], v[76:77], off offset:3072
	v_add_u32_e32 v0, 0xfffff000, v64
	v_ashrrev_i32_e32 v0, 10, v0
	v_add_u32_e32 v0, 1, v0
	v_cmp_lt_i32_e32 vcc, s33, v64
	s_mov_b32 s2, 0x1000000
	global_load_dwordx4 v[186:189], v[86:87], off offset:1024
	global_load_dwordx4 v[186:189], v[86:87], off offset:2048
	global_load_dwordx4 v[186:189], v[86:87], off offset:3072
	flat_load_dwordx4 v[8:11], v[86:87]
	v_cndmask_b32_e32 v4, 0, v0, vcc
	v_add_u32_e32 v0, s38, v64
	v_cmp_lt_i32_e32 vcc, s6, v0
	v_ashrrev_i32_e32 v5, 31, v4
	v_lshl_add_u64 v[88:89], v[4:5], 0, s[28:29]
	v_cndmask_b32_e32 v0, v0, v64, vcc
	v_add_u32_e32 v1, 0xfffff000, v0
	v_ashrrev_i32_e32 v1, 10, v1
	v_add_u32_e32 v1, 1, v1
	v_cmp_lt_i32_e32 vcc, s33, v0
	v_mad_u64_u32 v[4:5], s[4:5], v88, s7, v[78:79]
	s_nop 0
	v_cndmask_b32_e32 v2, 0, v1, vcc
	v_add_u32_e32 v1, s35, v64
	v_cmp_lt_i32_e32 vcc, s6, v1
	v_mad_i32_i24 v5, v89, s7, v5
	global_load_dwordx4 v[186:189], v[4:5], off offset:1024
	global_load_dwordx4 v[186:189], v[4:5], off offset:2048
	global_load_dwordx4 v[186:189], v[4:5], off offset:3072
	flat_load_dwordx4 v[12:15], v[4:5]
	v_cndmask_b32_e32 v40, v1, v64, vcc
	v_add_u32_e32 v1, 0xfffff000, v40
	v_ashrrev_i32_e32 v1, 10, v1
	v_add_u32_e32 v1, 1, v1
	v_cmp_lt_i32_e32 vcc, s33, v40
	v_ashrrev_i32_e32 v3, 31, v2
	v_lshl_add_u64 v[92:93], v[2:3], 0, s[28:29]
	v_cndmask_b32_e32 v42, 0, v1, vcc
	v_add_u32_e32 v1, s26, v64
	v_cmp_lt_i32_e32 vcc, s6, v1
	s_mov_b64 s[8:9], 0x1000000
	v_mad_u64_u32 v[48:49], s[4:5], v92, s7, v[78:79]
	v_cndmask_b32_e32 v20, v1, v64, vcc
	v_add_u32_e32 v1, 0xfffff000, v20
	v_ashrrev_i32_e32 v1, 10, v1
	v_add_u32_e32 v1, 1, v1
	v_cmp_lt_i32_e32 vcc, s33, v20
	v_lshlrev_b32_e32 v152, 1, v66
	v_mad_i32_i24 v49, v93, s7, v49
	v_cndmask_b32_e32 v22, 0, v1, vcc
	v_add_co_u32_e32 v6, vcc, s2, v84
	s_brev_b32 s2, 64
	s_nop 0
	v_addc_co_u32_e32 v7, vcc, 0, v85, vcc
	v_add_co_u32_e32 v24, vcc, s2, v84
	global_load_dwordx2 v[186:187], v[6:7], off offset:512
	global_load_dwordx2 v[186:187], v[6:7], off offset:1024
	global_load_dwordx2 v[186:187], v[6:7], off offset:1536
	flat_load_dwordx2 v[16:17], v[6:7]
	s_nop 0
	v_addc_co_u32_e32 v25, vcc, 0, v85, vcc
	global_load_dwordx2 v[186:187], v[24:25], off offset:512
	global_load_dwordx2 v[186:187], v[24:25], off offset:1024
	global_load_dwordx2 v[186:187], v[24:25], off offset:1536
	flat_load_dwordx2 v[26:27], v[24:25]
	v_lshlrev_b32_e32 v104, 1, v68
	v_mov_b32_e32 v105, v153
	v_lshlrev_b32_e32 v106, 1, v70
	v_mov_b32_e32 v107, v153
	v_lshlrev_b32_e32 v120, 1, v72
	v_mov_b32_e32 v121, v153
	v_ashrrev_i32_e32 v41, 31, v40
	v_ashrrev_i32_e32 v43, 31, v42
	v_lshlrev_b64 v[96:97], 11, v[40:41]
	v_lshl_add_u64 v[98:99], v[42:43], 0, s[28:29]
	v_lshl_add_u64 v[42:43], s[56:57], 0, v[96:97]
	v_ashrrev_i32_e32 v21, 31, v20
	v_ashrrev_i32_e32 v23, 31, v22
	s_mov_b32 s2, 0x3727c5ac
	s_waitcnt vmcnt(0) lgkmcnt(0)
	v_lshlrev_b32_e32 v18, 16, v16
	v_and_b32_e32 v19, 0xffff0000, v16
	v_lshlrev_b32_e32 v16, 16, v17
	v_and_b32_e32 v17, 0xffff0000, v17
	v_lshlrev_b32_e32 v28, 16, v26
	v_and_b32_e32 v29, 0xffff0000, v26
	v_lshlrev_b32_e32 v26, 16, v27
	v_and_b32_e32 v27, 0xffff0000, v27
	v_pk_add_f32 v[18:19], v[18:19], v[28:29]
	v_pk_add_f32 v[16:17], v[16:17], v[26:27]
	v_pk_mul_f32 v[12:13], v[12:13], v[18:19]
	v_pk_mul_f32 v[14:15], v[14:15], v[16:17]
	v_pk_fma_f32 v[8:9], v[8:9], s[42:43], v[12:13] op_sel_hi:[1,0,1]
	v_pk_fma_f32 v[10:11], v[10:11], s[42:43], v[14:15] op_sel_hi:[1,0,1]
	v_mov_b32_e32 v14, v8
	v_pk_mov_b32 v[12:13], v[8:9], v[10:11] op_sel:[1,0]
	v_mov_b32_e32 v15, v11
	v_pk_add_f32 v[12:13], v[12:13], v[14:15]
	s_nop 0
	v_add_f32_e32 v1, v12, v13
	flat_load_dwordx4 v[12:15], v[86:87] offset:1024
	flat_load_dwordx4 v[16:19], v[4:5] offset:1024
	flat_load_dwordx2 v[26:27], v[6:7] offset:512
	flat_load_dwordx2 v[32:33], v[24:25] offset:512
	v_add_f32_e32 v28, 0, v1
	v_ashrrev_i32_e32 v1, 31, v0
	v_lshlrev_b64 v[90:91], 11, v[0:1]
	v_lshlrev_b64 v[2:3], 12, v[0:1]
	s_waitcnt vmcnt(0) lgkmcnt(0)
	v_lshlrev_b32_e32 v30, 16, v26
	v_and_b32_e32 v31, 0xffff0000, v26
	v_lshlrev_b32_e32 v26, 16, v27
	v_and_b32_e32 v27, 0xffff0000, v27
	v_lshlrev_b32_e32 v34, 16, v32
	v_and_b32_e32 v35, 0xffff0000, v32
	v_lshlrev_b32_e32 v32, 16, v33
	v_and_b32_e32 v33, 0xffff0000, v33
	v_pk_add_f32 v[30:31], v[30:31], v[34:35]
	v_pk_add_f32 v[26:27], v[26:27], v[32:33]
	v_pk_mul_f32 v[16:17], v[16:17], v[30:31]
	v_pk_mul_f32 v[18:19], v[18:19], v[26:27]
	v_pk_fma_f32 v[12:13], v[12:13], s[42:43], v[16:17] op_sel_hi:[1,0,1]
	v_pk_fma_f32 v[14:15], v[14:15], s[42:43], v[18:19] op_sel_hi:[1,0,1]
	v_mov_b32_e32 v18, v12
	v_pk_mov_b32 v[16:17], v[12:13], v[14:15] op_sel:[1,0]
	v_mov_b32_e32 v19, v15
	v_pk_add_f32 v[16:17], v[16:17], v[18:19]
	s_nop 0
	v_pk_add_f32 v[30:31], v[16:17], v[16:17] op_sel:[0,1] op_sel_hi:[1,0]
	flat_load_dwordx4 v[16:19], v[86:87] offset:2048
	flat_load_dwordx4 v[32:35], v[4:5] offset:2048
	flat_load_dwordx2 v[26:27], v[6:7] offset:1024
	flat_load_dwordx2 v[38:39], v[24:25] offset:1024
	s_waitcnt vmcnt(0) lgkmcnt(0)
	v_lshlrev_b32_e32 v36, 16, v26
	v_and_b32_e32 v37, 0xffff0000, v26
	v_lshlrev_b32_e32 v44, 16, v38
	v_and_b32_e32 v45, 0xffff0000, v38
	v_lshlrev_b32_e32 v26, 16, v27
	v_and_b32_e32 v27, 0xffff0000, v27
	v_lshlrev_b32_e32 v38, 16, v39
	v_and_b32_e32 v39, 0xffff0000, v39
	v_pk_add_f32 v[36:37], v[36:37], v[44:45]
	v_pk_add_f32 v[26:27], v[26:27], v[38:39]
	v_pk_mul_f32 v[32:33], v[32:33], v[36:37]
	v_pk_mul_f32 v[26:27], v[34:35], v[26:27]
	v_pk_fma_f32 v[16:17], v[16:17], s[42:43], v[32:33] op_sel_hi:[1,0,1]
	flat_load_dwordx4 v[32:35], v[86:87] offset:3072
	flat_load_dwordx4 v[36:39], v[4:5] offset:3072
	s_nop 0
	flat_load_dwordx2 v[4:5], v[6:7] offset:1536
	v_pk_fma_f32 v[18:19], v[18:19], s[42:43], v[26:27] op_sel_hi:[1,0,1]
	flat_load_dwordx2 v[24:25], v[24:25] offset:1536
	v_add_f32_e32 v44, v16, v17
	v_add_f32_e32 v46, v18, v19
	s_waitcnt vmcnt(0) lgkmcnt(0)
	v_lshlrev_b32_e32 v6, 16, v4
	v_and_b32_e32 v7, 0xffff0000, v4
	v_lshlrev_b32_e32 v26, 16, v24
	v_and_b32_e32 v27, 0xffff0000, v24
	v_lshlrev_b32_e32 v4, 16, v5
	v_and_b32_e32 v5, 0xffff0000, v5
	v_lshlrev_b32_e32 v24, 16, v25
	v_and_b32_e32 v25, 0xffff0000, v25
	v_pk_add_f32 v[6:7], v[6:7], v[26:27]
	v_pk_add_f32 v[4:5], v[4:5], v[24:25]
	v_pk_mul_f32 v[6:7], v[36:37], v[6:7]
	v_pk_mul_f32 v[4:5], v[38:39], v[4:5]
	v_pk_fma_f32 v[24:25], v[32:33], s[42:43], v[6:7] op_sel_hi:[1,0,1]
	v_pk_fma_f32 v[26:27], v[34:35], s[42:43], v[4:5] op_sel_hi:[1,0,1]
	v_mov_b32_e32 v29, v24
	v_mov_b32_e32 v31, v25
	v_pk_add_f32 v[4:5], v[28:29], v[30:31]
	v_mov_b32_e32 v45, v26
	v_mov_b32_e32 v47, v27
	v_lshl_add_u64 v[28:29], s[56:57], 0, v[90:91]
	v_pk_add_f32 v[6:7], v[44:45], v[46:47]
	v_lshl_add_u64 v[44:45], v[28:29], 0, s[8:9]
	v_pk_add_f32 v[4:5], v[4:5], v[6:7]
	v_lshl_add_u64 v[52:53], v[28:29], 0, v[152:153]
	v_lshl_add_u64 v[34:35], v[44:45], 0, v[152:153]
	v_add_f32_e32 v122, v4, v5
	global_load_dwordx4 v[186:189], v[48:49], off offset:1024
	global_load_dwordx4 v[186:189], v[48:49], off offset:2048
	global_load_dwordx4 v[186:189], v[48:49], off offset:3072
	flat_load_dwordx4 v[4:7], v[48:49]
	global_load_dwordx2 v[186:187], v[52:53], off offset:512
	global_load_dwordx2 v[186:187], v[52:53], off offset:1024
	global_load_dwordx2 v[186:187], v[52:53], off offset:1536
	flat_load_dwordx2 v[28:29], v[52:53]
	v_lshl_add_u64 v[32:33], v[80:81], 0, v[2:3]
	global_load_dwordx2 v[186:187], v[34:35], off offset:512
	global_load_dwordx2 v[186:187], v[34:35], off offset:1024
	global_load_dwordx2 v[186:187], v[34:35], off offset:1536
	flat_load_dwordx2 v[34:35], v[34:35]
	v_lshl_add_u64 v[38:39], v[44:45], 0, v[104:105]
	global_load_dwordx4 v[186:189], v[32:33], off offset:1024
	global_load_dwordx4 v[186:189], v[32:33], off offset:2048
	global_load_dwordx4 v[186:189], v[32:33], off offset:3072
	flat_load_dwordx4 v[0:3], v[32:33]
	v_lshl_add_u64 v[54:55], v[44:45], 0, v[106:107]
	v_lshl_add_u64 v[44:45], v[44:45], 0, v[120:121]
	s_waitcnt vmcnt(0) lgkmcnt(0)
	v_lshlrev_b32_e32 v30, 16, v28
	v_and_b32_e32 v31, 0xffff0000, v28
	v_lshlrev_b32_e32 v28, 16, v29
	v_and_b32_e32 v29, 0xffff0000, v29
	v_lshlrev_b32_e32 v36, 16, v34
	v_and_b32_e32 v37, 0xffff0000, v34
	v_lshlrev_b32_e32 v34, 16, v35
	v_and_b32_e32 v35, 0xffff0000, v35
	v_pk_add_f32 v[30:31], v[30:31], v[36:37]
	v_pk_add_f32 v[28:29], v[28:29], v[34:35]
	v_pk_mul_f32 v[4:5], v[4:5], v[30:31]
	v_pk_mul_f32 v[6:7], v[6:7], v[28:29]
	v_pk_fma_f32 v[28:29], v[0:1], s[42:43], v[4:5] op_sel_hi:[1,0,1]
	v_pk_fma_f32 v[30:31], v[2:3], s[42:43], v[6:7] op_sel_hi:[1,0,1]
	v_mov_b32_e32 v2, v28
	v_pk_mov_b32 v[0:1], v[28:29], v[30:31] op_sel:[1,0]
	v_mov_b32_e32 v3, v31
	v_pk_add_f32 v[0:1], v[0:1], v[2:3]
	s_nop 0
	v_add_f32_e32 v0, v0, v1
	v_add_f32_e32 v46, 0, v0
	flat_load_dwordx4 v[0:3], v[32:33] offset:1024
	flat_load_dwordx4 v[4:7], v[48:49] offset:1024
	flat_load_dwordx2 v[34:35], v[52:53] offset:512
	s_waitcnt vmcnt(0) lgkmcnt(0)
	v_lshlrev_b32_e32 v36, 16, v34
	flat_load_dwordx2 v[38:39], v[38:39]
	v_and_b32_e32 v37, 0xffff0000, v34
	v_lshlrev_b32_e32 v34, 16, v35
	v_and_b32_e32 v35, 0xffff0000, v35
	s_waitcnt vmcnt(0) lgkmcnt(0)
	v_lshlrev_b32_e32 v50, 16, v38
	v_and_b32_e32 v51, 0xffff0000, v38
	v_lshlrev_b32_e32 v38, 16, v39
	v_and_b32_e32 v39, 0xffff0000, v39
	v_pk_add_f32 v[36:37], v[36:37], v[50:51]
	v_pk_add_f32 v[34:35], v[34:35], v[38:39]
	v_pk_mul_f32 v[4:5], v[4:5], v[36:37]
	v_pk_mul_f32 v[6:7], v[6:7], v[34:35]
	v_pk_fma_f32 v[38:39], v[0:1], s[42:43], v[4:5] op_sel_hi:[1,0,1]
	v_pk_fma_f32 v[60:61], v[2:3], s[42:43], v[6:7] op_sel_hi:[1,0,1]
	v_mov_b32_e32 v2, v38
	v_pk_mov_b32 v[0:1], v[38:39], v[60:61] op_sel:[1,0]
	v_mov_b32_e32 v3, v61
	v_pk_add_f32 v[0:1], v[0:1], v[2:3]
	s_nop 0
	v_pk_add_f32 v[50:51], v[0:1], v[0:1] op_sel:[0,1] op_sel_hi:[1,0]
	flat_load_dwordx4 v[0:3], v[32:33] offset:2048
	flat_load_dwordx4 v[4:7], v[48:49] offset:2048
	flat_load_dwordx2 v[34:35], v[52:53] offset:1024
	s_waitcnt vmcnt(0) lgkmcnt(0)
	v_lshlrev_b32_e32 v36, 16, v34
	flat_load_dwordx2 v[54:55], v[54:55]
	v_and_b32_e32 v37, 0xffff0000, v34
	v_lshlrev_b32_e32 v34, 16, v35
	v_and_b32_e32 v35, 0xffff0000, v35
	s_waitcnt vmcnt(0) lgkmcnt(0)
	v_lshlrev_b32_e32 v56, 16, v54
	v_and_b32_e32 v57, 0xffff0000, v54
	v_lshlrev_b32_e32 v54, 16, v55
	v_and_b32_e32 v55, 0xffff0000, v55
	v_pk_add_f32 v[34:35], v[34:35], v[54:55]
	v_pk_add_f32 v[36:37], v[36:37], v[56:57]
	v_pk_mul_f32 v[6:7], v[6:7], v[34:35]
	v_pk_mul_f32 v[4:5], v[4:5], v[36:37]
	v_pk_fma_f32 v[36:37], v[2:3], s[42:43], v[6:7] op_sel_hi:[1,0,1]
	v_pk_fma_f32 v[34:35], v[0:1], s[42:43], v[4:5] op_sel_hi:[1,0,1]
	flat_load_dwordx4 v[0:3], v[32:33] offset:3072
	flat_load_dwordx4 v[4:7], v[48:49] offset:3072
	s_nop 0
	flat_load_dwordx2 v[52:53], v[52:53] offset:1536
	v_add_f32_e32 v54, v34, v35
	flat_load_dwordx2 v[44:45], v[44:45]
	v_add_f32_e32 v56, v36, v37
	s_waitcnt vmcnt(0) lgkmcnt(0)
	v_lshlrev_b32_e32 v48, 16, v52
	v_and_b32_e32 v49, 0xffff0000, v52
	v_lshlrev_b32_e32 v58, 16, v44
	v_and_b32_e32 v59, 0xffff0000, v44
	v_lshlrev_b32_e32 v52, 16, v53
	v_and_b32_e32 v53, 0xffff0000, v53
	v_lshlrev_b32_e32 v44, 16, v45
	v_and_b32_e32 v45, 0xffff0000, v45
	v_pk_add_f32 v[48:49], v[48:49], v[58:59]
	v_pk_add_f32 v[44:45], v[52:53], v[44:45]
	v_pk_mul_f32 v[4:5], v[4:5], v[48:49]
	v_pk_mul_f32 v[6:7], v[6:7], v[44:45]
	v_pk_fma_f32 v[62:63], v[0:1], s[42:43], v[4:5] op_sel_hi:[1,0,1]
	v_pk_fma_f32 v[118:119], v[2:3], s[42:43], v[6:7] op_sel_hi:[1,0,1]
	v_mov_b32_e32 v47, v62
	v_mov_b32_e32 v51, v63
	v_pk_add_f32 v[0:1], v[46:47], v[50:51]
	v_mov_b32_e32 v55, v118
	v_mov_b32_e32 v57, v119
	v_lshl_add_u64 v[44:45], v[42:43], 0, s[8:9]
	v_mad_u64_u32 v[46:47], s[4:5], v98, s7, v[78:79]
	v_pk_add_f32 v[2:3], v[54:55], v[56:57]
	v_mad_i32_i24 v47, v99, s7, v47
	v_lshl_add_u64 v[42:43], v[42:43], 0, v[152:153]
	v_lshl_add_u64 v[52:53], v[44:45], 0, v[152:153]
	v_pk_add_f32 v[0:1], v[0:1], v[2:3]
	global_load_dwordx4 v[186:189], v[46:47], off offset:1024
	global_load_dwordx4 v[186:189], v[46:47], off offset:2048
	global_load_dwordx4 v[186:189], v[46:47], off offset:3072
	flat_load_dwordx4 v[4:7], v[46:47]
	global_load_dwordx2 v[186:187], v[42:43], off offset:512
	global_load_dwordx2 v[186:187], v[42:43], off offset:1024
	global_load_dwordx2 v[186:187], v[42:43], off offset:1536
	flat_load_dwordx2 v[48:49], v[42:43]
	v_add_f32_e32 v126, v0, v1
	global_load_dwordx2 v[186:187], v[52:53], off offset:512
	global_load_dwordx2 v[186:187], v[52:53], off offset:1024
	global_load_dwordx2 v[186:187], v[52:53], off offset:1536
	flat_load_dwordx2 v[52:53], v[52:53]
	v_lshlrev_b64 v[0:1], 12, v[40:41]
	v_lshl_add_u64 v[40:41], v[80:81], 0, v[0:1]
	global_load_dwordx4 v[186:189], v[40:41], off offset:1024
	global_load_dwordx4 v[186:189], v[40:41], off offset:2048
	global_load_dwordx4 v[186:189], v[40:41], off offset:3072
	flat_load_dwordx4 v[0:3], v[40:41]
	v_lshl_add_u64 v[56:57], v[44:45], 0, v[104:105]
	v_lshl_add_u64 v[102:103], v[44:45], 0, v[106:107]
	v_lshl_add_u64 v[44:45], v[44:45], 0, v[120:121]
	s_waitcnt vmcnt(0) lgkmcnt(0)
	v_lshlrev_b32_e32 v50, 16, v48
	v_and_b32_e32 v51, 0xffff0000, v48
	v_lshlrev_b32_e32 v48, 16, v49
	v_and_b32_e32 v49, 0xffff0000, v49
	v_lshlrev_b32_e32 v54, 16, v52
	v_and_b32_e32 v55, 0xffff0000, v52
	v_lshlrev_b32_e32 v52, 16, v53
	v_and_b32_e32 v53, 0xffff0000, v53
	v_pk_add_f32 v[50:51], v[50:51], v[54:55]
	v_pk_add_f32 v[48:49], v[48:49], v[52:53]
	v_pk_mul_f32 v[4:5], v[4:5], v[50:51]
	v_pk_mul_f32 v[6:7], v[6:7], v[48:49]
	v_pk_fma_f32 v[50:51], v[0:1], s[42:43], v[4:5] op_sel_hi:[1,0,1]
	v_pk_fma_f32 v[52:53], v[2:3], s[42:43], v[6:7] op_sel_hi:[1,0,1]
	v_mov_b32_e32 v2, v50
	v_pk_mov_b32 v[0:1], v[50:51], v[52:53] op_sel:[1,0]
	v_mov_b32_e32 v3, v53
	v_pk_add_f32 v[0:1], v[0:1], v[2:3]
	s_nop 0
	v_add_f32_e32 v0, v0, v1
	v_add_f32_e32 v94, 0, v0
	flat_load_dwordx4 v[0:3], v[40:41] offset:1024
	flat_load_dwordx4 v[4:7], v[46:47] offset:1024
	flat_load_dwordx2 v[48:49], v[42:43] offset:512
	s_waitcnt vmcnt(0) lgkmcnt(0)
	v_lshlrev_b32_e32 v54, 16, v48
	flat_load_dwordx2 v[56:57], v[56:57]
	v_and_b32_e32 v55, 0xffff0000, v48
	v_lshlrev_b32_e32 v48, 16, v49
	v_and_b32_e32 v49, 0xffff0000, v49
	s_waitcnt vmcnt(0) lgkmcnt(0)
	v_lshlrev_b32_e32 v58, 16, v56
	v_and_b32_e32 v59, 0xffff0000, v56
	v_lshlrev_b32_e32 v56, 16, v57
	v_and_b32_e32 v57, 0xffff0000, v57
	v_pk_add_f32 v[54:55], v[54:55], v[58:59]
	v_pk_add_f32 v[48:49], v[48:49], v[56:57]
	v_pk_mul_f32 v[4:5], v[4:5], v[54:55]
	v_pk_mul_f32 v[6:7], v[6:7], v[48:49]
	v_pk_fma_f32 v[56:57], v[0:1], s[42:43], v[4:5] op_sel_hi:[1,0,1]
	v_pk_fma_f32 v[58:59], v[2:3], s[42:43], v[6:7] op_sel_hi:[1,0,1]
	v_mov_b32_e32 v2, v56
	v_pk_mov_b32 v[0:1], v[56:57], v[58:59] op_sel:[1,0]
	v_mov_b32_e32 v3, v59
	v_pk_add_f32 v[0:1], v[0:1], v[2:3]
	s_nop 0
	v_pk_add_f32 v[100:101], v[0:1], v[0:1] op_sel:[0,1] op_sel_hi:[1,0]
	flat_load_dwordx4 v[0:3], v[40:41] offset:2048
	flat_load_dwordx4 v[4:7], v[46:47] offset:2048
	flat_load_dwordx2 v[48:49], v[42:43] offset:1024
	s_waitcnt vmcnt(0) lgkmcnt(0)
	v_lshlrev_b32_e32 v54, 16, v48
	flat_load_dwordx2 v[102:103], v[102:103]
	v_and_b32_e32 v55, 0xffff0000, v48
	v_lshlrev_b32_e32 v48, 16, v49
	v_and_b32_e32 v49, 0xffff0000, v49
	s_waitcnt vmcnt(0) lgkmcnt(0)
	v_lshlrev_b32_e32 v108, 16, v102
	v_and_b32_e32 v109, 0xffff0000, v102
	v_lshlrev_b32_e32 v102, 16, v103
	v_and_b32_e32 v103, 0xffff0000, v103
	v_pk_add_f32 v[48:49], v[48:49], v[102:103]
	v_pk_add_f32 v[54:55], v[54:55], v[108:109]
	v_pk_mul_f32 v[6:7], v[6:7], v[48:49]
	v_pk_mul_f32 v[4:5], v[4:5], v[54:55]
	v_pk_fma_f32 v[116:117], v[2:3], s[42:43], v[6:7] op_sel_hi:[1,0,1]
	v_pk_fma_f32 v[54:55], v[0:1], s[42:43], v[4:5] op_sel_hi:[1,0,1]
	flat_load_dwordx4 v[0:3], v[40:41] offset:3072
	flat_load_dwordx4 v[4:7], v[46:47] offset:3072
	s_nop 0
	flat_load_dwordx2 v[42:43], v[42:43] offset:1536
	v_add_f32_e32 v102, v54, v55
	flat_load_dwordx2 v[44:45], v[44:45]
	v_add_f32_e32 v108, v116, v117
	s_waitcnt vmcnt(0) lgkmcnt(0)
	v_lshlrev_b32_e32 v46, 16, v42
	v_and_b32_e32 v47, 0xffff0000, v42
	v_lshlrev_b32_e32 v42, 16, v43
	v_and_b32_e32 v43, 0xffff0000, v43
	v_lshlrev_b32_e32 v48, 16, v44
	v_and_b32_e32 v49, 0xffff0000, v44
	v_lshlrev_b32_e32 v44, 16, v45
	v_and_b32_e32 v45, 0xffff0000, v45
	v_pk_add_f32 v[42:43], v[42:43], v[44:45]
	v_pk_add_f32 v[44:45], v[46:47], v[48:49]
	v_pk_mul_f32 v[6:7], v[6:7], v[42:43]
	v_pk_mul_f32 v[4:5], v[4:5], v[44:45]
	v_pk_fma_f32 v[48:49], v[2:3], s[42:43], v[6:7] op_sel_hi:[1,0,1]
	v_pk_fma_f32 v[46:47], v[0:1], s[42:43], v[4:5] op_sel_hi:[1,0,1]
	v_mov_b32_e32 v103, v48
	v_mov_b32_e32 v95, v46
	v_mov_b32_e32 v101, v47
	v_mov_b32_e32 v109, v49
	v_pk_add_f32 v[0:1], v[94:95], v[100:101]
	v_pk_add_f32 v[2:3], v[102:103], v[108:109]
	v_lshlrev_b64 v[94:95], 11, v[20:21]
	v_pk_add_f32 v[0:1], v[0:1], v[2:3]
	v_lshl_add_u64 v[100:101], v[22:23], 0, s[28:29]
	v_add_f32_e32 v125, v0, v1
	v_lshlrev_b64 v[0:1], 12, v[20:21]
	v_lshl_add_u64 v[20:21], s[56:57], 0, v[94:95]
	v_lshl_add_u64 v[22:23], v[20:21], 0, s[8:9]
	v_mad_u64_u32 v[128:129], s[4:5], v100, s7, v[78:79]
	v_mad_i32_i24 v129, v101, s7, v129
	v_lshl_add_u64 v[20:21], v[20:21], 0, v[152:153]
	v_lshl_add_u64 v[108:109], v[22:23], 0, v[152:153]
	global_load_dwordx4 v[186:189], v[128:129], off offset:1024
	global_load_dwordx4 v[186:189], v[128:129], off offset:2048
	global_load_dwordx4 v[186:189], v[128:129], off offset:3072
	flat_load_dwordx4 v[4:7], v[128:129]
	global_load_dwordx2 v[186:187], v[20:21], off offset:512
	global_load_dwordx2 v[186:187], v[20:21], off offset:1024
	global_load_dwordx2 v[186:187], v[20:21], off offset:1536
	flat_load_dwordx2 v[42:43], v[20:21]
	v_lshl_add_u64 v[102:103], v[80:81], 0, v[0:1]
	global_load_dwordx2 v[186:187], v[108:109], off offset:512
	global_load_dwordx2 v[186:187], v[108:109], off offset:1024
	global_load_dwordx2 v[186:187], v[108:109], off offset:1536
	flat_load_dwordx2 v[108:109], v[108:109]
	v_lshl_add_u64 v[104:105], v[22:23], 0, v[104:105]
	global_load_dwordx4 v[186:189], v[102:103], off offset:1024
	global_load_dwordx4 v[186:189], v[102:103], off offset:2048
	global_load_dwordx4 v[186:189], v[102:103], off offset:3072
	flat_load_dwordx4 v[0:3], v[102:103]
	v_lshl_add_u64 v[106:107], v[22:23], 0, v[106:107]
	v_lshl_add_u64 v[22:23], v[22:23], 0, v[120:121]
	v_readlane_b32 s4, v254, 33
	v_readlane_b32 s5, v254, 34
	s_waitcnt vmcnt(0) lgkmcnt(0)
	v_lshlrev_b32_e32 v44, 16, v42
	v_and_b32_e32 v45, 0xffff0000, v42
	v_lshlrev_b32_e32 v42, 16, v43
	v_and_b32_e32 v43, 0xffff0000, v43
	v_lshlrev_b32_e32 v110, 16, v108
	v_and_b32_e32 v111, 0xffff0000, v108
	v_lshlrev_b32_e32 v108, 16, v109
	v_and_b32_e32 v109, 0xffff0000, v109
	v_pk_add_f32 v[44:45], v[44:45], v[110:111]
	v_pk_add_f32 v[42:43], v[42:43], v[108:109]
	v_pk_mul_f32 v[4:5], v[4:5], v[44:45]
	v_pk_mul_f32 v[6:7], v[6:7], v[42:43]
	v_pk_fma_f32 v[44:45], v[0:1], s[42:43], v[4:5] op_sel_hi:[1,0,1]
	v_pk_fma_f32 v[114:115], v[2:3], s[42:43], v[6:7] op_sel_hi:[1,0,1]
	v_mov_b32_e32 v2, v44
	v_pk_mov_b32 v[0:1], v[44:45], v[114:115] op_sel:[1,0]
	v_mov_b32_e32 v3, v115
	v_pk_add_f32 v[0:1], v[0:1], v[2:3]
	s_nop 0
	v_add_f32_e32 v0, v0, v1
	v_add_f32_e32 v130, 0, v0
	flat_load_dwordx4 v[0:3], v[102:103] offset:1024
	flat_load_dwordx4 v[4:7], v[128:129] offset:1024
	flat_load_dwordx2 v[42:43], v[20:21] offset:512
	s_waitcnt vmcnt(0) lgkmcnt(0)
	v_lshlrev_b32_e32 v108, 16, v42
	flat_load_dwordx2 v[104:105], v[104:105]
	v_and_b32_e32 v109, 0xffff0000, v42
	v_lshlrev_b32_e32 v42, 16, v43
	v_and_b32_e32 v43, 0xffff0000, v43
	s_waitcnt vmcnt(0) lgkmcnt(0)
	v_lshlrev_b32_e32 v110, 16, v104
	v_and_b32_e32 v111, 0xffff0000, v104
	v_lshlrev_b32_e32 v104, 16, v105
	v_and_b32_e32 v105, 0xffff0000, v105
	v_pk_add_f32 v[108:109], v[108:109], v[110:111]
	v_pk_add_f32 v[42:43], v[42:43], v[104:105]
	v_pk_mul_f32 v[4:5], v[4:5], v[108:109]
	v_pk_mul_f32 v[6:7], v[6:7], v[42:43]
	v_pk_fma_f32 v[42:43], v[0:1], s[42:43], v[4:5] op_sel_hi:[1,0,1]
	v_pk_fma_f32 v[112:113], v[2:3], s[42:43], v[6:7] op_sel_hi:[1,0,1]
	v_mov_b32_e32 v2, v42
	v_pk_mov_b32 v[0:1], v[42:43], v[112:113] op_sel:[1,0]
	v_mov_b32_e32 v3, v113
	v_pk_add_f32 v[0:1], v[0:1], v[2:3]
	s_nop 0
	v_pk_add_f32 v[132:133], v[0:1], v[0:1] op_sel:[0,1] op_sel_hi:[1,0]
	flat_load_dwordx4 v[0:3], v[102:103] offset:2048
	flat_load_dwordx4 v[4:7], v[128:129] offset:2048
	flat_load_dwordx2 v[104:105], v[20:21] offset:1024
	s_waitcnt vmcnt(0) lgkmcnt(0)
	v_lshlrev_b32_e32 v108, 16, v104
	flat_load_dwordx2 v[106:107], v[106:107]
	v_and_b32_e32 v109, 0xffff0000, v104
	v_lshlrev_b32_e32 v104, 16, v105
	v_and_b32_e32 v105, 0xffff0000, v105
	s_waitcnt vmcnt(0) lgkmcnt(0)
	v_lshlrev_b32_e32 v110, 16, v106
	v_and_b32_e32 v111, 0xffff0000, v106
	v_lshlrev_b32_e32 v106, 16, v107
	v_and_b32_e32 v107, 0xffff0000, v107
	v_pk_add_f32 v[104:105], v[104:105], v[106:107]
	v_pk_add_f32 v[106:107], v[108:109], v[110:111]
	v_pk_mul_f32 v[6:7], v[6:7], v[104:105]
	v_pk_mul_f32 v[4:5], v[4:5], v[106:107]
	v_pk_fma_f32 v[110:111], v[2:3], s[42:43], v[6:7] op_sel_hi:[1,0,1]
	v_pk_fma_f32 v[108:109], v[0:1], s[42:43], v[4:5] op_sel_hi:[1,0,1]
	flat_load_dwordx4 v[0:3], v[102:103] offset:3072
	flat_load_dwordx4 v[4:7], v[128:129] offset:3072
	s_nop 0
	flat_load_dwordx2 v[20:21], v[20:21] offset:1536
	v_add_f32_e32 v134, v108, v109
	flat_load_dwordx2 v[22:23], v[22:23]
	v_add_f32_e32 v136, v110, v111
	s_waitcnt vmcnt(0) lgkmcnt(0)
	v_lshlrev_b32_e32 v104, 16, v20
	v_and_b32_e32 v105, 0xffff0000, v20
	v_lshlrev_b32_e32 v20, 16, v21
	v_and_b32_e32 v21, 0xffff0000, v21
	v_lshlrev_b32_e32 v106, 16, v22
	v_and_b32_e32 v107, 0xffff0000, v22
	v_lshlrev_b32_e32 v22, 16, v23
	v_and_b32_e32 v23, 0xffff0000, v23
	v_pk_add_f32 v[20:21], v[20:21], v[22:23]
	v_pk_add_f32 v[22:23], v[104:105], v[106:107]
	v_pk_mul_f32 v[6:7], v[6:7], v[20:21]
	v_pk_mul_f32 v[4:5], v[4:5], v[22:23]
	v_pk_fma_f32 v[106:107], v[2:3], s[42:43], v[6:7] op_sel_hi:[1,0,1]
	v_pk_fma_f32 v[104:105], v[0:1], s[42:43], v[4:5] op_sel_hi:[1,0,1]
	v_mov_b32_e32 v135, v106
	v_mov_b32_e32 v131, v104
	v_mov_b32_e32 v133, v105
	v_mov_b32_e32 v137, v107
	v_pk_add_f32 v[0:1], v[130:131], v[132:133]
	v_pk_add_f32 v[2:3], v[134:135], v[136:137]
	ds_bpermute_b32 v22, v67, v126
	v_pk_add_f32 v[0:1], v[0:1], v[2:3]
	s_waitcnt lgkmcnt(0)
	v_add_f32_e32 v22, v126, v22
	v_add_f32_e32 v65, v0, v1
	ds_bpermute_b32 v0, v67, v122
	ds_bpermute_b32 v23, v69, v22
	s_waitcnt lgkmcnt(1)
	v_add_f32_e32 v0, v122, v0
	ds_bpermute_b32 v1, v69, v0
	s_waitcnt lgkmcnt(1)
	v_add_f32_e32 v22, v22, v23
	ds_bpermute_b32 v23, v71, v22
	s_waitcnt lgkmcnt(1)
	v_add_f32_e32 v0, v0, v1
	ds_bpermute_b32 v1, v71, v0
	s_waitcnt lgkmcnt(1)
	v_add_f32_e32 v22, v22, v23
	ds_bpermute_b32 v23, v73, v22
	s_waitcnt lgkmcnt(1)
	v_add_f32_e32 v0, v0, v1
	ds_bpermute_b32 v1, v73, v0
	s_waitcnt lgkmcnt(1)
	v_add_f32_e32 v22, v22, v23
	ds_bpermute_b32 v23, v123, v22
	s_waitcnt lgkmcnt(1)
	v_add_f32_e32 v0, v0, v1
	ds_bpermute_b32 v1, v123, v0
	s_waitcnt lgkmcnt(1)
	v_add_f32_e32 v22, v22, v23
	ds_bpermute_b32 v23, v124, v22
	s_waitcnt lgkmcnt(1)
	v_add_f32_e32 v0, v0, v1
	ds_bpermute_b32 v1, v124, v0
	s_waitcnt lgkmcnt(1)
	v_add_f32_e32 v122, v22, v23
	v_fmamk_f32 v29, v122, 0xba800000, v29
	v_fmac_f32_e32 v28, 0xba800000, v122
	v_fmamk_f32 v31, v122, 0xba800000, v31
	s_waitcnt lgkmcnt(0)
	v_add_f32_e32 v20, v0, v1
	v_fmamk_f32 v9, v20, 0xba800000, v9
	v_fmac_f32_e32 v8, 0xba800000, v20
	v_fmamk_f32 v11, v20, 0xba800000, v11
	v_fmac_f32_e32 v10, 0xba800000, v20
	v_pk_mul_f32 v[0:1], v[10:11], v[10:11]
	v_pk_mul_f32 v[2:3], v[8:9], v[8:9]
	v_fmamk_f32 v13, v20, 0xba800000, v13
	v_pk_mov_b32 v[4:5], v[2:3], v[0:1] op_sel:[1,0]
	v_mov_b32_e32 v3, v1
	v_pk_add_f32 v[0:1], v[4:5], v[2:3]
	v_fmac_f32_e32 v12, 0xba800000, v20
	v_fmamk_f32 v15, v20, 0xba800000, v15
	v_fmac_f32_e32 v14, 0xba800000, v20
	v_pk_add_f32 v[0:1], v[0:1], v[0:1] op_sel_hi:[0,1]
	v_pk_mul_f32 v[2:3], v[14:15], v[14:15]
	v_pk_mul_f32 v[4:5], v[12:13], v[12:13]
	v_fmac_f32_e32 v16, 0xba800000, v20
	v_pk_mov_b32 v[6:7], v[4:5], v[2:3] op_sel:[1,0]
	v_mov_b32_e32 v5, v3
	v_fmamk_f32 v17, v20, 0xba800000, v17
	v_fmac_f32_e32 v18, 0xba800000, v20
	v_mul_f32_e32 v0, v16, v16
	v_pk_add_f32 v[2:3], v[6:7], v[4:5]
	v_fmamk_f32 v19, v20, 0xba800000, v19
	v_pk_fma_f32 v[4:5], v[16:17], v[16:17], v[0:1] op_sel_hi:[1,1,0]
	v_mul_f32_e32 v0, v18, v18
	v_pk_add_f32 v[2:3], v[2:3], v[2:3] op_sel_hi:[0,1]
	v_pk_fma_f32 v[6:7], v[18:19], v[18:19], v[0:1] op_sel_hi:[1,1,0]
	v_fmamk_f32 v27, v20, 0xba800000, v27
	v_fmac_f32_e32 v26, 0xba800000, v20
	v_fmamk_f32 v25, v20, 0xba800000, v25
	v_fmac_f32_e32 v24, 0xba800000, v20
	v_mul_f32_e32 v4, v24, v24
	v_mul_f32_e32 v6, v25, v25
	v_mul_f32_e32 v0, v26, v26
	v_mul_f32_e32 v2, v27, v27
	v_pk_add_f32 v[4:5], v[4:5], v[6:7]
	v_pk_add_f32 v[0:1], v[0:1], v[2:3]
	v_fmac_f32_e32 v30, 0xba800000, v122
	v_pk_add_f32 v[20:21], v[4:5], v[0:1]
	v_mov_b64_e32 v[0:1], v[154:155]
	v_mov_b64_e32 v[2:3], v[156:157]
	v_mov_b64_e32 v[4:5], v[158:159]
	v_mov_b64_e32 v[6:7], v[160:161]
	v_pk_mul_f32 v[22:23], v[30:31], v[30:31]
	v_pk_mul_f32 v[120:121], v[28:29], v[28:29]
	v_fmamk_f32 v39, v122, 0xba800000, v39
	v_pk_mov_b32 v[126:127], v[120:121], v[22:23] op_sel:[1,0]
	v_mov_b32_e32 v121, v23
	v_pk_add_f32 v[22:23], v[126:127], v[120:121]
	v_fmac_f32_e32 v38, 0xba800000, v122
	v_fmamk_f32 v61, v122, 0xba800000, v61
	v_fmac_f32_e32 v60, 0xba800000, v122
	v_pk_add_f32 v[22:23], v[22:23], v[22:23] op_sel_hi:[0,1]
	v_pk_mul_f32 v[120:121], v[60:61], v[60:61]
	v_pk_mul_f32 v[126:127], v[38:39], v[38:39]
	v_fmac_f32_e32 v34, 0xba800000, v122
	v_pk_mov_b32 v[128:129], v[126:127], v[120:121] op_sel:[1,0]
	v_mov_b32_e32 v127, v121
	v_fmamk_f32 v35, v122, 0xba800000, v35
	v_fmac_f32_e32 v36, 0xba800000, v122
	v_mul_f32_e32 v22, v34, v34
	v_pk_add_f32 v[120:121], v[128:129], v[126:127]
	v_fmamk_f32 v37, v122, 0xba800000, v37
	v_pk_fma_f32 v[126:127], v[34:35], v[34:35], v[22:23] op_sel_hi:[1,1,0]
	v_mul_f32_e32 v22, v36, v36
	v_pk_add_f32 v[120:121], v[120:121], v[120:121] op_sel_hi:[0,1]
	v_pk_fma_f32 v[128:129], v[36:37], v[36:37], v[22:23] op_sel_hi:[1,1,0]
	v_fmamk_f32 v119, v122, 0xba800000, v119
	v_fmac_f32_e32 v118, 0xba800000, v122
	v_fmamk_f32 v63, v122, 0xba800000, v63
	v_fmac_f32_e32 v62, 0xba800000, v122
	v_mul_f32_e32 v126, v62, v62
	v_mul_f32_e32 v128, v63, v63
	v_mul_f32_e32 v22, v118, v118
	v_mul_f32_e32 v120, v119, v119
	v_pk_add_f32 v[126:127], v[126:127], v[128:129]
	v_pk_add_f32 v[22:23], v[22:23], v[120:121]
	v_mov_b32_e32 v121, v20
	v_pk_add_f32 v[22:23], v[126:127], v[22:23]
	s_nop 0
	v_mov_b32_e32 v120, v22
	v_mov_b32_e32 v20, v23
	v_pk_add_f32 v[20:21], v[120:121], v[20:21]
	ds_bpermute_b32 v23, v67, v21
	ds_bpermute_b32 v22, v67, v20
	v_mov_b64_e32 v[120:121], s[2:3]
	s_mov_b32 s2, 0x3a800000
	s_waitcnt lgkmcnt(0)
	v_pk_add_f32 v[20:21], v[20:21], v[22:23]
	ds_bpermute_b32 v23, v69, v21
	ds_bpermute_b32 v22, v69, v20
	s_waitcnt lgkmcnt(0)
	v_pk_add_f32 v[20:21], v[20:21], v[22:23]
	ds_bpermute_b32 v23, v71, v21
	ds_bpermute_b32 v22, v71, v20
	s_waitcnt lgkmcnt(0)
	v_pk_add_f32 v[20:21], v[20:21], v[22:23]
	ds_bpermute_b32 v23, v73, v21
	ds_bpermute_b32 v22, v73, v20
	s_waitcnt lgkmcnt(0)
	v_pk_add_f32 v[20:21], v[20:21], v[22:23]
	ds_bpermute_b32 v23, v123, v21
	ds_bpermute_b32 v22, v123, v20
	s_waitcnt lgkmcnt(0)
	v_pk_add_f32 v[20:21], v[20:21], v[22:23]
	ds_bpermute_b32 v23, v124, v21
	ds_bpermute_b32 v22, v124, v20
	s_waitcnt lgkmcnt(0)
	v_pk_add_f32 v[20:21], v[20:21], v[22:23]
	s_nop 0
	v_pk_fma_f32 v[126:127], v[20:21], s[2:3], v[120:121] op_sel_hi:[1,0,0]
	s_nop 0
	v_mul_f32_e32 v20, 0x4b800000, v127
	v_cmp_gt_f32_e64 s[8:9], s68, v127
	v_cmp_gt_f32_e32 vcc, s68, v126
	s_nop 0
	v_cndmask_b32_e64 v20, v127, v20, s[8:9]
	v_rsq_f32_e32 v20, v20
	s_nop 0
	v_mul_f32_e32 v21, 0x45800000, v20
	v_cndmask_b32_e64 v122, v20, v21, s[8:9]
	v_pk_mul_f32 v[8:9], v[8:9], v[122:123] op_sel_hi:[1,0]
	v_pk_mul_f32 v[10:11], v[10:11], v[122:123] op_sel_hi:[1,0]
	v_pk_fma_f32 v[20:21], v[0:1], v[8:9], v[4:5]
	v_pk_fma_f32 v[22:23], v[2:3], v[10:11], v[6:7]
	flat_store_dwordx4 v[86:87], v[20:23]
	v_mov_b64_e32 v[0:1], v[162:163]
	v_mov_b64_e32 v[2:3], v[164:165]
	v_mov_b64_e32 v[4:5], v[166:167]
	v_mov_b64_e32 v[6:7], v[168:169]
	v_pk_mul_f32 v[8:9], v[14:15], v[122:123] op_sel_hi:[1,0]
	v_pk_mul_f32 v[10:11], v[12:13], v[122:123] op_sel_hi:[1,0]
	v_pk_fma_f32 v[14:15], v[2:3], v[8:9], v[6:7]
	v_pk_fma_f32 v[12:13], v[0:1], v[10:11], v[4:5]
	flat_store_dwordx4 v[86:87], v[12:15] offset:1024
	v_mov_b64_e32 v[0:1], v[170:171]
	v_mov_b64_e32 v[2:3], v[172:173]
	v_mov_b64_e32 v[4:5], v[174:175]
	v_mov_b64_e32 v[6:7], v[176:177]
	v_pk_mul_f32 v[8:9], v[18:19], v[122:123] op_sel_hi:[1,0]
	v_pk_mul_f32 v[10:11], v[16:17], v[122:123] op_sel_hi:[1,0]
	v_pk_mul_f32 v[18:19], v[24:25], v[122:123] op_sel_hi:[1,0]
	v_pk_mul_f32 v[16:17], v[26:27], v[122:123] op_sel_hi:[1,0]
	v_pk_fma_f32 v[4:5], v[0:1], v[10:11], v[4:5]
	v_pk_fma_f32 v[6:7], v[2:3], v[8:9], v[6:7]
	flat_store_dwordx4 v[86:87], v[4:7] offset:2048
	v_mov_b64_e32 v[0:1], v[178:179]
	v_mov_b64_e32 v[2:3], v[180:181]
	v_mov_b64_e32 v[8:9], v[182:183]
	v_mov_b64_e32 v[10:11], v[184:185]
	v_pk_fma_f32 v[0:1], v[0:1], v[18:19], v[8:9]
	v_mul_f32_e32 v8, 0x4b800000, v126
	v_cndmask_b32_e32 v8, v126, v8, vcc
	v_rsq_f32_e32 v8, v8
	v_pk_fma_f32 v[2:3], v[2:3], v[16:17], v[10:11]
	flat_store_dwordx4 v[86:87], v[0:3] offset:3072
	v_mul_f32_e32 v9, 0x45800000, v8
	v_cndmask_b32_e32 v122, v8, v9, vcc
	v_mov_b64_e32 v[8:9], v[154:155]
	v_mov_b64_e32 v[10:11], v[156:157]
	v_mov_b64_e32 v[16:17], v[158:159]
	v_mov_b64_e32 v[18:19], v[160:161]
	v_pk_mul_f32 v[24:25], v[30:31], v[122:123] op_sel_hi:[1,0]
	v_pk_mul_f32 v[26:27], v[28:29], v[122:123] op_sel_hi:[1,0]
	v_pk_mul_f32 v[30:31], v[60:61], v[122:123] op_sel_hi:[1,0]
	v_pk_mul_f32 v[28:29], v[38:39], v[122:123] op_sel_hi:[1,0]
	v_pk_mul_f32 v[36:37], v[36:37], v[122:123] op_sel_hi:[1,0]
	v_pk_mul_f32 v[34:35], v[34:35], v[122:123] op_sel_hi:[1,0]
	v_pk_mul_f32 v[38:39], v[118:119], v[122:123] op_sel_hi:[1,0]
	v_pk_mul_f32 v[60:61], v[62:63], v[122:123] op_sel_hi:[1,0]
	ds_bpermute_b32 v62, v67, v65
	s_waitcnt lgkmcnt(0)
	v_add_f32_e32 v62, v65, v62
	ds_bpermute_b32 v63, v69, v62
	s_waitcnt lgkmcnt(0)
	v_add_f32_e32 v62, v62, v63
	ds_bpermute_b32 v63, v71, v62
	s_waitcnt lgkmcnt(0)
	v_add_f32_e32 v62, v62, v63
	ds_bpermute_b32 v63, v73, v62
	s_waitcnt lgkmcnt(0)
	v_add_f32_e32 v62, v62, v63
	ds_bpermute_b32 v63, v123, v62
	s_waitcnt lgkmcnt(0)
	v_add_f32_e32 v62, v62, v63
	ds_bpermute_b32 v63, v124, v62
	s_waitcnt lgkmcnt(0)
	v_add_f32_e32 v65, v62, v63
	v_fmamk_f32 v45, v65, 0xba800000, v45
	v_fmac_f32_e32 v44, 0xba800000, v65
	v_fmamk_f32 v115, v65, 0xba800000, v115
	v_fmac_f32_e32 v114, 0xba800000, v65
	v_pk_mul_f32 v[62:63], v[114:115], v[114:115]
	v_pk_mul_f32 v[118:119], v[44:45], v[44:45]
	v_fmamk_f32 v43, v65, 0xba800000, v43
	v_pk_mov_b32 v[126:127], v[118:119], v[62:63] op_sel:[1,0]
	v_mov_b32_e32 v119, v63
	v_pk_add_f32 v[62:63], v[126:127], v[118:119]
	v_fmac_f32_e32 v42, 0xba800000, v65
	v_fmamk_f32 v113, v65, 0xba800000, v113
	v_fmac_f32_e32 v112, 0xba800000, v65
	v_pk_add_f32 v[62:63], v[62:63], v[62:63] op_sel_hi:[0,1]
	v_pk_mul_f32 v[118:119], v[112:113], v[112:113]
	v_pk_mul_f32 v[126:127], v[42:43], v[42:43]
	v_fmac_f32_e32 v108, 0xba800000, v65
	v_pk_mov_b32 v[128:129], v[126:127], v[118:119] op_sel:[1,0]
	v_mov_b32_e32 v127, v119
	v_fmamk_f32 v109, v65, 0xba800000, v109
	v_fmac_f32_e32 v110, 0xba800000, v65
	v_mul_f32_e32 v62, v108, v108
	v_pk_add_f32 v[118:119], v[128:129], v[126:127]
	v_fmamk_f32 v111, v65, 0xba800000, v111
	v_pk_fma_f32 v[126:127], v[108:109], v[108:109], v[62:63] op_sel_hi:[1,1,0]
	v_mul_f32_e32 v62, v110, v110
	v_pk_add_f32 v[118:119], v[118:119], v[118:119] op_sel_hi:[0,1]
	v_pk_fma_f32 v[128:129], v[110:111], v[110:111], v[62:63] op_sel_hi:[1,1,0]
	v_fmamk_f32 v107, v65, 0xba800000, v107
	v_fmac_f32_e32 v106, 0xba800000, v65
	v_fmamk_f32 v105, v65, 0xba800000, v105
	v_fmac_f32_e32 v104, 0xba800000, v65
	v_mul_f32_e32 v126, v104, v104
	v_mul_f32_e32 v128, v105, v105
	v_mul_f32_e32 v62, v106, v106
	v_pk_fma_f32 v[8:9], v[8:9], v[26:27], v[16:17]
	v_pk_fma_f32 v[10:11], v[10:11], v[24:25], v[18:19]
	flat_store_dwordx4 v[32:33], v[8:11]
	v_mov_b64_e32 v[16:17], v[162:163]
	v_mov_b64_e32 v[18:19], v[164:165]
	v_mov_b64_e32 v[24:25], v[166:167]
	v_mov_b64_e32 v[26:27], v[168:169]
	v_mul_f32_e32 v118, v107, v107
	v_pk_add_f32 v[126:127], v[126:127], v[128:129]
	v_pk_add_f32 v[62:63], v[62:63], v[118:119]
	v_pk_fma_f32 v[28:29], v[16:17], v[28:29], v[24:25]
	v_pk_fma_f32 v[30:31], v[18:19], v[30:31], v[26:27]
	flat_store_dwordx4 v[32:33], v[28:31] offset:1024
	v_mov_b64_e32 v[16:17], v[170:171]
	v_mov_b64_e32 v[18:19], v[172:173]
	v_mov_b64_e32 v[24:25], v[174:175]
	v_mov_b64_e32 v[26:27], v[176:177]
	v_pk_add_f32 v[62:63], v[126:127], v[62:63]
	v_pk_fma_f32 v[24:25], v[16:17], v[34:35], v[24:25]
	v_pk_fma_f32 v[26:27], v[18:19], v[36:37], v[26:27]
	flat_store_dwordx4 v[32:33], v[24:27] offset:2048
	v_mov_b64_e32 v[16:17], v[178:179]
	v_mov_b64_e32 v[18:19], v[180:181]
	v_mov_b64_e32 v[34:35], v[182:183]
	v_mov_b64_e32 v[36:37], v[184:185]
	v_mov_b32_e32 v118, v62
	v_pk_fma_f32 v[16:17], v[16:17], v[60:61], v[34:35]
	v_pk_fma_f32 v[18:19], v[18:19], v[38:39], v[36:37]
	flat_store_dwordx4 v[32:33], v[16:19] offset:3072
	ds_bpermute_b32 v32, v67, v125
	s_waitcnt lgkmcnt(0)
	v_add_f32_e32 v32, v125, v32
	ds_bpermute_b32 v33, v69, v32
	s_waitcnt lgkmcnt(0)
	v_add_f32_e32 v32, v32, v33
	ds_bpermute_b32 v33, v71, v32
	s_waitcnt lgkmcnt(0)
	v_add_f32_e32 v32, v32, v33
	ds_bpermute_b32 v33, v73, v32
	s_waitcnt lgkmcnt(0)
	v_add_f32_e32 v32, v32, v33
	ds_bpermute_b32 v33, v123, v32
	s_waitcnt lgkmcnt(0)
	v_add_f32_e32 v32, v32, v33
	ds_bpermute_b32 v33, v124, v32
	s_waitcnt lgkmcnt(0)
	v_add_f32_e32 v60, v32, v33
	v_fmamk_f32 v51, v60, 0xba800000, v51
	v_fmac_f32_e32 v50, 0xba800000, v60
	v_fmamk_f32 v53, v60, 0xba800000, v53
	v_fmac_f32_e32 v52, 0xba800000, v60
	v_pk_mul_f32 v[32:33], v[52:53], v[52:53]
	v_pk_mul_f32 v[34:35], v[50:51], v[50:51]
	v_fmamk_f32 v57, v60, 0xba800000, v57
	v_pk_mov_b32 v[36:37], v[34:35], v[32:33] op_sel:[1,0]
	v_mov_b32_e32 v35, v33
	v_pk_add_f32 v[32:33], v[36:37], v[34:35]
	v_fmac_f32_e32 v56, 0xba800000, v60
	v_fmamk_f32 v59, v60, 0xba800000, v59
	v_fmac_f32_e32 v58, 0xba800000, v60
	v_pk_add_f32 v[32:33], v[32:33], v[32:33] op_sel_hi:[0,1]
	v_pk_mul_f32 v[34:35], v[58:59], v[58:59]
	v_pk_mul_f32 v[36:37], v[56:57], v[56:57]
	v_fmac_f32_e32 v54, 0xba800000, v60
	v_pk_mov_b32 v[38:39], v[36:37], v[34:35] op_sel:[1,0]
	v_mov_b32_e32 v37, v35
	v_fmamk_f32 v55, v60, 0xba800000, v55
	v_fmac_f32_e32 v116, 0xba800000, v60
	v_mul_f32_e32 v32, v54, v54
	v_pk_add_f32 v[34:35], v[38:39], v[36:37]
	v_fmamk_f32 v117, v60, 0xba800000, v117
	v_pk_fma_f32 v[36:37], v[54:55], v[54:55], v[32:33] op_sel_hi:[1,1,0]
	v_mul_f32_e32 v32, v116, v116
	v_pk_add_f32 v[34:35], v[34:35], v[34:35] op_sel_hi:[0,1]
	v_pk_fma_f32 v[38:39], v[116:117], v[116:117], v[32:33] op_sel_hi:[1,1,0]
	v_fmamk_f32 v49, v60, 0xba800000, v49
	v_fmac_f32_e32 v48, 0xba800000, v60
	v_fmamk_f32 v47, v60, 0xba800000, v47
	v_fmac_f32_e32 v46, 0xba800000, v60
	v_mul_f32_e32 v36, v46, v46
	v_mul_f32_e32 v38, v47, v47
	v_mul_f32_e32 v32, v48, v48
	v_mul_f32_e32 v34, v49, v49
	v_pk_add_f32 v[36:37], v[36:37], v[38:39]
	v_pk_add_f32 v[32:33], v[32:33], v[34:35]
	s_nop 0
	v_pk_add_f32 v[60:61], v[36:37], v[32:33]
	v_mov_b64_e32 v[32:33], v[154:155]
	v_mov_b64_e32 v[34:35], v[156:157]
	v_mov_b64_e32 v[36:37], v[158:159]
	v_mov_b64_e32 v[38:39], v[160:161]
	v_mov_b32_e32 v119, v60
	v_mov_b32_e32 v60, v63
	v_pk_add_f32 v[60:61], v[118:119], v[60:61]
	ds_bpermute_b32 v63, v67, v61
	ds_bpermute_b32 v62, v67, v60
	s_waitcnt lgkmcnt(0)
	v_pk_add_f32 v[60:61], v[60:61], v[62:63]
	ds_bpermute_b32 v63, v69, v61
	ds_bpermute_b32 v62, v69, v60
	s_waitcnt lgkmcnt(0)
	v_pk_add_f32 v[60:61], v[60:61], v[62:63]
	ds_bpermute_b32 v63, v71, v61
	ds_bpermute_b32 v62, v71, v60
	s_waitcnt lgkmcnt(0)
	v_pk_add_f32 v[60:61], v[60:61], v[62:63]
	ds_bpermute_b32 v63, v73, v61
	ds_bpermute_b32 v62, v73, v60
	s_waitcnt lgkmcnt(0)
	v_pk_add_f32 v[60:61], v[60:61], v[62:63]
	ds_bpermute_b32 v63, v123, v61
	ds_bpermute_b32 v62, v123, v60
	s_waitcnt lgkmcnt(0)
	v_pk_add_f32 v[60:61], v[60:61], v[62:63]
	ds_bpermute_b32 v63, v124, v61
	ds_bpermute_b32 v62, v124, v60
	s_waitcnt lgkmcnt(0)
	v_pk_add_f32 v[60:61], v[60:61], v[62:63]
	s_nop 0
	v_pk_fma_f32 v[118:119], v[60:61], s[2:3], v[120:121] op_sel_hi:[1,0,0]
	s_nop 0
	v_mul_f32_e32 v60, 0x4b800000, v119
	v_cmp_gt_f32_e64 s[8:9], s68, v119
	v_cmp_gt_f32_e32 vcc, s68, v118
	s_nop 0
	v_cndmask_b32_e64 v60, v119, v60, s[8:9]
	v_rsq_f32_e32 v60, v60
	s_nop 0
	v_mul_f32_e32 v61, 0x45800000, v60
	v_cndmask_b32_e64 v120, v60, v61, s[8:9]
	v_pk_mul_f32 v[52:53], v[52:53], v[120:121] op_sel_hi:[1,0]
	v_pk_mul_f32 v[50:51], v[50:51], v[120:121] op_sel_hi:[1,0]
	v_pk_mul_f32 v[46:47], v[46:47], v[120:121] op_sel_hi:[1,0]
	v_pk_fma_f32 v[60:61], v[32:33], v[50:51], v[36:37]
	v_pk_fma_f32 v[62:63], v[34:35], v[52:53], v[38:39]
	flat_store_dwordx4 v[40:41], v[60:63]
	v_mov_b64_e32 v[32:33], v[162:163]
	v_mov_b64_e32 v[34:35], v[164:165]
	v_mov_b64_e32 v[36:37], v[166:167]
	v_mov_b64_e32 v[38:39], v[168:169]
	v_pk_mul_f32 v[50:51], v[58:59], v[120:121] op_sel_hi:[1,0]
	v_pk_mul_f32 v[52:53], v[56:57], v[120:121] op_sel_hi:[1,0]
	v_pk_fma_f32 v[58:59], v[34:35], v[50:51], v[38:39]
	v_pk_fma_f32 v[56:57], v[32:33], v[52:53], v[36:37]
	flat_store_dwordx4 v[40:41], v[56:59] offset:1024
	v_mov_b64_e32 v[32:33], v[170:171]
	v_mov_b64_e32 v[34:35], v[172:173]
	v_mov_b64_e32 v[36:37], v[174:175]
	v_mov_b64_e32 v[38:39], v[176:177]
	v_pk_mul_f32 v[50:51], v[116:117], v[120:121] op_sel_hi:[1,0]
	v_pk_mul_f32 v[52:53], v[54:55], v[120:121] op_sel_hi:[1,0]
	v_pk_fma_f32 v[54:55], v[34:35], v[50:51], v[38:39]
	v_pk_fma_f32 v[52:53], v[32:33], v[52:53], v[36:37]
	flat_store_dwordx4 v[40:41], v[52:55] offset:2048
	v_mov_b64_e32 v[32:33], v[178:179]
	v_mov_b64_e32 v[34:35], v[180:181]
	v_mov_b64_e32 v[36:37], v[182:183]
	v_mov_b64_e32 v[38:39], v[184:185]
	v_pk_mul_f32 v[50:51], v[48:49], v[120:121] op_sel_hi:[1,0]
	v_pk_fma_f32 v[48:49], v[32:33], v[46:47], v[36:37]
	v_mul_f32_e32 v32, 0x4b800000, v118
	v_cndmask_b32_e32 v32, v118, v32, vcc
	v_rsq_f32_e32 v32, v32
	v_pk_fma_f32 v[50:51], v[34:35], v[50:51], v[38:39]
	flat_store_dwordx4 v[40:41], v[48:51] offset:3072
	v_mul_f32_e32 v33, 0x45800000, v32
	v_cndmask_b32_e32 v116, v32, v33, vcc
	v_mov_b64_e32 v[32:33], v[154:155]
	v_mov_b64_e32 v[34:35], v[156:157]
	v_mov_b64_e32 v[36:37], v[158:159]
	v_mov_b64_e32 v[38:39], v[160:161]
	v_pk_mul_f32 v[40:41], v[114:115], v[116:117] op_sel_hi:[1,0]
	v_pk_mul_f32 v[44:45], v[44:45], v[116:117] op_sel_hi:[1,0]
	v_pk_mul_f32 v[112:113], v[112:113], v[116:117] op_sel_hi:[1,0]
	v_pk_mul_f32 v[110:111], v[110:111], v[116:117] op_sel_hi:[1,0]
	v_pk_mul_f32 v[108:109], v[108:109], v[116:117] op_sel_hi:[1,0]
	s_andn2_b64 vcc, exec, s[4:5]
	v_pk_fma_f32 v[44:45], v[32:33], v[44:45], v[36:37]
	v_pk_fma_f32 v[46:47], v[34:35], v[40:41], v[38:39]
	flat_store_dwordx4 v[102:103], v[44:47]
	v_mov_b64_e32 v[32:33], v[162:163]
	v_mov_b64_e32 v[34:35], v[164:165]
	v_mov_b64_e32 v[36:37], v[166:167]
	v_mov_b64_e32 v[38:39], v[168:169]
	v_pk_mul_f32 v[40:41], v[42:43], v[116:117] op_sel_hi:[1,0]
	v_pk_fma_f32 v[42:43], v[34:35], v[112:113], v[38:39]
	v_pk_fma_f32 v[40:41], v[32:33], v[40:41], v[36:37]
	flat_store_dwordx4 v[102:103], v[40:43] offset:1024
	v_mov_b64_e32 v[32:33], v[170:171]
	v_mov_b64_e32 v[34:35], v[172:173]
	v_mov_b64_e32 v[36:37], v[174:175]
	v_mov_b64_e32 v[38:39], v[176:177]
	v_pk_fma_f32 v[36:37], v[32:33], v[108:109], v[36:37]
	v_pk_fma_f32 v[38:39], v[34:35], v[110:111], v[38:39]
	flat_store_dwordx4 v[102:103], v[36:39] offset:2048
	v_pk_mul_f32 v[108:109], v[106:107], v[116:117] op_sel_hi:[1,0]
	v_pk_mul_f32 v[110:111], v[104:105], v[116:117] op_sel_hi:[1,0]
	v_mov_b64_e32 v[32:33], v[178:179]
	v_mov_b64_e32 v[34:35], v[180:181]
	v_mov_b64_e32 v[104:105], v[182:183]
	v_mov_b64_e32 v[106:107], v[184:185]
	v_pk_fma_f32 v[32:33], v[32:33], v[110:111], v[104:105]
	v_pk_fma_f32 v[34:35], v[34:35], v[108:109], v[106:107]
	flat_store_dwordx4 v[102:103], v[32:35] offset:3072
	s_cbranch_vccnz .LBB0_50
	v_mad_u64_u32 v[104:105], s[4:5], v88, s7, 0
	v_mad_u64_u32 v[102:103], s[4:5], v92, s7, 0
	v_mad_i32_i24 v105, v89, s7, v105
	v_mad_i32_i24 v103, v93, s7, v103
	v_mad_u64_u32 v[92:93], s[4:5], v98, s7, 0
	v_mad_u64_u32 v[88:89], s[4:5], v100, s7, 0
	v_mad_i32_i24 v93, v99, s7, v93
	v_lshl_add_u64 v[98:99], s[60:61], 0, v[104:105]
	s_mov_b64 s[4:5], 0x6000
	s_mov_b64 s[8:9], 0x7000
	v_mad_i32_i24 v89, v101, s7, v89
	v_lshl_add_u64 v[100:101], v[98:99], 0, s[4:5]
	v_lshl_add_u64 v[98:99], v[98:99], 0, s[8:9]
	v_lshlrev_b32_e32 v152, 2, v66
	v_lshl_add_u64 v[104:105], v[100:101], 0, v[152:153]
	v_lshl_add_u64 v[108:109], v[98:99], 0, v[152:153]
	global_load_dwordx4 v[186:189], v[104:105], off offset:1024
	global_load_dwordx4 v[190:193], v[104:105], off offset:2048
	global_load_dwordx4 v[194:197], v[104:105], off offset:3072
	flat_load_dwordx4 v[104:107], v[104:105]
	s_nop 0
	global_load_dwordx4 v[198:201], v[108:109], off offset:1024
	global_load_dwordx4 v[202:205], v[108:109], off offset:2048
	global_load_dwordx4 v[224:227], v[108:109], off offset:3072
	flat_load_dwordx4 v[108:111], v[108:109]
	s_waitcnt vmcnt(0) lgkmcnt(0)
	v_pk_add_f32 v[110:111], v[110:111], 1.0 op_sel_hi:[1,0]
	v_pk_add_f32 v[108:109], v[108:109], 1.0 op_sel_hi:[1,0]
	v_pk_fma_f32 v[22:23], v[22:23], v[110:111], v[106:107]
	v_pk_fma_f32 v[20:21], v[20:21], v[108:109], v[104:105]
	s_nop 0
	v_cvt_pk_bf16_f32 v20, v20, v21
	v_cvt_pk_bf16_f32 v21, v22, v23
	flat_store_dwordx2 v[84:85], v[20:21]
	v_lshlrev_b32_e32 v20, 2, v68
	v_mov_b32_e32 v21, v153
	v_lshl_add_u64 v[22:23], v[100:101], 0, v[20:21]
	v_mov_b64_e32 v[104:105], v[186:187]
	v_mov_b64_e32 v[106:107], v[188:189]
	v_lshl_add_u64 v[22:23], v[98:99], 0, v[20:21]
	v_mov_b64_e32 v[108:109], v[198:199]
	v_mov_b64_e32 v[110:111], v[200:201]
	v_pk_add_f32 v[22:23], v[110:111], 1.0 op_sel_hi:[1,0]
	v_pk_add_f32 v[108:109], v[108:109], 1.0 op_sel_hi:[1,0]
	v_pk_fma_f32 v[14:15], v[14:15], v[22:23], v[106:107]
	v_pk_fma_f32 v[12:13], v[12:13], v[108:109], v[104:105]
	s_nop 0
	v_cvt_pk_bf16_f32 v12, v12, v13
	v_cvt_pk_bf16_f32 v13, v14, v15
	flat_store_dwordx2 v[84:85], v[12:13] offset:512
	v_lshlrev_b32_e32 v12, 2, v70
	v_mov_b32_e32 v13, v153
	v_lshl_add_u64 v[14:15], v[100:101], 0, v[12:13]
	v_mov_b64_e32 v[104:105], v[190:191]
	v_mov_b64_e32 v[106:107], v[192:193]
	v_lshl_add_u64 v[14:15], v[98:99], 0, v[12:13]
	v_mov_b64_e32 v[108:109], v[202:203]
	v_mov_b64_e32 v[110:111], v[204:205]
	v_pk_add_f32 v[14:15], v[110:111], 1.0 op_sel_hi:[1,0]
	v_pk_add_f32 v[22:23], v[108:109], 1.0 op_sel_hi:[1,0]
	v_pk_fma_f32 v[6:7], v[6:7], v[14:15], v[106:107]
	v_pk_fma_f32 v[4:5], v[4:5], v[22:23], v[104:105]
	s_nop 0
	v_cvt_pk_bf16_f32 v4, v4, v5
	v_cvt_pk_bf16_f32 v5, v6, v7
	flat_store_dwordx2 v[84:85], v[4:5] offset:1024
	v_lshlrev_b32_e32 v4, 2, v72
	v_mov_b32_e32 v5, v153
	v_lshl_add_u64 v[6:7], v[100:101], 0, v[4:5]
	v_mov_b64_e32 v[104:105], v[194:195]
	v_mov_b64_e32 v[106:107], v[196:197]
	v_lshl_add_u64 v[6:7], v[98:99], 0, v[4:5]
	v_mov_b64_e32 v[98:99], v[224:225]
	v_mov_b64_e32 v[100:101], v[226:227]
	v_pk_add_f32 v[6:7], v[100:101], 1.0 op_sel_hi:[1,0]
	v_pk_add_f32 v[14:15], v[98:99], 1.0 op_sel_hi:[1,0]
	v_pk_fma_f32 v[2:3], v[2:3], v[6:7], v[106:107]
	v_pk_fma_f32 v[0:1], v[0:1], v[14:15], v[104:105]
	s_nop 0
	v_cvt_pk_bf16_f32 v0, v0, v1
	v_cvt_pk_bf16_f32 v1, v2, v3
	flat_store_dwordx2 v[84:85], v[0:1] offset:1536
	v_lshl_add_u64 v[0:1], s[60:61], 0, v[102:103]
	v_lshl_add_u64 v[2:3], v[0:1], 0, s[4:5]
	v_lshl_add_u64 v[0:1], v[0:1], 0, s[8:9]
	v_lshl_add_u64 v[6:7], v[2:3], 0, v[152:153]
	global_load_dwordx4 v[186:189], v[6:7], off offset:1024
	global_load_dwordx4 v[190:193], v[6:7], off offset:2048
	global_load_dwordx4 v[194:197], v[6:7], off offset:3072
	flat_load_dwordx4 v[98:101], v[6:7]
	v_lshl_add_u64 v[6:7], v[0:1], 0, v[152:153]
	global_load_dwordx4 v[198:201], v[6:7], off offset:1024
	global_load_dwordx4 v[202:205], v[6:7], off offset:2048
	global_load_dwordx4 v[224:227], v[6:7], off offset:3072
	flat_load_dwordx4 v[102:105], v[6:7]
	s_waitcnt vmcnt(0) lgkmcnt(0)
	v_pk_add_f32 v[6:7], v[104:105], 1.0 op_sel_hi:[1,0]
	v_pk_add_f32 v[14:15], v[102:103], 1.0 op_sel_hi:[1,0]
	v_pk_fma_f32 v[6:7], v[10:11], v[6:7], v[100:101]
	v_pk_fma_f32 v[8:9], v[8:9], v[14:15], v[98:99]
	v_lshl_add_u64 v[10:11], v[82:83], 0, v[90:91]
	v_cvt_pk_bf16_f32 v8, v8, v9
	v_cvt_pk_bf16_f32 v9, v6, v7
	flat_store_dwordx2 v[10:11], v[8:9]
	v_lshl_add_u64 v[6:7], v[2:3], 0, v[20:21]
	v_lshl_add_u64 v[14:15], v[0:1], 0, v[20:21]
	v_mov_b64_e32 v[6:7], v[186:187]
	v_mov_b64_e32 v[8:9], v[188:189]
	s_nop 0
	v_mov_b64_e32 v[98:99], v[198:199]
	v_mov_b64_e32 v[100:101], v[200:201]
	v_pk_add_f32 v[14:15], v[100:101], 1.0 op_sel_hi:[1,0]
	v_pk_add_f32 v[22:23], v[98:99], 1.0 op_sel_hi:[1,0]
	v_pk_fma_f32 v[8:9], v[30:31], v[14:15], v[8:9]
	v_pk_fma_f32 v[6:7], v[28:29], v[22:23], v[6:7]
	v_lshl_add_u64 v[14:15], v[0:1], 0, v[12:13]
	v_cvt_pk_bf16_f32 v6, v6, v7
	v_cvt_pk_bf16_f32 v7, v8, v9
	flat_store_dwordx2 v[10:11], v[6:7] offset:512
	v_lshl_add_u64 v[6:7], v[2:3], 0, v[12:13]
	v_mov_b64_e32 v[6:7], v[190:191]
	v_mov_b64_e32 v[8:9], v[192:193]
	v_lshl_add_u64 v[2:3], v[2:3], 0, v[4:5]
	v_mov_b64_e32 v[28:29], v[202:203]
	v_mov_b64_e32 v[30:31], v[204:205]
	v_lshl_add_u64 v[0:1], v[0:1], 0, v[4:5]
	v_pk_add_f32 v[14:15], v[30:31], 1.0 op_sel_hi:[1,0]
	v_pk_add_f32 v[22:23], v[28:29], 1.0 op_sel_hi:[1,0]
	v_pk_fma_f32 v[8:9], v[26:27], v[14:15], v[8:9]
	v_pk_fma_f32 v[6:7], v[24:25], v[22:23], v[6:7]
	s_nop 0
	v_cvt_pk_bf16_f32 v6, v6, v7
	v_cvt_pk_bf16_f32 v7, v8, v9
	flat_store_dwordx2 v[10:11], v[6:7] offset:1024
	v_mov_b64_e32 v[6:7], v[194:195]
	v_mov_b64_e32 v[8:9], v[196:197]
	s_nop 0
	v_mov_b64_e32 v[0:1], v[224:225]
	v_mov_b64_e32 v[2:3], v[226:227]
	v_pk_add_f32 v[2:3], v[2:3], 1.0 op_sel_hi:[1,0]
	v_pk_add_f32 v[0:1], v[0:1], 1.0 op_sel_hi:[1,0]
	v_pk_fma_f32 v[2:3], v[18:19], v[2:3], v[8:9]
	v_pk_fma_f32 v[0:1], v[16:17], v[0:1], v[6:7]
	v_lshl_add_u64 v[18:19], v[82:83], 0, v[94:95]
	v_cvt_pk_bf16_f32 v0, v0, v1
	v_cvt_pk_bf16_f32 v1, v2, v3
	flat_store_dwordx2 v[10:11], v[0:1] offset:1536
	v_lshl_add_u64 v[0:1], s[60:61], 0, v[92:93]
	v_lshl_add_u64 v[2:3], v[0:1], 0, s[4:5]
	v_lshl_add_u64 v[0:1], v[0:1], 0, s[8:9]
	v_lshl_add_u64 v[6:7], v[2:3], 0, v[152:153]
	v_lshl_add_u64 v[10:11], v[0:1], 0, v[152:153]
	global_load_dwordx4 v[186:189], v[6:7], off offset:1024
	global_load_dwordx4 v[190:193], v[6:7], off offset:2048
	global_load_dwordx4 v[194:197], v[6:7], off offset:3072
	flat_load_dwordx4 v[6:9], v[6:7]
	s_nop 0
	global_load_dwordx4 v[198:201], v[10:11], off offset:1024
	global_load_dwordx4 v[202:205], v[10:11], off offset:2048
	global_load_dwordx4 v[224:227], v[10:11], off offset:3072
	flat_load_dwordx4 v[14:17], v[10:11]
	s_waitcnt vmcnt(0) lgkmcnt(0)
	v_pk_add_f32 v[10:11], v[16:17], 1.0 op_sel_hi:[1,0]
	v_pk_add_f32 v[14:15], v[14:15], 1.0 op_sel_hi:[1,0]
	v_pk_fma_f32 v[8:9], v[62:63], v[10:11], v[8:9]
	v_pk_fma_f32 v[6:7], v[60:61], v[14:15], v[6:7]
	v_lshl_add_u64 v[10:11], v[82:83], 0, v[96:97]
	v_cvt_pk_bf16_f32 v6, v6, v7
	v_cvt_pk_bf16_f32 v7, v8, v9
	flat_store_dwordx2 v[10:11], v[6:7]
	v_lshl_add_u64 v[6:7], v[2:3], 0, v[20:21]
	v_lshl_add_u64 v[14:15], v[0:1], 0, v[20:21]
	v_mov_b64_e32 v[6:7], v[186:187]
	v_mov_b64_e32 v[8:9], v[188:189]
	s_nop 0
	v_mov_b64_e32 v[14:15], v[198:199]
	v_mov_b64_e32 v[16:17], v[200:201]
	v_pk_add_f32 v[16:17], v[16:17], 1.0 op_sel_hi:[1,0]
	v_pk_add_f32 v[14:15], v[14:15], 1.0 op_sel_hi:[1,0]
	v_pk_fma_f32 v[8:9], v[58:59], v[16:17], v[8:9]
	v_pk_fma_f32 v[6:7], v[56:57], v[14:15], v[6:7]
	v_lshl_add_u64 v[14:15], v[0:1], 0, v[12:13]
	v_cvt_pk_bf16_f32 v6, v6, v7
	v_cvt_pk_bf16_f32 v7, v8, v9
	flat_store_dwordx2 v[10:11], v[6:7] offset:512
	v_lshl_add_u64 v[6:7], v[2:3], 0, v[12:13]
	v_mov_b64_e32 v[6:7], v[190:191]
	v_mov_b64_e32 v[8:9], v[192:193]
	v_lshl_add_u64 v[2:3], v[2:3], 0, v[4:5]
	v_mov_b64_e32 v[14:15], v[202:203]
	v_mov_b64_e32 v[16:17], v[204:205]
	v_lshl_add_u64 v[0:1], v[0:1], 0, v[4:5]
	v_pk_add_f32 v[16:17], v[16:17], 1.0 op_sel_hi:[1,0]
	v_pk_add_f32 v[14:15], v[14:15], 1.0 op_sel_hi:[1,0]
	v_pk_fma_f32 v[8:9], v[54:55], v[16:17], v[8:9]
	v_pk_fma_f32 v[6:7], v[52:53], v[14:15], v[6:7]
	s_nop 0
	v_cvt_pk_bf16_f32 v6, v6, v7
	v_cvt_pk_bf16_f32 v7, v8, v9
	flat_store_dwordx2 v[10:11], v[6:7] offset:1024
	v_mov_b64_e32 v[6:7], v[194:195]
	v_mov_b64_e32 v[8:9], v[196:197]
	s_nop 0
	v_mov_b64_e32 v[0:1], v[224:225]
	v_mov_b64_e32 v[2:3], v[226:227]
	v_pk_add_f32 v[2:3], v[2:3], 1.0 op_sel_hi:[1,0]
	v_pk_add_f32 v[0:1], v[0:1], 1.0 op_sel_hi:[1,0]
	v_pk_fma_f32 v[2:3], v[50:51], v[2:3], v[8:9]
	v_pk_fma_f32 v[0:1], v[48:49], v[0:1], v[6:7]
	s_nop 0
	v_cvt_pk_bf16_f32 v0, v0, v1
	v_cvt_pk_bf16_f32 v1, v2, v3
	flat_store_dwordx2 v[10:11], v[0:1] offset:1536
	v_lshl_add_u64 v[0:1], s[60:61], 0, v[88:89]
	v_lshl_add_u64 v[2:3], v[0:1], 0, s[4:5]
	v_lshl_add_u64 v[0:1], v[0:1], 0, s[8:9]
	v_lshl_add_u64 v[6:7], v[2:3], 0, v[152:153]
	v_lshl_add_u64 v[10:11], v[0:1], 0, v[152:153]
	global_load_dwordx4 v[186:189], v[6:7], off offset:1024
	global_load_dwordx4 v[190:193], v[6:7], off offset:2048
	global_load_dwordx4 v[194:197], v[6:7], off offset:3072
	flat_load_dwordx4 v[6:9], v[6:7]
	s_nop 0
	global_load_dwordx4 v[198:201], v[10:11], off offset:1024
	global_load_dwordx4 v[202:205], v[10:11], off offset:2048
	global_load_dwordx4 v[224:227], v[10:11], off offset:3072
	flat_load_dwordx4 v[14:17], v[10:11]
	s_waitcnt vmcnt(0) lgkmcnt(0)
	v_pk_add_f32 v[10:11], v[16:17], 1.0 op_sel_hi:[1,0]
	v_pk_add_f32 v[14:15], v[14:15], 1.0 op_sel_hi:[1,0]
	v_pk_fma_f32 v[8:9], v[46:47], v[10:11], v[8:9]
	v_pk_fma_f32 v[6:7], v[44:45], v[14:15], v[6:7]
	v_lshl_add_u64 v[10:11], v[0:1], 0, v[20:21]
	v_cvt_pk_bf16_f32 v6, v6, v7
	v_cvt_pk_bf16_f32 v7, v8, v9
	flat_store_dwordx2 v[18:19], v[6:7]
	v_lshl_add_u64 v[6:7], v[2:3], 0, v[20:21]
	v_mov_b64_e32 v[6:7], v[186:187]
	v_mov_b64_e32 v[8:9], v[188:189]
	s_nop 0
	v_mov_b64_e32 v[14:15], v[198:199]
	v_mov_b64_e32 v[16:17], v[200:201]
	v_pk_add_f32 v[10:11], v[16:17], 1.0 op_sel_hi:[1,0]
	v_pk_add_f32 v[14:15], v[14:15], 1.0 op_sel_hi:[1,0]
	v_pk_fma_f32 v[8:9], v[42:43], v[10:11], v[8:9]
	v_pk_fma_f32 v[6:7], v[40:41], v[14:15], v[6:7]
	v_lshl_add_u64 v[10:11], v[0:1], 0, v[12:13]
	v_cvt_pk_bf16_f32 v6, v6, v7
	v_cvt_pk_bf16_f32 v7, v8, v9
	flat_store_dwordx2 v[18:19], v[6:7] offset:512
	v_lshl_add_u64 v[6:7], v[2:3], 0, v[12:13]
	v_mov_b64_e32 v[6:7], v[190:191]
	v_mov_b64_e32 v[8:9], v[192:193]
	v_lshl_add_u64 v[2:3], v[2:3], 0, v[4:5]
	v_mov_b64_e32 v[10:11], v[202:203]
	v_mov_b64_e32 v[12:13], v[204:205]
	v_lshl_add_u64 v[0:1], v[0:1], 0, v[4:5]
	v_pk_add_f32 v[12:13], v[12:13], 1.0 op_sel_hi:[1,0]
	v_pk_add_f32 v[10:11], v[10:11], 1.0 op_sel_hi:[1,0]
	v_pk_fma_f32 v[8:9], v[38:39], v[12:13], v[8:9]
	v_pk_fma_f32 v[6:7], v[36:37], v[10:11], v[6:7]
	s_nop 0
	v_cvt_pk_bf16_f32 v6, v6, v7
	v_cvt_pk_bf16_f32 v7, v8, v9
	flat_store_dwordx2 v[18:19], v[6:7] offset:1024
	v_mov_b64_e32 v[6:7], v[194:195]
	v_mov_b64_e32 v[8:9], v[196:197]
	s_nop 0
	v_mov_b64_e32 v[0:1], v[224:225]
	v_mov_b64_e32 v[2:3], v[226:227]
	v_pk_add_f32 v[2:3], v[2:3], 1.0 op_sel_hi:[1,0]
	v_pk_add_f32 v[0:1], v[0:1], 1.0 op_sel_hi:[1,0]
	v_pk_fma_f32 v[2:3], v[34:35], v[2:3], v[8:9]
	v_pk_fma_f32 v[0:1], v[32:33], v[0:1], v[6:7]
	s_nop 0
	v_cvt_pk_bf16_f32 v0, v0, v1
	v_cvt_pk_bf16_f32 v1, v2, v3
	flat_store_dwordx2 v[18:19], v[0:1] offset:1536
	s_branch .LBB0_50

.LBB0_212:
	s_waitcnt vmcnt(0) lgkmcnt(0)
	v_lshlrev_b32_e32 v228, 16, v202
	v_and_b32_e32 v229, 0xffff0000, v202
	v_lshlrev_b32_e32 v202, 16, v203
	v_and_b32_e32 v203, 0xffff0000, v203
	v_lshlrev_b32_e32 v230, 16, v204
	v_and_b32_e32 v231, 0xffff0000, v204
	v_lshlrev_b32_e32 v204, 16, v205
	v_and_b32_e32 v205, 0xffff0000, v205
	v_pk_mul_f32 v[94:95], v[94:95], 0.5 op_sel_hi:[1,0]
	v_pk_mul_f32 v[92:93], v[92:93], 0.5 op_sel_hi:[1,0]
	v_pk_add_f32 v[202:203], v[202:203], v[204:205]
	v_pk_add_f32 v[204:205], v[228:229], v[230:231]
	v_pk_mul_f32 v[94:95], v[94:95], v[202:203]
	v_pk_mul_f32 v[92:93], v[92:93], v[204:205]
	v_pk_fma_f32 v[90:91], v[90:91], s[42:43], v[94:95] op_sel_hi:[1,0,1]
	v_pk_fma_f32 v[88:89], v[88:89], s[42:43], v[92:93] op_sel_hi:[1,0,1]
	v_add_f32_e32 v93, v90, v91
	v_add_f32_e32 v92, v88, v89
	v_add_f32_e32 v92, v92, v93
	v_add_f32_e32 v143, 0, v92
	v_lshlrev_b32_e32 v92, 16, v198
	v_and_b32_e32 v93, 0xffff0000, v198
	v_lshlrev_b32_e32 v94, 16, v199
	v_and_b32_e32 v95, 0xffff0000, v199
	v_lshlrev_b32_e32 v198, 16, v200
	v_and_b32_e32 v199, 0xffff0000, v200
	v_lshlrev_b32_e32 v200, 16, v201
	v_and_b32_e32 v201, 0xffff0000, v201
	v_pk_mul_f32 v[86:87], v[86:87], 0.5 op_sel_hi:[1,0]
	v_pk_mul_f32 v[84:85], v[84:85], 0.5 op_sel_hi:[1,0]
	v_pk_add_f32 v[94:95], v[94:95], v[200:201]
	v_pk_add_f32 v[92:93], v[92:93], v[198:199]
	v_pk_mul_f32 v[86:87], v[86:87], v[94:95]
	v_pk_mul_f32 v[84:85], v[84:85], v[92:93]
	v_pk_fma_f32 v[86:87], v[78:79], s[42:43], v[86:87] op_sel_hi:[1,0,1]
	v_pk_fma_f32 v[84:85], v[76:77], s[42:43], v[84:85] op_sel_hi:[1,0,1]
	v_add_f32_e32 v77, v86, v87
	v_add_f32_e32 v76, v84, v85
	v_add_f32_e32 v76, v76, v77
	v_add_f32_e32 v143, v143, v76
	v_lshlrev_b32_e32 v76, 16, v194
	v_and_b32_e32 v77, 0xffff0000, v194
	v_lshlrev_b32_e32 v78, 16, v195
	v_and_b32_e32 v79, 0xffff0000, v195
	v_lshlrev_b32_e32 v92, 16, v196
	v_and_b32_e32 v93, 0xffff0000, v196
	v_lshlrev_b32_e32 v94, 16, v197
	v_and_b32_e32 v95, 0xffff0000, v197
	v_pk_mul_f32 v[82:83], v[82:83], 0.5 op_sel_hi:[1,0]
	v_pk_mul_f32 v[80:81], v[80:81], 0.5 op_sel_hi:[1,0]
	v_pk_add_f32 v[78:79], v[78:79], v[94:95]
	v_pk_add_f32 v[76:77], v[76:77], v[92:93]
	v_pk_mul_f32 v[78:79], v[82:83], v[78:79]
	v_pk_mul_f32 v[76:77], v[80:81], v[76:77]
	v_pk_fma_f32 v[82:83], v[74:75], s[42:43], v[78:79] op_sel_hi:[1,0,1]
	v_pk_fma_f32 v[80:81], v[72:73], s[42:43], v[76:77] op_sel_hi:[1,0,1]
	v_lshlrev_b32_e32 v72, 16, v188
	v_and_b32_e32 v73, 0xffff0000, v188
	v_lshlrev_b32_e32 v74, 16, v189
	v_and_b32_e32 v75, 0xffff0000, v189
	v_lshlrev_b32_e32 v76, 16, v190
	v_and_b32_e32 v77, 0xffff0000, v190
	v_lshlrev_b32_e32 v78, 16, v191
	v_and_b32_e32 v79, 0xffff0000, v191
	v_pk_mul_f32 v[70:71], v[70:71], 0.5 op_sel_hi:[1,0]
	v_pk_mul_f32 v[68:69], v[68:69], 0.5 op_sel_hi:[1,0]
	v_pk_add_f32 v[74:75], v[74:75], v[78:79]
	v_pk_add_f32 v[72:73], v[72:73], v[76:77]
	v_pk_mul_f32 v[70:71], v[70:71], v[74:75]
	v_pk_mul_f32 v[68:69], v[68:69], v[72:73]
	v_pk_fma_f32 v[188:189], v[66:67], s[42:43], v[70:71] op_sel_hi:[1,0,1]
	v_pk_fma_f32 v[190:191], v[64:65], s[42:43], v[68:69] op_sel_hi:[1,0,1]
	v_add_f32_e32 v65, v188, v189
	v_add_f32_e32 v64, v190, v191
	v_add_f32_e32 v64, v64, v65
	v_add_f32_e32 v72, 0, v64
	v_lshlrev_b32_e32 v64, 16, v184
	v_and_b32_e32 v65, 0xffff0000, v184
	v_lshlrev_b32_e32 v66, 16, v185
	v_and_b32_e32 v67, 0xffff0000, v185
	v_lshlrev_b32_e32 v68, 16, v186
	v_and_b32_e32 v69, 0xffff0000, v186
	v_lshlrev_b32_e32 v70, 16, v187
	v_and_b32_e32 v71, 0xffff0000, v187
	v_pk_mul_f32 v[62:63], v[62:63], 0.5 op_sel_hi:[1,0]
	v_pk_mul_f32 v[60:61], v[60:61], 0.5 op_sel_hi:[1,0]
	v_pk_add_f32 v[66:67], v[66:67], v[70:71]
	v_pk_add_f32 v[64:65], v[64:65], v[68:69]
	v_pk_mul_f32 v[62:63], v[62:63], v[66:67]
	v_pk_mul_f32 v[60:61], v[60:61], v[64:65]
	v_pk_fma_f32 v[186:187], v[54:55], s[42:43], v[62:63] op_sel_hi:[1,0,1]
	v_pk_fma_f32 v[184:185], v[52:53], s[42:43], v[60:61] op_sel_hi:[1,0,1]
	v_add_f32_e32 v53, v186, v187
	v_add_f32_e32 v52, v184, v185
	v_add_f32_e32 v52, v52, v53
	v_add_f32_e32 v64, v72, v52
	v_lshlrev_b32_e32 v52, 16, v180
	v_and_b32_e32 v53, 0xffff0000, v180
	v_lshlrev_b32_e32 v54, 16, v181
	v_and_b32_e32 v55, 0xffff0000, v181
	v_lshlrev_b32_e32 v60, 16, v182
	v_and_b32_e32 v61, 0xffff0000, v182
	v_lshlrev_b32_e32 v62, 16, v183
	v_and_b32_e32 v63, 0xffff0000, v183
	v_pk_mul_f32 v[58:59], v[58:59], 0.5 op_sel_hi:[1,0]
	v_pk_mul_f32 v[56:57], v[56:57], 0.5 op_sel_hi:[1,0]
	v_pk_add_f32 v[54:55], v[54:55], v[62:63]
	v_pk_add_f32 v[52:53], v[52:53], v[60:61]
	v_pk_mul_f32 v[54:55], v[58:59], v[54:55]
	v_pk_mul_f32 v[52:53], v[56:57], v[52:53]
	v_pk_fma_f32 v[50:51], v[50:51], s[42:43], v[54:55] op_sel_hi:[1,0,1]
	v_pk_fma_f32 v[48:49], v[48:49], s[42:43], v[52:53] op_sel_hi:[1,0,1]
	v_add_f32_e32 v53, v50, v51
	v_add_f32_e32 v52, v48, v49
	v_add_f32_e32 v52, v52, v53
	v_add_f32_e32 v60, v64, v52
	v_lshlrev_b32_e32 v52, 16, v176
	v_and_b32_e32 v53, 0xffff0000, v176
	v_lshlrev_b32_e32 v54, 16, v177
	v_and_b32_e32 v55, 0xffff0000, v177
	v_lshlrev_b32_e32 v56, 16, v178
	v_and_b32_e32 v57, 0xffff0000, v178
	v_lshlrev_b32_e32 v58, 16, v179
	v_and_b32_e32 v59, 0xffff0000, v179
	v_pk_mul_f32 v[46:47], v[46:47], 0.5 op_sel_hi:[1,0]
	v_pk_mul_f32 v[44:45], v[44:45], 0.5 op_sel_hi:[1,0]
	v_pk_add_f32 v[54:55], v[54:55], v[58:59]
	v_pk_add_f32 v[52:53], v[52:53], v[56:57]
	v_pk_mul_f32 v[46:47], v[46:47], v[54:55]
	v_pk_mul_f32 v[44:45], v[44:45], v[52:53]
	v_pk_fma_f32 v[178:179], v[42:43], s[42:43], v[46:47] op_sel_hi:[1,0,1]
	v_pk_fma_f32 v[176:177], v[40:41], s[42:43], v[44:45] op_sel_hi:[1,0,1]
	v_add_f32_e32 v41, v178, v179
	v_add_f32_e32 v40, v176, v177
	v_add_f32_e32 v40, v40, v41
	v_add_f32_e32 v42, v60, v40
	ds_bpermute_b32 v43, v99, v42
	v_add_f32_e32 v92, v80, v81
	v_add_f32_e32 v93, v82, v83
	v_add_f32_e32 v40, v92, v93
	v_add_f32_e32 v52, v143, v40
	s_waitcnt lgkmcnt(0)
	v_add_f32_e32 v46, v42, v43
	ds_bpermute_b32 v47, v101, v46
	v_lshlrev_b32_e32 v40, 16, v172
	v_and_b32_e32 v41, 0xffff0000, v172
	v_lshlrev_b32_e32 v44, 16, v174
	v_and_b32_e32 v45, 0xffff0000, v174
	s_waitcnt lgkmcnt(0)
	v_add_f32_e32 v53, v46, v47
	ds_bpermute_b32 v54, v103, v53
	v_pk_mul_f32 v[36:37], v[36:37], 0.5 op_sel_hi:[1,0]
	v_pk_add_f32 v[40:41], v[40:41], v[44:45]
	v_lshlrev_b32_e32 v42, 16, v173
	v_pk_mul_f32 v[36:37], v[36:37], v[40:41]
	s_waitcnt lgkmcnt(0)
	v_add_f32_e32 v53, v53, v54
	ds_bpermute_b32 v54, v105, v53
	v_and_b32_e32 v43, 0xffff0000, v173
	v_lshlrev_b32_e32 v46, 16, v175
	v_and_b32_e32 v47, 0xffff0000, v175
	v_pk_mul_f32 v[38:39], v[38:39], 0.5 op_sel_hi:[1,0]
	s_waitcnt lgkmcnt(0)
	v_add_f32_e32 v40, v53, v54
	ds_bpermute_b32 v41, v225, v40
	v_pk_add_f32 v[42:43], v[42:43], v[46:47]
	v_pk_fma_f32 v[92:93], v[32:33], s[42:43], v[36:37] op_sel_hi:[1,0,1]
	v_pk_mul_f32 v[38:39], v[38:39], v[42:43]
	v_add_f32_e32 v32, v92, v93
	v_pk_fma_f32 v[94:95], v[34:35], s[42:43], v[38:39] op_sel_hi:[1,0,1]
	s_waitcnt lgkmcnt(0)
	v_add_f32_e32 v34, v40, v41
	ds_bpermute_b32 v35, v226, v34
	v_add_f32_e32 v33, v94, v95
	v_add_f32_e32 v32, v32, v33
	v_add_f32_e32 v42, v52, v32
	v_lshlrev_b64 v[32:33], 11, v[192:193]
	s_waitcnt lgkmcnt(0)
	v_add_f32_e32 v43, v34, v35
	v_fmamk_f32 v191, v43, 0xba800000, v191
	v_fmac_f32_e32 v190, 0xba800000, v43
	v_fmamk_f32 v189, v43, 0xba800000, v189
	v_fmac_f32_e32 v188, 0xba800000, v43
	v_pk_mul_f32 v[34:35], v[188:189], v[188:189]
	v_pk_mul_f32 v[36:37], v[190:191], v[190:191]
	v_fmamk_f32 v185, v43, 0xba800000, v185
	v_pk_mov_b32 v[38:39], v[36:37], v[34:35] op_sel:[1,0]
	v_mov_b32_e32 v37, v35
	v_pk_add_f32 v[34:35], v[38:39], v[36:37]
	v_fmac_f32_e32 v184, 0xba800000, v43
	v_pk_add_f32 v[34:35], v[34:35], v[34:35] op_sel_hi:[0,1]
	v_fmamk_f32 v187, v43, 0xba800000, v187
	v_fmac_f32_e32 v186, 0xba800000, v43
	ds_bpermute_b32 v34, v99, v42
	v_pk_mul_f32 v[36:37], v[186:187], v[186:187]
	v_pk_mul_f32 v[38:39], v[184:185], v[184:185]
	v_fmac_f32_e32 v48, 0xba800000, v43
	v_pk_mov_b32 v[40:41], v[38:39], v[36:37] op_sel:[1,0]
	v_mov_b32_e32 v39, v37
	v_pk_add_f32 v[36:37], v[40:41], v[38:39]
	v_fmamk_f32 v49, v43, 0xba800000, v49
	v_pk_add_f32 v[36:37], v[36:37], v[36:37] op_sel_hi:[0,1]
	s_waitcnt lgkmcnt(0)
	v_add_f32_e32 v36, v42, v34
	ds_bpermute_b32 v38, v101, v36
	v_fmac_f32_e32 v50, 0xba800000, v43
	v_mul_f32_e32 v34, v48, v48
	v_fmamk_f32 v51, v43, 0xba800000, v51
	v_fmamk_f32 v179, v43, 0xba800000, v179
	s_waitcnt lgkmcnt(0)
	v_add_f32_e32 v36, v36, v38
	ds_bpermute_b32 v42, v103, v36
	v_pk_fma_f32 v[38:39], v[48:49], v[48:49], v[34:35] op_sel_hi:[1,1,0]
	v_mul_f32_e32 v34, v50, v50
	v_pk_fma_f32 v[40:41], v[50:51], v[50:51], v[34:35] op_sel_hi:[1,1,0]
	v_fmac_f32_e32 v178, 0xba800000, v43
	s_waitcnt lgkmcnt(0)
	v_add_f32_e32 v34, v36, v42
	ds_bpermute_b32 v36, v105, v34
	v_fmamk_f32 v177, v43, 0xba800000, v177
	v_fmac_f32_e32 v176, 0xba800000, v43
	v_mul_f32_e32 v38, v176, v176
	v_mul_f32_e32 v40, v177, v177
	s_waitcnt lgkmcnt(0)
	v_add_f32_e32 v42, v34, v36
	v_mul_f32_e32 v34, v178, v178
	v_mul_f32_e32 v36, v179, v179
	v_pk_add_f32 v[38:39], v[38:39], v[40:41]
	v_pk_add_f32 v[34:35], v[34:35], v[36:37]
	ds_bpermute_b32 v43, v225, v42
	v_pk_add_f32 v[34:35], v[38:39], v[34:35]
	ds_read_b128 v[36:39], v210
	ds_read_b128 v[56:59], v210 offset:4096
	v_lshl_add_u64 v[32:33], s[56:57], 0, v[32:33]
	s_mov_b64 s[4:5], 0x1000000
	s_waitcnt lgkmcnt(0)
	v_add_f32_e32 v40, v42, v43
	ds_bpermute_b32 v41, v226, v40
	v_ashrrev_i32_e32 v136, 10, v136
	v_lshl_add_u64 v[60:61], v[32:33], 0, s[4:5]
	v_mov_b32_e32 v145, v153
	v_add_u32_e32 v136, 1, v136
	s_waitcnt lgkmcnt(0)
	v_add_f32_e32 v52, v40, v41
	v_fmamk_f32 v89, v52, 0xba800000, v89
	v_fmac_f32_e32 v88, 0xba800000, v52
	v_fmamk_f32 v91, v52, 0xba800000, v91
	v_fmac_f32_e32 v90, 0xba800000, v52
	v_pk_mul_f32 v[40:41], v[90:91], v[90:91]
	v_pk_mul_f32 v[42:43], v[88:89], v[88:89]
	v_fmamk_f32 v85, v52, 0xba800000, v85
	v_pk_mov_b32 v[44:45], v[42:43], v[40:41] op_sel:[1,0]
	v_mov_b32_e32 v43, v41
	v_pk_add_f32 v[40:41], v[44:45], v[42:43]
	v_fmac_f32_e32 v84, 0xba800000, v52
	v_fmamk_f32 v87, v52, 0xba800000, v87
	v_fmac_f32_e32 v86, 0xba800000, v52
	v_pk_add_f32 v[40:41], v[40:41], v[40:41] op_sel_hi:[0,1]
	v_pk_mul_f32 v[42:43], v[86:87], v[86:87]
	v_pk_mul_f32 v[44:45], v[84:85], v[84:85]
	v_fmac_f32_e32 v80, 0xba800000, v52
	v_pk_mov_b32 v[46:47], v[44:45], v[42:43] op_sel:[1,0]
	v_mov_b32_e32 v45, v43
	v_fmamk_f32 v81, v52, 0xba800000, v81
	v_fmac_f32_e32 v82, 0xba800000, v52
	v_mul_f32_e32 v40, v80, v80
	v_pk_add_f32 v[42:43], v[46:47], v[44:45]
	v_fmamk_f32 v83, v52, 0xba800000, v83
	v_pk_fma_f32 v[44:45], v[80:81], v[80:81], v[40:41] op_sel_hi:[1,1,0]
	v_mul_f32_e32 v40, v82, v82
	v_pk_add_f32 v[42:43], v[42:43], v[42:43] op_sel_hi:[0,1]
	v_pk_fma_f32 v[46:47], v[82:83], v[82:83], v[40:41] op_sel_hi:[1,1,0]
	v_fmamk_f32 v95, v52, 0xba800000, v95
	v_fmac_f32_e32 v94, 0xba800000, v52
	v_fmamk_f32 v93, v52, 0xba800000, v93
	v_fmac_f32_e32 v92, 0xba800000, v52
	v_mul_f32_e32 v44, v92, v92
	v_mul_f32_e32 v46, v93, v93
	v_mul_f32_e32 v40, v94, v94
	v_mul_f32_e32 v42, v95, v95
	v_pk_add_f32 v[44:45], v[44:45], v[46:47]
	v_pk_add_f32 v[40:41], v[40:41], v[42:43]
	v_mov_b32_e32 v43, v34
	v_pk_add_f32 v[40:41], v[44:45], v[40:41]
	v_mov_b32_e32 v147, v153
	v_mov_b32_e32 v42, v40
	v_mov_b32_e32 v34, v41
	v_pk_add_f32 v[34:35], v[42:43], v[34:35]
	ds_bpermute_b32 v41, v99, v35
	ds_bpermute_b32 v40, v99, v34
	v_lshl_add_u64 v[192:193], v[60:61], 0, v[144:145]
	v_cndmask_b32_e64 v136, v136, 0, s[10:11]
	v_lshl_add_u64 v[172:173], v[32:33], 0, v[146:147]
	v_lshl_add_u64 v[180:181], v[60:61], 0, v[146:147]
	s_waitcnt lgkmcnt(0)
	v_pk_add_f32 v[34:35], v[34:35], v[40:41]
	ds_bpermute_b32 v41, v101, v35
	ds_bpermute_b32 v40, v101, v34
	v_ashrrev_i32_e32 v137, 31, v136
	v_lshl_add_u64 v[136:137], v[136:137], 0, s[28:29]
	v_mad_u64_u32 v[62:63], s[4:5], v136, s7, v[110:111]
	s_waitcnt lgkmcnt(0)
	v_pk_add_f32 v[46:47], v[34:35], v[40:41]
	ds_bpermute_b32 v53, v103, v47
	ds_bpermute_b32 v52, v103, v46
	v_lshl_add_u64 v[44:45], v[170:171], 0, v[152:153]
	v_mad_i32_i24 v63, v137, s7, v63
	flat_load_dwordx4 v[40:43], v[44:45]
	flat_load_dwordx4 v[32:35], v[44:45] offset:1024
	flat_load_dwordx4 v[68:71], v[62:63]
	flat_load_dwordx4 v[64:67], v[62:63] offset:1024
	v_mov_b32_e32 v149, v153
	s_waitcnt lgkmcnt(0)
	v_pk_add_f32 v[46:47], v[46:47], v[52:53]
	ds_bpermute_b32 v53, v105, v47
	ds_bpermute_b32 v52, v105, v46
	v_mov_b32_e32 v143, v153
	s_mov_b32 s2, 0x3727c5ac
	v_lshl_add_u64 v[148:149], v[60:61], 0, v[148:149]
	v_lshl_add_u64 v[60:61], v[60:61], 0, v[142:143]
	s_waitcnt lgkmcnt(0)
	v_pk_add_f32 v[144:145], v[46:47], v[52:53]
	ds_bpermute_b32 v147, v225, v145
	ds_bpermute_b32 v146, v225, v144
	flat_load_dwordx4 v[52:55], v[44:45] offset:2048
	s_nop 0
	flat_load_dwordx4 v[44:47], v[44:45] offset:3072
	s_nop 0
	flat_load_dwordx4 v[76:79], v[62:63] offset:2048
	flat_load_dwordx4 v[72:75], v[62:63] offset:3072
	v_mov_b64_e32 v[142:143], s[2:3]
	s_mov_b32 s2, 0x3a800000
	v_pk_mul_f32 v[230:231], v[24:25], 0.5 op_sel_hi:[1,0]
	s_waitcnt lgkmcnt(0)
	v_pk_add_f32 v[62:63], v[144:145], v[146:147]
	ds_bpermute_b32 v183, v226, v63
	ds_bpermute_b32 v182, v226, v62
	flat_load_dwordx2 v[174:175], v[172:173]
	flat_load_dwordx2 v[170:171], v[172:173] offset:512
	flat_load_dwordx2 v[146:147], v[172:173] offset:1024
	flat_load_dwordx2 v[144:145], v[172:173] offset:1536
	v_pk_mul_f32 v[228:229], v[26:27], 0.5 op_sel_hi:[1,0]
	v_pk_mul_f32 v[196:197], v[28:29], 0.5 op_sel_hi:[1,0]
	v_lshlrev_b32_e32 v198, 16, v162
	s_waitcnt lgkmcnt(0)
	v_pk_add_f32 v[62:63], v[62:63], v[182:183]
	flat_load_dwordx2 v[182:183], v[180:181]
	s_nop 0
	flat_load_dwordx2 v[180:181], v[192:193]
	flat_load_dwordx2 v[172:173], v[148:149]
	s_nop 0
	flat_load_dwordx2 v[148:149], v[60:61]
	v_pk_fma_f32 v[194:195], v[62:63], s[2:3], v[142:143] op_sel_hi:[1,0,0]
	v_lshlrev_b64 v[60:61], 12, v[138:139]
	v_mul_f32_e32 v62, 0x4b800000, v195
	v_cmp_gt_f32_e32 vcc, s68, v195
	v_lshl_add_u64 v[138:139], v[112:113], 0, v[60:61]
	v_mul_f32_e32 v24, 0x4b800000, v194
	v_cndmask_b32_e32 v62, v195, v62, vcc
	v_rsq_f32_e32 v62, v62
	v_and_b32_e32 v199, 0xffff0000, v162
	v_lshlrev_b32_e32 v162, 16, v163
	v_and_b32_e32 v163, 0xffff0000, v163
	v_mul_f32_e32 v60, 0x45800000, v62
	v_cndmask_b32_e32 v192, v62, v60, vcc
	v_pk_mul_f32 v[60:61], v[190:191], v[192:193] op_sel_hi:[1,0]
	v_pk_mul_f32 v[62:63], v[188:189], v[192:193] op_sel_hi:[1,0]
	s_waitcnt vmcnt(0) lgkmcnt(0)
	v_pk_fma_f32 v[60:61], v[36:37], v[60:61], v[56:57]
	v_pk_fma_f32 v[62:63], v[38:39], v[62:63], v[58:59]
	flat_store_dwordx4 v[138:139], v[60:63]
	ds_read_b128 v[36:39], v210 offset:1024
	ds_read_b128 v[56:59], v210 offset:5120
	v_pk_mul_f32 v[186:187], v[186:187], v[192:193] op_sel_hi:[1,0]
	v_pk_mul_f32 v[184:185], v[184:185], v[192:193] op_sel_hi:[1,0]
	v_pk_mul_f32 v[50:51], v[50:51], v[192:193] op_sel_hi:[1,0]
	v_pk_mul_f32 v[48:49], v[48:49], v[192:193] op_sel_hi:[1,0]
	v_pk_mul_f32 v[178:179], v[178:179], v[192:193] op_sel_hi:[1,0]
	v_pk_mul_f32 v[176:177], v[176:177], v[192:193] op_sel_hi:[1,0]
	v_cmp_gt_f32_e32 vcc, s68, v194
	v_pk_mul_f32 v[192:193], v[30:31], 0.5 op_sel_hi:[1,0]
	v_lshlrev_b32_e32 v188, 16, v166
	v_cndmask_b32_e32 v24, v194, v24, vcc
	v_rsq_f32_e32 v26, v24
	v_lshlrev_b64 v[24:25], 12, v[140:141]
	v_and_b32_e32 v189, 0xffff0000, v166
	v_lshlrev_b32_e32 v166, 16, v167
	v_and_b32_e32 v167, 0xffff0000, v167
	v_lshlrev_b32_e32 v190, 16, v168
	v_and_b32_e32 v191, 0xffff0000, v168
	v_lshlrev_b32_e32 v168, 16, v169
	v_and_b32_e32 v169, 0xffff0000, v169
	v_lshlrev_b32_e32 v200, 16, v164
	v_and_b32_e32 v201, 0xffff0000, v164
	v_lshlrev_b32_e32 v164, 16, v165
	v_and_b32_e32 v165, 0xffff0000, v165
	v_lshlrev_b32_e32 v202, 16, v158
	v_and_b32_e32 v203, 0xffff0000, v158
	v_lshlrev_b32_e32 v158, 16, v159
	v_and_b32_e32 v159, 0xffff0000, v159
	v_lshlrev_b32_e32 v204, 16, v160
	v_and_b32_e32 v205, 0xffff0000, v160
	v_lshlrev_b32_e32 v160, 16, v161
	v_and_b32_e32 v161, 0xffff0000, v161
	v_pk_add_f32 v[166:167], v[166:167], v[168:169]
	v_pk_add_f32 v[168:169], v[188:189], v[190:191]
	v_pk_mul_f32 v[22:23], v[22:23], 0.5 op_sel_hi:[1,0]
	v_pk_mul_f32 v[20:21], v[20:21], 0.5 op_sel_hi:[1,0]
	v_lshlrev_b32_e32 v232, 16, v150
	v_and_b32_e32 v233, 0xffff0000, v150
	v_lshlrev_b32_e32 v150, 16, v151
	v_and_b32_e32 v151, 0xffff0000, v151
	v_lshlrev_b32_e32 v234, 16, v156
	v_and_b32_e32 v235, 0xffff0000, v156
	v_lshlrev_b32_e32 v156, 16, v157
	v_and_b32_e32 v157, 0xffff0000, v157
	v_pk_add_f32 v[162:163], v[162:163], v[164:165]
	v_pk_add_f32 v[164:165], v[198:199], v[200:201]
	v_pk_add_f32 v[158:159], v[158:159], v[160:161]
	v_pk_add_f32 v[160:161], v[202:203], v[204:205]
	v_pk_mul_f32 v[168:169], v[196:197], v[168:169]
	v_pk_mul_f32 v[166:167], v[192:193], v[166:167]
	v_pk_mul_f32 v[18:19], v[18:19], 0.5 op_sel_hi:[1,0]
	v_pk_mul_f32 v[16:17], v[16:17], 0.5 op_sel_hi:[1,0]
	v_pk_add_f32 v[150:151], v[150:151], v[156:157]
	v_pk_add_f32 v[156:157], v[232:233], v[234:235]
	v_pk_mul_f32 v[164:165], v[20:21], v[164:165]
	v_pk_mul_f32 v[162:163], v[22:23], v[162:163]
	v_pk_mul_f32 v[160:161], v[230:231], v[160:161]
	v_pk_fma_f32 v[22:23], v[2:3], s[42:43], v[166:167] op_sel_hi:[1,0,1]
	v_pk_fma_f32 v[20:21], v[0:1], s[42:43], v[168:169] op_sel_hi:[1,0,1]
	v_pk_mul_f32 v[158:159], v[228:229], v[158:159]
	v_pk_mul_f32 v[156:157], v[16:17], v[156:157]
	v_pk_mul_f32 v[150:151], v[18:19], v[150:151]
	v_pk_fma_f32 v[18:19], v[6:7], s[42:43], v[162:163] op_sel_hi:[1,0,1]
	v_pk_fma_f32 v[16:17], v[4:5], s[42:43], v[164:165] op_sel_hi:[1,0,1]
	v_pk_fma_f32 v[4:5], v[8:9], s[42:43], v[160:161] op_sel_hi:[1,0,1]
	v_add_f32_e32 v8, v20, v21
	v_add_f32_e32 v9, v22, v23
	v_pk_fma_f32 v[6:7], v[10:11], s[42:43], v[158:159] op_sel_hi:[1,0,1]
	v_add_f32_e32 v10, v16, v17
	v_add_f32_e32 v11, v18, v19
	v_add_f32_e32 v8, v8, v9
	v_pk_fma_f32 v[2:3], v[14:15], s[42:43], v[150:151] op_sel_hi:[1,0,1]
	v_pk_fma_f32 v[0:1], v[12:13], s[42:43], v[156:157] op_sel_hi:[1,0,1]
	v_add_f32_e32 v12, v4, v5
	v_add_f32_e32 v13, v6, v7
	v_add_f32_e32 v9, v10, v11
	v_add_f32_e32 v8, 0, v8
	v_add_f32_e32 v14, v0, v1
	v_add_f32_e32 v15, v2, v3
	v_add_f32_e32 v10, v12, v13
	s_waitcnt vmcnt(1) lgkmcnt(0)
	v_pk_fma_f32 v[56:57], v[36:37], v[184:185], v[56:57]
	v_pk_fma_f32 v[58:59], v[38:39], v[186:187], v[58:59]
	flat_store_dwordx4 v[138:139], v[56:59] offset:1024
	ds_read_b128 v[36:39], v210 offset:2048
	ds_read_b128 v[184:187], v210 offset:6144
	v_add_f32_e32 v8, v8, v9
	v_add_f32_e32 v11, v14, v15
	v_add_f32_e32 v8, v8, v10
	v_add_f32_e32 v8, v8, v11
	ds_bpermute_b32 v9, v99, v8
	v_lshlrev_b32_e32 v14, 16, v171
	v_and_b32_e32 v15, 0xffff0000, v171
	s_waitcnt lgkmcnt(0)
	v_lshlrev_b32_e32 v162, 16, v182
	v_and_b32_e32 v163, 0xffff0000, v182
	v_add_f32_e32 v8, v8, v9
	ds_bpermute_b32 v9, v101, v8
	v_lshlrev_b32_e32 v164, 16, v183
	v_and_b32_e32 v165, 0xffff0000, v183
	v_lshlrev_b32_e32 v168, 16, v181
	v_and_b32_e32 v169, 0xffff0000, v181
	s_waitcnt lgkmcnt(0)
	v_add_f32_e32 v8, v8, v9
	ds_bpermute_b32 v9, v103, v8
	v_and_b32_e32 v13, 0xffff0000, v170
	v_lshlrev_b32_e32 v166, 16, v180
	v_and_b32_e32 v167, 0xffff0000, v180
	v_pk_add_f32 v[14:15], v[14:15], v[168:169]
	s_waitcnt lgkmcnt(0)
	v_add_f32_e32 v8, v8, v9
	ds_bpermute_b32 v9, v105, v8
	v_pk_mul_f32 v[70:71], v[70:71], 0.5 op_sel_hi:[1,0]
	v_pk_mul_f32 v[68:69], v[68:69], 0.5 op_sel_hi:[1,0]
	v_pk_mul_f32 v[66:67], v[66:67], 0.5 op_sel_hi:[1,0]
	v_pk_mul_f32 v[64:65], v[64:65], 0.5 op_sel_hi:[1,0]
	s_waitcnt lgkmcnt(0)
	v_add_f32_e32 v8, v8, v9
	ds_bpermute_b32 v9, v225, v8
	v_pk_mul_f32 v[66:67], v[66:67], v[14:15]
	v_lshlrev_b32_e32 v158, 16, v146
	v_and_b32_e32 v159, 0xffff0000, v146
	v_lshlrev_b32_e32 v146, 16, v147
	s_waitcnt lgkmcnt(0)
	v_add_f32_e32 v8, v8, v9
	ds_bpermute_b32 v9, v226, v8
	v_and_b32_e32 v147, 0xffff0000, v147
	v_lshlrev_b32_e32 v160, 16, v144
	v_and_b32_e32 v161, 0xffff0000, v144
	v_lshlrev_b32_e32 v144, 16, v145
	s_waitcnt lgkmcnt(0)
	v_add_f32_e32 v12, v8, v9
	v_fmamk_f32 v21, v12, 0xba800000, v21
	v_fmac_f32_e32 v20, 0xba800000, v12
	v_fmamk_f32 v23, v12, 0xba800000, v23
	v_fmac_f32_e32 v22, 0xba800000, v12
	v_fmamk_f32 v17, v12, 0xba800000, v17
	v_fmac_f32_e32 v16, 0xba800000, v12
	v_fmamk_f32 v19, v12, 0xba800000, v19
	v_fmac_f32_e32 v18, 0xba800000, v12
	v_fmamk_f32 v5, v12, 0xba800000, v5
	v_fmac_f32_e32 v4, 0xba800000, v12
	v_fmamk_f32 v7, v12, 0xba800000, v7
	v_fmac_f32_e32 v6, 0xba800000, v12
	v_fmamk_f32 v3, v12, 0xba800000, v3
	v_fmac_f32_e32 v2, 0xba800000, v12
	v_fmamk_f32 v1, v12, 0xba800000, v1
	v_fmac_f32_e32 v0, 0xba800000, v12
	v_lshlrev_b32_e32 v12, 16, v170
	v_pk_add_f32 v[12:13], v[12:13], v[166:167]
	v_and_b32_e32 v145, 0xffff0000, v145
	v_pk_mul_f32 v[64:65], v[64:65], v[12:13]
	v_lshlrev_b32_e32 v170, 16, v172
	v_and_b32_e32 v171, 0xffff0000, v172
	v_lshlrev_b32_e32 v172, 16, v173
	v_and_b32_e32 v173, 0xffff0000, v173
	v_pk_add_f32 v[158:159], v[158:159], v[170:171]
	v_pk_add_f32 v[146:147], v[146:147], v[172:173]
	v_pk_mul_f32 v[78:79], v[78:79], 0.5 op_sel_hi:[1,0]
	v_pk_mul_f32 v[76:77], v[76:77], 0.5 op_sel_hi:[1,0]
	v_pk_mul_f32 v[74:75], v[74:75], 0.5 op_sel_hi:[1,0]
	v_pk_mul_f32 v[72:73], v[72:73], 0.5 op_sel_hi:[1,0]
	v_pk_mul_f32 v[150:151], v[22:23], v[22:23]
	v_pk_mul_f32 v[156:157], v[20:21], v[20:21]
	v_readlane_b32 s4, v254, 33
	v_readlane_b32 s5, v254, 34
	s_waitcnt vmcnt(2) lgkmcnt(0)
	v_pk_fma_f32 v[48:49], v[36:37], v[48:49], v[184:185]
	v_pk_fma_f32 v[50:51], v[38:39], v[50:51], v[186:187]
	flat_store_dwordx4 v[138:139], v[48:51] offset:2048
	ds_read_b128 v[36:39], v210 offset:3072
	ds_read_b128 v[184:187], v210 offset:7168
	s_waitcnt vmcnt(3) lgkmcnt(0)
	v_pk_fma_f32 v[36:37], v[36:37], v[176:177], v[184:185]
	v_pk_fma_f32 v[38:39], v[38:39], v[178:179], v[186:187]
	flat_store_dwordx4 v[138:139], v[36:39] offset:3072
	ds_read_b128 v[176:179], v210
	ds_read_b128 v[184:187], v210 offset:4096
	v_lshl_add_u64 v[138:139], v[112:113], 0, v[24:25]
	v_mul_f32_e32 v24, 0x45800000, v26
	v_cndmask_b32_e32 v140, v26, v24, vcc
	v_pk_mul_f32 v[26:27], v[90:91], v[140:141] op_sel_hi:[1,0]
	v_pk_mul_f32 v[24:25], v[88:89], v[140:141] op_sel_hi:[1,0]
	v_pk_mul_f32 v[8:9], v[86:87], v[140:141] op_sel_hi:[1,0]
	v_pk_mul_f32 v[10:11], v[84:85], v[140:141] op_sel_hi:[1,0]
	s_waitcnt vmcnt(4) lgkmcnt(0)
	v_pk_fma_f32 v[24:25], v[176:177], v[24:25], v[184:185]
	v_pk_fma_f32 v[26:27], v[178:179], v[26:27], v[186:187]
	flat_store_dwordx4 v[138:139], v[24:27]
	ds_read_b128 v[28:31], v210 offset:1024
	ds_read_b128 v[88:91], v210 offset:5120
	s_waitcnt vmcnt(5) lgkmcnt(0)
	v_pk_fma_f32 v[28:29], v[28:29], v[10:11], v[88:89]
	v_pk_fma_f32 v[30:31], v[30:31], v[8:9], v[90:91]
	flat_store_dwordx4 v[138:139], v[28:31] offset:1024
	ds_read_b128 v[84:87], v210 offset:2048
	ds_read_b128 v[88:91], v210 offset:6144
	v_lshlrev_b32_e32 v8, 16, v174
	v_and_b32_e32 v9, 0xffff0000, v174
	v_lshlrev_b32_e32 v10, 16, v175
	v_and_b32_e32 v11, 0xffff0000, v175
	v_pk_add_f32 v[8:9], v[8:9], v[162:163]
	v_pk_add_f32 v[10:11], v[10:11], v[164:165]
	v_pk_mul_f32 v[8:9], v[68:69], v[8:9]
	v_pk_mul_f32 v[10:11], v[70:71], v[10:11]
	v_pk_fma_f32 v[12:13], v[40:41], s[42:43], v[8:9] op_sel_hi:[1,0,1]
	v_pk_fma_f32 v[14:15], v[42:43], s[42:43], v[10:11] op_sel_hi:[1,0,1]
	v_pk_fma_f32 v[8:9], v[34:35], s[42:43], v[66:67] op_sel_hi:[1,0,1]
	v_pk_mul_f32 v[10:11], v[82:83], v[140:141] op_sel_hi:[1,0]
	v_pk_mul_f32 v[34:35], v[80:81], v[140:141] op_sel_hi:[1,0]
	v_lshlrev_b32_e32 v174, 16, v148
	v_and_b32_e32 v175, 0xffff0000, v148
	v_lshlrev_b32_e32 v148, 16, v149
	v_and_b32_e32 v149, 0xffff0000, v149
	v_pk_add_f32 v[160:161], v[160:161], v[174:175]
	v_pk_add_f32 v[144:145], v[144:145], v[148:149]
	v_pk_mul_f32 v[68:69], v[78:79], v[146:147]
	v_pk_mul_f32 v[146:147], v[76:77], v[158:159]
	v_pk_mul_f32 v[144:145], v[74:75], v[144:145]
	v_pk_mul_f32 v[148:149], v[72:73], v[160:161]
	v_pk_fma_f32 v[66:67], v[46:47], s[42:43], v[144:145] op_sel_hi:[1,0,1]
	v_mov_b32_e32 v47, v9
	v_pk_fma_f32 v[70:71], v[54:55], s[42:43], v[68:69] op_sel_hi:[1,0,1]
	v_pk_fma_f32 v[68:69], v[52:53], s[42:43], v[146:147] op_sel_hi:[1,0,1]
	v_add_f32_e32 v54, v70, v71
	v_add_f32_e32 v52, v68, v69
	v_mov_b32_e32 v53, v66
	v_mov_b32_e32 v55, v67
	s_waitcnt vmcnt(6) lgkmcnt(0)
	v_pk_fma_f32 v[40:41], v[84:85], v[34:35], v[88:89]
	v_pk_fma_f32 v[42:43], v[86:87], v[10:11], v[90:91]
	flat_store_dwordx4 v[138:139], v[40:43] offset:2048
	ds_read_b128 v[72:75], v210 offset:3072
	ds_read_b128 v[76:79], v210 offset:7168
	v_pk_fma_f32 v[10:11], v[32:33], s[42:43], v[64:65] op_sel_hi:[1,0,1]
	v_pk_fma_f32 v[64:65], v[44:45], s[42:43], v[148:149] op_sel_hi:[1,0,1]
	v_pk_mov_b32 v[32:33], v[12:13], v[14:15] op_sel:[1,0]
	v_mov_b32_e32 v34, v12
	v_mov_b32_e32 v35, v15
	v_pk_mov_b32 v[44:45], v[10:11], v[8:9] op_sel:[1,0]
	v_mov_b32_e32 v46, v10
	v_pk_add_f32 v[32:33], v[32:33], v[34:35]
	v_pk_add_f32 v[34:35], v[44:45], v[46:47]
	v_add_f32_e32 v46, v32, v33
	v_pk_add_f32 v[32:33], v[34:35], v[34:35] op_sel:[0,1] op_sel_hi:[1,0]
	v_mov_b32_e32 v81, v64
	v_add_f32_e32 v80, 0, v46
	v_mov_b32_e32 v33, v65
	v_pk_add_f32 v[44:45], v[52:53], v[54:55]
	v_pk_add_f32 v[32:33], v[80:81], v[32:33]
	v_pk_mul_f32 v[34:35], v[16:17], v[16:17]
	v_pk_add_f32 v[32:33], v[32:33], v[44:45]
	v_mul_f32_e32 v44, v4, v4
	v_add_f32_e32 v45, v32, v33
	ds_bpermute_b32 v47, v99, v45
	v_pk_mul_f32 v[32:33], v[18:19], v[18:19]
	v_mul_f32_e32 v46, v6, v6
	v_pk_mov_b32 v[52:53], v[156:157], v[150:151] op_sel:[1,0]
	v_mov_b32_e32 v157, v151
	s_waitcnt lgkmcnt(0)
	v_add_f32_e32 v45, v45, v47
	ds_bpermute_b32 v47, v101, v45
	v_pk_mov_b32 v[54:55], v[34:35], v[32:33] op_sel:[1,0]
	v_mov_b32_e32 v35, v33
	v_pk_fma_f32 v[32:33], v[4:5], v[4:5], v[44:45] op_sel_hi:[1,1,0]
	v_pk_add_f32 v[34:35], v[54:55], v[34:35]
	s_waitcnt lgkmcnt(0)
	v_add_f32_e32 v80, v45, v47
	ds_bpermute_b32 v81, v103, v80
	v_pk_fma_f32 v[44:45], v[6:7], v[6:7], v[46:47] op_sel_hi:[1,1,0]
	v_pk_add_f32 v[46:47], v[52:53], v[156:157]
	v_mul_f32_e32 v32, v0, v0
	v_mul_f32_e32 v44, v1, v1
	s_waitcnt lgkmcnt(0)
	v_add_f32_e32 v52, v80, v81
	ds_bpermute_b32 v53, v105, v52
	v_pk_add_f32 v[32:33], v[32:33], v[44:45]
	v_pk_add_f32 v[46:47], v[46:47], v[46:47] op_sel_hi:[0,1]
	v_pk_add_f32 v[34:35], v[34:35], v[34:35] op_sel_hi:[0,1]
	v_mul_f32_e32 v46, v2, v2
	s_waitcnt lgkmcnt(0)
	v_add_f32_e32 v52, v52, v53
	ds_bpermute_b32 v53, v225, v52
	v_mul_f32_e32 v34, v3, v3
	v_pk_add_f32 v[34:35], v[46:47], v[34:35]
	s_waitcnt lgkmcnt(0)
	v_add_f32_e32 v44, v52, v53
	ds_bpermute_b32 v45, v226, v44
	v_pk_add_f32 v[80:81], v[32:33], v[34:35]
	v_pk_mul_f32 v[32:33], v[94:95], v[140:141] op_sel_hi:[1,0]
	v_pk_mul_f32 v[34:35], v[92:93], v[140:141] op_sel_hi:[1,0]
	v_mov_b32_e32 v83, v80
	s_waitcnt lgkmcnt(0)
	v_add_f32_e32 v44, v44, v45
	v_fmamk_f32 v13, v44, 0xba800000, v13
	v_fmac_f32_e32 v12, 0xba800000, v44
	v_fmamk_f32 v15, v44, 0xba800000, v15
	v_fmac_f32_e32 v14, 0xba800000, v44
	v_fmamk_f32 v11, v44, 0xba800000, v11
	v_fmac_f32_e32 v10, 0xba800000, v44
	v_fmamk_f32 v9, v44, 0xba800000, v9
	v_fmac_f32_e32 v8, 0xba800000, v44
	v_fmamk_f32 v69, v44, 0xba800000, v69
	v_fmac_f32_e32 v68, 0xba800000, v44
	v_fmamk_f32 v71, v44, 0xba800000, v71
	v_fmac_f32_e32 v70, 0xba800000, v44
	v_fmamk_f32 v67, v44, 0xba800000, v67
	v_fmac_f32_e32 v66, 0xba800000, v44
	v_fmamk_f32 v65, v44, 0xba800000, v65
	v_fmac_f32_e32 v64, 0xba800000, v44
	v_pk_mul_f32 v[84:85], v[14:15], v[14:15]
	v_mul_f32_e32 v80, v70, v70
	s_waitcnt vmcnt(7) lgkmcnt(0)
	v_pk_fma_f32 v[52:53], v[72:73], v[34:35], v[76:77]
	v_pk_fma_f32 v[54:55], v[74:75], v[32:33], v[78:79]
	flat_store_dwordx4 v[138:139], v[52:55] offset:3072
	ds_read_b128 v[32:35], v210
	ds_read_b128 v[44:47], v210 offset:4096
	v_pk_mul_f32 v[72:73], v[12:13], v[12:13]
	v_pk_mul_f32 v[74:75], v[8:9], v[8:9]
	v_pk_mul_f32 v[76:77], v[10:11], v[10:11]
	v_pk_mov_b32 v[86:87], v[72:73], v[84:85] op_sel:[1,0]
	v_mov_b32_e32 v73, v85
	v_pk_mov_b32 v[84:85], v[76:77], v[74:75] op_sel:[1,0]
	v_mov_b32_e32 v77, v75
	v_mul_f32_e32 v78, v68, v68
	v_pk_add_f32 v[72:73], v[86:87], v[72:73]
	v_pk_add_f32 v[76:77], v[84:85], v[76:77]
	v_pk_fma_f32 v[74:75], v[68:69], v[68:69], v[78:79] op_sel_hi:[1,1,0]
	v_pk_fma_f32 v[78:79], v[70:71], v[70:71], v[80:81] op_sel_hi:[1,1,0]
	v_pk_add_f32 v[72:73], v[72:73], v[72:73] op_sel_hi:[0,1]
	v_pk_add_f32 v[76:77], v[76:77], v[76:77] op_sel_hi:[0,1]
	v_mul_f32_e32 v74, v64, v64
	v_mul_f32_e32 v78, v65, v65
	v_mul_f32_e32 v72, v66, v66
	v_mul_f32_e32 v76, v67, v67
	v_pk_add_f32 v[74:75], v[74:75], v[78:79]
	v_pk_add_f32 v[72:73], v[72:73], v[76:77]
	s_nop 0
	v_pk_add_f32 v[72:73], v[74:75], v[72:73]
	s_nop 0
	v_mov_b32_e32 v82, v72
	v_mov_b32_e32 v80, v73
	v_pk_add_f32 v[72:73], v[82:83], v[80:81]
	ds_bpermute_b32 v75, v99, v73
	ds_bpermute_b32 v74, v99, v72
	s_waitcnt lgkmcnt(0)
	v_pk_add_f32 v[72:73], v[72:73], v[74:75]
	ds_bpermute_b32 v75, v101, v73
	ds_bpermute_b32 v74, v101, v72
	s_waitcnt lgkmcnt(0)
	v_pk_add_f32 v[72:73], v[72:73], v[74:75]
	ds_bpermute_b32 v75, v103, v73
	ds_bpermute_b32 v74, v103, v72
	s_waitcnt lgkmcnt(0)
	v_pk_add_f32 v[72:73], v[72:73], v[74:75]
	ds_bpermute_b32 v75, v105, v73
	ds_bpermute_b32 v74, v105, v72
	s_waitcnt lgkmcnt(0)
	v_pk_add_f32 v[72:73], v[72:73], v[74:75]
	ds_bpermute_b32 v75, v225, v73
	ds_bpermute_b32 v74, v225, v72
	s_waitcnt lgkmcnt(0)
	v_pk_add_f32 v[72:73], v[72:73], v[74:75]
	ds_bpermute_b32 v75, v226, v73
	ds_bpermute_b32 v74, v226, v72
	s_waitcnt lgkmcnt(0)
	v_pk_add_f32 v[72:73], v[72:73], v[74:75]
	s_nop 0
	v_pk_fma_f32 v[72:73], v[72:73], s[2:3], v[142:143] op_sel_hi:[1,0,0]
	s_nop 0
	v_mul_f32_e32 v74, 0x4b800000, v73
	v_cmp_gt_f32_e32 vcc, s68, v73
	s_nop 1
	v_cndmask_b32_e32 v73, v73, v74, vcc
	v_rsq_f32_e32 v73, v73
	v_lshlrev_b64 v[74:75], 12, v[132:133]
	v_lshl_add_u64 v[74:75], v[112:113], 0, v[74:75]
	v_mul_f32_e32 v76, 0x45800000, v73
	v_cndmask_b32_e32 v76, v73, v76, vcc
	v_pk_mul_f32 v[22:23], v[22:23], v[76:77] op_sel_hi:[1,0]
	v_pk_mul_f32 v[20:21], v[20:21], v[76:77] op_sel_hi:[1,0]
	s_waitcnt vmcnt(8) lgkmcnt(0)
	v_pk_fma_f32 v[46:47], v[34:35], v[22:23], v[46:47]
	v_pk_fma_f32 v[44:45], v[32:33], v[20:21], v[44:45]
	flat_store_dwordx4 v[74:75], v[44:47]
	ds_read_b128 v[20:23], v210 offset:1024
	ds_read_b128 v[32:35], v210 offset:5120
	v_pk_mul_f32 v[18:19], v[18:19], v[76:77] op_sel_hi:[1,0]
	v_pk_mul_f32 v[16:17], v[16:17], v[76:77] op_sel_hi:[1,0]
	v_pk_mul_f32 v[6:7], v[6:7], v[76:77] op_sel_hi:[1,0]
	v_pk_mul_f32 v[4:5], v[4:5], v[76:77] op_sel_hi:[1,0]
	v_pk_mul_f32 v[2:3], v[2:3], v[76:77] op_sel_hi:[1,0]
	v_pk_mul_f32 v[0:1], v[0:1], v[76:77] op_sel_hi:[1,0]
	v_mul_f32_e32 v73, 0x4b800000, v72
	v_cmp_gt_f32_e32 vcc, s68, v72
	s_waitcnt vmcnt(9) lgkmcnt(0)
	v_pk_fma_f32 v[32:33], v[20:21], v[16:17], v[32:33]
	v_pk_fma_f32 v[34:35], v[22:23], v[18:19], v[34:35]
	flat_store_dwordx4 v[74:75], v[32:35] offset:1024
	ds_read_b128 v[16:19], v210 offset:2048
	ds_read_b128 v[20:23], v210 offset:6144
	v_cndmask_b32_e32 v72, v72, v73, vcc
	s_waitcnt vmcnt(10) lgkmcnt(0)
	v_pk_fma_f32 v[20:21], v[16:17], v[4:5], v[20:21]
	v_pk_fma_f32 v[22:23], v[18:19], v[6:7], v[22:23]
	flat_store_dwordx4 v[74:75], v[20:23] offset:2048
	ds_read_b128 v[4:7], v210 offset:3072
	ds_read_b128 v[16:19], v210 offset:7168
	s_waitcnt vmcnt(11) lgkmcnt(0)
	v_pk_fma_f32 v[16:17], v[4:5], v[0:1], v[16:17]
	v_pk_fma_f32 v[18:19], v[6:7], v[2:3], v[18:19]
	flat_store_dwordx4 v[74:75], v[16:19] offset:3072
	ds_read_b128 v[0:3], v210
	ds_read_b128 v[4:7], v210 offset:4096
	v_rsq_f32_e32 v74, v72
	v_lshl_add_u64 v[72:73], v[112:113], 0, v[134:135]
	v_mul_f32_e32 v75, 0x45800000, v74
	v_cndmask_b32_e32 v74, v74, v75, vcc
	v_pk_mul_f32 v[14:15], v[14:15], v[74:75] op_sel_hi:[1,0]
	v_pk_mul_f32 v[12:13], v[12:13], v[74:75] op_sel_hi:[1,0]
	v_pk_mul_f32 v[76:77], v[8:9], v[74:75] op_sel_hi:[1,0]
	v_pk_mul_f32 v[8:9], v[10:11], v[74:75] op_sel_hi:[1,0]
	v_pk_mul_f32 v[70:71], v[70:71], v[74:75] op_sel_hi:[1,0]
	v_pk_mul_f32 v[68:69], v[68:69], v[74:75] op_sel_hi:[1,0]
	v_pk_mul_f32 v[66:67], v[66:67], v[74:75] op_sel_hi:[1,0]
	v_pk_mul_f32 v[64:65], v[64:65], v[74:75] op_sel_hi:[1,0]
	s_andn2_b64 vcc, exec, s[4:5]
	s_waitcnt vmcnt(12) lgkmcnt(0)
	v_pk_fma_f32 v[12:13], v[0:1], v[12:13], v[4:5]
	v_pk_fma_f32 v[14:15], v[2:3], v[14:15], v[6:7]
	flat_store_dwordx4 v[72:73], v[12:15]
	ds_read_b128 v[0:3], v210 offset:1024
	ds_read_b128 v[4:7], v210 offset:5120
	s_waitcnt vmcnt(13) lgkmcnt(0)
	v_pk_fma_f32 v[8:9], v[0:1], v[8:9], v[4:5]
	v_pk_fma_f32 v[10:11], v[2:3], v[76:77], v[6:7]
	flat_store_dwordx4 v[72:73], v[8:11] offset:1024
	ds_read_b128 v[0:3], v210 offset:2048
	ds_read_b128 v[4:7], v210 offset:6144
	s_waitcnt vmcnt(14) lgkmcnt(0)
	v_pk_fma_f32 v[4:5], v[0:1], v[68:69], v[4:5]
	v_pk_fma_f32 v[6:7], v[2:3], v[70:71], v[6:7]
	flat_store_dwordx4 v[72:73], v[4:7] offset:2048
	ds_read_b128 v[0:3], v210 offset:3072
	ds_read_b128 v[68:71], v210 offset:7168
	s_waitcnt vmcnt(15) lgkmcnt(0)
	v_pk_fma_f32 v[0:1], v[0:1], v[64:65], v[68:69]
	v_pk_fma_f32 v[2:3], v[2:3], v[66:67], v[70:71]
	flat_store_dwordx4 v[72:73], v[0:3] offset:3072
	s_cbranch_vccnz .LBB0_179
	v_mad_u64_u32 v[70:71], s[4:5], v126, s7, 0
	v_mad_i32_i24 v71, v127, s7, v71
	v_mad_u64_u32 v[68:69], s[4:5], v128, s7, 0
	v_mad_u64_u32 v[66:67], s[4:5], v130, s7, 0
	v_mad_u64_u32 v[64:65], s[4:5], v136, s7, 0
	v_lshl_add_u64 v[70:71], s[60:61], 0, v[70:71]
	s_mov_b64 s[4:5], 0x3000
	s_mov_b64 s[8:9], 0x4000
	v_lshl_add_u64 v[72:73], v[70:71], 0, s[4:5]
	v_lshl_add_u64 v[70:71], v[70:71], 0, s[8:9]
	v_lshl_add_u64 v[74:75], v[72:73], 0, v[152:153]
	v_lshl_add_u64 v[78:79], v[70:71], 0, v[152:153]
	global_load_dwordx4 v[214:217], v[74:75], off offset:1024
	global_load_dwordx4 v[218:221], v[74:75], off offset:2048
	flat_load_dwordx4 v[74:77], v[74:75]
	v_mad_i32_i24 v69, v129, s7, v69
	global_load_dwordx4 v[236:239], v[78:79], off offset:1024
	global_load_dwordx4 v[240:243], v[78:79], off offset:2048
	flat_load_dwordx4 v[78:81], v[78:79]
	v_mad_i32_i24 v67, v131, s7, v67
	v_mad_i32_i24 v65, v137, s7, v65
	s_waitcnt vmcnt(0) lgkmcnt(0)
	v_pk_add_f32 v[80:81], v[80:81], 1.0 op_sel_hi:[1,0]
	v_pk_add_f32 v[78:79], v[78:79], 1.0 op_sel_hi:[1,0]
	v_pk_fma_f32 v[62:63], v[62:63], v[80:81], v[76:77]
	v_pk_fma_f32 v[60:61], v[60:61], v[78:79], v[74:75]
	s_nop 0
	v_cvt_pk_bf16_f32 v60, v60, v61
	v_cvt_pk_bf16_f32 v61, v62, v63
	flat_store_dwordx2 v[118:119], v[60:61]
	v_lshlrev_b32_e32 v60, 2, v100
	v_mov_b32_e32 v61, v153
	v_lshl_add_u64 v[62:63], v[72:73], 0, v[60:61]
	v_mov_b64_e32 v[74:75], v[214:215]
	v_mov_b64_e32 v[76:77], v[216:217]
	v_lshl_add_u64 v[62:63], v[70:71], 0, v[60:61]
	v_mov_b64_e32 v[78:79], v[236:237]
	v_mov_b64_e32 v[80:81], v[238:239]
	v_pk_add_f32 v[62:63], v[80:81], 1.0 op_sel_hi:[1,0]
	v_pk_add_f32 v[78:79], v[78:79], 1.0 op_sel_hi:[1,0]
	v_pk_fma_f32 v[58:59], v[58:59], v[62:63], v[76:77]
	v_pk_fma_f32 v[56:57], v[56:57], v[78:79], v[74:75]
	s_nop 0
	v_cvt_pk_bf16_f32 v56, v56, v57
	v_cvt_pk_bf16_f32 v57, v58, v59
	flat_store_dwordx2 v[118:119], v[56:57] offset:512
	v_lshlrev_b32_e32 v56, 2, v102
	v_mov_b32_e32 v57, v153
	v_lshl_add_u64 v[58:59], v[72:73], 0, v[56:57]
	v_mov_b64_e32 v[74:75], v[218:219]
	v_mov_b64_e32 v[76:77], v[220:221]
	v_lshl_add_u64 v[58:59], v[70:71], 0, v[56:57]
	v_mov_b64_e32 v[78:79], v[240:241]
	v_mov_b64_e32 v[80:81], v[242:243]
	v_pk_add_f32 v[58:59], v[80:81], 1.0 op_sel_hi:[1,0]
	v_pk_add_f32 v[62:63], v[78:79], 1.0 op_sel_hi:[1,0]
	v_pk_fma_f32 v[50:51], v[50:51], v[58:59], v[76:77]
	v_pk_fma_f32 v[48:49], v[48:49], v[62:63], v[74:75]
	s_nop 0
	v_cvt_pk_bf16_f32 v48, v48, v49
	v_cvt_pk_bf16_f32 v49, v50, v51
	flat_store_dwordx2 v[118:119], v[48:49] offset:1024
	v_lshlrev_b32_e32 v48, 2, v104
	v_mov_b32_e32 v49, v153
	v_lshl_add_u64 v[50:51], v[72:73], 0, v[48:49]
	flat_load_dwordx4 v[72:75], v[50:51]
	v_lshl_add_u64 v[50:51], v[70:71], 0, v[48:49]
	flat_load_dwordx4 v[76:79], v[50:51]
	s_waitcnt vmcnt(0) lgkmcnt(0)
	v_pk_add_f32 v[50:51], v[78:79], 1.0 op_sel_hi:[1,0]
	v_pk_add_f32 v[58:59], v[76:77], 1.0 op_sel_hi:[1,0]
	v_pk_fma_f32 v[38:39], v[38:39], v[50:51], v[74:75]
	v_pk_fma_f32 v[36:37], v[36:37], v[58:59], v[72:73]
	v_lshlrev_b64 v[50:51], 11, v[124:125]
	v_cvt_pk_bf16_f32 v36, v36, v37
	v_cvt_pk_bf16_f32 v37, v38, v39
	flat_store_dwordx2 v[118:119], v[36:37] offset:1536
	v_lshl_add_u64 v[36:37], s[60:61], 0, v[68:69]
	v_lshl_add_u64 v[38:39], v[36:37], 0, s[4:5]
	v_lshl_add_u64 v[36:37], v[36:37], 0, s[8:9]
	v_lshl_add_u64 v[58:59], v[38:39], 0, v[152:153]
	global_load_dwordx4 v[214:217], v[58:59], off offset:1024
	global_load_dwordx4 v[218:221], v[58:59], off offset:2048
	flat_load_dwordx4 v[68:71], v[58:59]
	v_lshl_add_u64 v[58:59], v[36:37], 0, v[152:153]
	global_load_dwordx4 v[236:239], v[58:59], off offset:1024
	global_load_dwordx4 v[240:243], v[58:59], off offset:2048
	flat_load_dwordx4 v[72:75], v[58:59]
	v_lshl_add_u64 v[50:51], v[114:115], 0, v[50:51]
	s_waitcnt vmcnt(0) lgkmcnt(0)
	v_pk_add_f32 v[58:59], v[74:75], 1.0 op_sel_hi:[1,0]
	v_pk_add_f32 v[62:63], v[72:73], 1.0 op_sel_hi:[1,0]
	v_pk_fma_f32 v[26:27], v[26:27], v[58:59], v[70:71]
	v_pk_fma_f32 v[24:25], v[24:25], v[62:63], v[68:69]
	v_lshl_add_u64 v[58:59], v[36:37], 0, v[60:61]
	v_cvt_pk_bf16_f32 v24, v24, v25
	v_cvt_pk_bf16_f32 v25, v26, v27
	flat_store_dwordx2 v[50:51], v[24:25]
	v_lshl_add_u64 v[24:25], v[38:39], 0, v[60:61]
	v_mov_b64_e32 v[24:25], v[214:215]
	v_mov_b64_e32 v[26:27], v[216:217]
	s_nop 0
	v_mov_b64_e32 v[68:69], v[236:237]
	v_mov_b64_e32 v[70:71], v[238:239]
	v_pk_add_f32 v[58:59], v[70:71], 1.0 op_sel_hi:[1,0]
	v_pk_add_f32 v[62:63], v[68:69], 1.0 op_sel_hi:[1,0]
	v_pk_fma_f32 v[26:27], v[30:31], v[58:59], v[26:27]
	v_pk_fma_f32 v[24:25], v[28:29], v[62:63], v[24:25]
	v_lshl_add_u64 v[28:29], v[36:37], 0, v[56:57]
	v_cvt_pk_bf16_f32 v24, v24, v25
	v_cvt_pk_bf16_f32 v25, v26, v27
	flat_store_dwordx2 v[50:51], v[24:25] offset:512
	v_lshl_add_u64 v[24:25], v[38:39], 0, v[56:57]
	v_mov_b64_e32 v[24:25], v[218:219]
	v_mov_b64_e32 v[26:27], v[220:221]
	s_nop 0
	v_mov_b64_e32 v[28:29], v[240:241]
	v_mov_b64_e32 v[30:31], v[242:243]
	v_pk_add_f32 v[30:31], v[30:31], 1.0 op_sel_hi:[1,0]
	v_pk_add_f32 v[28:29], v[28:29], 1.0 op_sel_hi:[1,0]
	v_pk_fma_f32 v[26:27], v[42:43], v[30:31], v[26:27]
	v_pk_fma_f32 v[24:25], v[40:41], v[28:29], v[24:25]
	v_lshl_add_u64 v[28:29], v[36:37], 0, v[48:49]
	v_cvt_pk_bf16_f32 v24, v24, v25
	v_cvt_pk_bf16_f32 v25, v26, v27
	flat_store_dwordx2 v[50:51], v[24:25] offset:1024
	v_lshl_add_u64 v[24:25], v[38:39], 0, v[48:49]
	flat_load_dwordx4 v[24:27], v[24:25]
	s_nop 0
	flat_load_dwordx4 v[28:31], v[28:29]
	s_waitcnt vmcnt(0) lgkmcnt(0)
	v_pk_add_f32 v[30:31], v[30:31], 1.0 op_sel_hi:[1,0]
	v_pk_add_f32 v[28:29], v[28:29], 1.0 op_sel_hi:[1,0]
	v_pk_fma_f32 v[26:27], v[54:55], v[30:31], v[26:27]
	v_pk_fma_f32 v[24:25], v[52:53], v[28:29], v[24:25]
	v_lshlrev_b64 v[30:31], 11, v[122:123]
	v_cvt_pk_bf16_f32 v24, v24, v25
	v_cvt_pk_bf16_f32 v25, v26, v27
	flat_store_dwordx2 v[50:51], v[24:25] offset:1536
	v_lshl_add_u64 v[24:25], s[60:61], 0, v[66:67]
	v_lshl_add_u64 v[40:41], v[24:25], 0, s[4:5]
	v_lshl_add_u64 v[24:25], v[24:25], 0, s[8:9]
	v_lshl_add_u64 v[26:27], v[40:41], 0, v[152:153]
	v_lshl_add_u64 v[36:37], v[24:25], 0, v[152:153]
	global_load_dwordx4 v[214:217], v[26:27], off offset:1024
	global_load_dwordx4 v[218:221], v[26:27], off offset:2048
	flat_load_dwordx4 v[26:29], v[26:27]
	v_lshl_add_u64 v[42:43], v[114:115], 0, v[30:31]
	global_load_dwordx4 v[236:239], v[36:37], off offset:1024
	global_load_dwordx4 v[240:243], v[36:37], off offset:2048
	flat_load_dwordx4 v[36:39], v[36:37]
	v_lshl_add_u64 v[30:31], v[24:25], 0, v[60:61]
	s_waitcnt vmcnt(0) lgkmcnt(0)
	v_pk_add_f32 v[38:39], v[38:39], 1.0 op_sel_hi:[1,0]
	v_pk_add_f32 v[36:37], v[36:37], 1.0 op_sel_hi:[1,0]
	v_pk_fma_f32 v[28:29], v[46:47], v[38:39], v[28:29]
	v_pk_fma_f32 v[26:27], v[44:45], v[36:37], v[26:27]
	s_nop 0
	v_cvt_pk_bf16_f32 v26, v26, v27
	v_cvt_pk_bf16_f32 v27, v28, v29
	flat_store_dwordx2 v[42:43], v[26:27]
	v_lshl_add_u64 v[26:27], v[40:41], 0, v[60:61]
	v_mov_b64_e32 v[26:27], v[214:215]
	v_mov_b64_e32 v[28:29], v[216:217]
	s_nop 0
	v_mov_b64_e32 v[36:37], v[236:237]
	v_mov_b64_e32 v[38:39], v[238:239]
	v_pk_add_f32 v[30:31], v[38:39], 1.0 op_sel_hi:[1,0]
	v_pk_add_f32 v[36:37], v[36:37], 1.0 op_sel_hi:[1,0]
	v_pk_fma_f32 v[28:29], v[34:35], v[30:31], v[28:29]
	v_pk_fma_f32 v[26:27], v[32:33], v[36:37], v[26:27]
	v_lshl_add_u64 v[30:31], v[24:25], 0, v[56:57]
	v_cvt_pk_bf16_f32 v26, v26, v27
	v_cvt_pk_bf16_f32 v27, v28, v29
	flat_store_dwordx2 v[42:43], v[26:27] offset:512
	v_lshl_add_u64 v[26:27], v[40:41], 0, v[56:57]
	v_mov_b64_e32 v[26:27], v[218:219]
	v_mov_b64_e32 v[28:29], v[220:221]
	v_lshl_add_u64 v[24:25], v[24:25], 0, v[48:49]
	v_mov_b64_e32 v[30:31], v[240:241]
	v_mov_b64_e32 v[32:33], v[242:243]
	v_pk_add_f32 v[32:33], v[32:33], 1.0 op_sel_hi:[1,0]
	v_pk_add_f32 v[30:31], v[30:31], 1.0 op_sel_hi:[1,0]
	v_pk_fma_f32 v[22:23], v[22:23], v[32:33], v[28:29]
	v_pk_fma_f32 v[20:21], v[20:21], v[30:31], v[26:27]
	v_lshlrev_b64 v[28:29], 11, v[120:121]
	v_cvt_pk_bf16_f32 v20, v20, v21
	v_cvt_pk_bf16_f32 v21, v22, v23
	flat_store_dwordx2 v[42:43], v[20:21] offset:1024
	v_lshl_add_u64 v[20:21], v[40:41], 0, v[48:49]
	flat_load_dwordx4 v[20:23], v[20:21]
	s_nop 0
	flat_load_dwordx4 v[24:27], v[24:25]
	s_waitcnt vmcnt(0) lgkmcnt(0)
	v_pk_add_f32 v[26:27], v[26:27], 1.0 op_sel_hi:[1,0]
	v_pk_add_f32 v[24:25], v[24:25], 1.0 op_sel_hi:[1,0]
	v_pk_fma_f32 v[18:19], v[18:19], v[26:27], v[22:23]
	v_pk_fma_f32 v[16:17], v[16:17], v[24:25], v[20:21]
	s_nop 0
	v_cvt_pk_bf16_f32 v16, v16, v17
	v_cvt_pk_bf16_f32 v17, v18, v19
	flat_store_dwordx2 v[42:43], v[16:17] offset:1536
	v_lshl_add_u64 v[16:17], s[60:61], 0, v[64:65]
	v_lshl_add_u64 v[26:27], v[16:17], 0, s[4:5]
	v_lshl_add_u64 v[16:17], v[16:17], 0, s[8:9]
	v_lshl_add_u64 v[18:19], v[26:27], 0, v[152:153]
	v_lshl_add_u64 v[22:23], v[16:17], 0, v[152:153]
	global_load_dwordx4 v[214:217], v[18:19], off offset:1024
	global_load_dwordx4 v[218:221], v[18:19], off offset:2048
	flat_load_dwordx4 v[18:21], v[18:19]
	s_nop 0
	global_load_dwordx4 v[236:239], v[22:23], off offset:1024
	global_load_dwordx4 v[240:243], v[22:23], off offset:2048
	flat_load_dwordx4 v[22:25], v[22:23]
	s_waitcnt vmcnt(0) lgkmcnt(0)
	v_pk_add_f32 v[24:25], v[24:25], 1.0 op_sel_hi:[1,0]
	v_pk_add_f32 v[22:23], v[22:23], 1.0 op_sel_hi:[1,0]
	v_pk_fma_f32 v[14:15], v[14:15], v[24:25], v[20:21]
	v_pk_fma_f32 v[12:13], v[12:13], v[22:23], v[18:19]
	v_lshl_add_u64 v[22:23], v[114:115], 0, v[28:29]
	v_cvt_pk_bf16_f32 v12, v12, v13
	v_cvt_pk_bf16_f32 v13, v14, v15
	flat_store_dwordx2 v[22:23], v[12:13]
	v_lshl_add_u64 v[12:13], v[26:27], 0, v[60:61]
	v_lshl_add_u64 v[18:19], v[16:17], 0, v[60:61]
	v_mov_b64_e32 v[12:13], v[214:215]
	v_mov_b64_e32 v[14:15], v[216:217]
	s_nop 0
	v_mov_b64_e32 v[18:19], v[236:237]
	v_mov_b64_e32 v[20:21], v[238:239]
	v_pk_add_f32 v[20:21], v[20:21], 1.0 op_sel_hi:[1,0]
	v_pk_add_f32 v[18:19], v[18:19], 1.0 op_sel_hi:[1,0]
	v_pk_fma_f32 v[10:11], v[10:11], v[20:21], v[14:15]
	v_pk_fma_f32 v[8:9], v[8:9], v[18:19], v[12:13]
	v_lshl_add_u64 v[12:13], v[16:17], 0, v[56:57]
	v_cvt_pk_bf16_f32 v8, v8, v9
	v_cvt_pk_bf16_f32 v9, v10, v11
	flat_store_dwordx2 v[22:23], v[8:9] offset:512
	v_lshl_add_u64 v[8:9], v[26:27], 0, v[56:57]
	v_mov_b64_e32 v[8:9], v[218:219]
	v_mov_b64_e32 v[10:11], v[220:221]
	s_nop 0
	v_mov_b64_e32 v[12:13], v[240:241]
	v_mov_b64_e32 v[14:15], v[242:243]
	v_pk_add_f32 v[14:15], v[14:15], 1.0 op_sel_hi:[1,0]
	v_pk_add_f32 v[12:13], v[12:13], 1.0 op_sel_hi:[1,0]
	v_pk_fma_f32 v[6:7], v[6:7], v[14:15], v[10:11]
	v_pk_fma_f32 v[4:5], v[4:5], v[12:13], v[8:9]
	v_lshl_add_u64 v[8:9], v[16:17], 0, v[48:49]
	v_cvt_pk_bf16_f32 v4, v4, v5
	v_cvt_pk_bf16_f32 v5, v6, v7
	flat_store_dwordx2 v[22:23], v[4:5] offset:1024
	v_lshl_add_u64 v[4:5], v[26:27], 0, v[48:49]
	flat_load_dwordx4 v[4:7], v[4:5]
	s_nop 0
	flat_load_dwordx4 v[8:11], v[8:9]
	s_waitcnt vmcnt(0) lgkmcnt(0)
	v_pk_add_f32 v[10:11], v[10:11], 1.0 op_sel_hi:[1,0]
	v_pk_add_f32 v[8:9], v[8:9], 1.0 op_sel_hi:[1,0]
	v_pk_fma_f32 v[2:3], v[2:3], v[10:11], v[6:7]
	v_pk_fma_f32 v[0:1], v[0:1], v[8:9], v[4:5]
	s_nop 0
	v_cvt_pk_bf16_f32 v0, v0, v1
	v_cvt_pk_bf16_f32 v1, v2, v3
	flat_store_dwordx2 v[22:23], v[0:1] offset:1536
	s_branch .LBB0_179

.LBB0_225:
	global_load_dwordx4 v[154:157], v[74:75], off
	global_load_dwordx4 v[158:161], v[76:77], off
	global_load_dwordx4 v[162:165], v[74:75], off offset:1024
	global_load_dwordx4 v[166:169], v[76:77], off offset:1024
	global_load_dwordx4 v[170:173], v[74:75], off offset:2048
	global_load_dwordx4 v[174:177], v[76:77], off offset:2048
	global_load_dwordx4 v[178:181], v[74:75], off offset:3072
	global_load_dwordx4 v[182:185], v[76:77], off offset:3072
	v_add_u32_e32 v0, 0xfffff000, v64
	v_ashrrev_i32_e32 v0, 10, v0
	v_add_u32_e32 v0, 1, v0
	v_cmp_lt_i32_e32 vcc, s33, v64
	global_load_dwordx4 v[186:189], v[86:87], off offset:1024
	global_load_dwordx4 v[186:189], v[86:87], off offset:2048
	global_load_dwordx4 v[186:189], v[86:87], off offset:3072
	flat_load_dwordx4 v[8:11], v[86:87]
	s_mov_b64 s[8:9], 0x1000000
	v_cndmask_b32_e32 v94, 0, v0, vcc
	v_add_u32_e32 v0, s38, v64
	v_cmp_lt_i32_e32 vcc, s6, v0
	v_ashrrev_i32_e32 v95, 31, v94
	v_lshl_add_u64 v[4:5], v[94:95], 0, s[28:29]
	v_cndmask_b32_e32 v0, v0, v64, vcc
	v_add_u32_e32 v1, 0xfffff000, v0
	v_ashrrev_i32_e32 v1, 10, v1
	v_add_u32_e32 v1, 1, v1
	v_cmp_lt_i32_e32 vcc, s33, v0
	v_mad_u64_u32 v[2:3], s[4:5], v4, s7, v[78:79]
	s_nop 0
	v_cndmask_b32_e32 v92, 0, v1, vcc
	v_add_u32_e32 v1, s35, v64
	v_cmp_lt_i32_e32 vcc, s6, v1
	s_mov_b32 s4, 0x1000000
	v_mad_i32_i24 v3, v5, s7, v3
	v_cndmask_b32_e32 v18, v1, v64, vcc
	v_add_u32_e32 v1, 0xfffff000, v18
	v_ashrrev_i32_e32 v1, 10, v1
	v_add_u32_e32 v1, 1, v1
	v_cmp_lt_i32_e32 vcc, s33, v18
	global_load_dwordx4 v[186:189], v[2:3], off offset:1024
	global_load_dwordx4 v[186:189], v[2:3], off offset:2048
	global_load_dwordx4 v[186:189], v[2:3], off offset:3072
	flat_load_dwordx4 v[12:15], v[2:3]
	v_ashrrev_i32_e32 v93, 31, v92
	v_cndmask_b32_e32 v90, 0, v1, vcc
	v_add_u32_e32 v1, s26, v64
	v_cmp_lt_i32_e32 vcc, s6, v1
	v_lshlrev_b32_e32 v152, 1, v66
	v_lshlrev_b32_e32 v42, 1, v68
	v_cndmask_b32_e32 v16, v1, v64, vcc
	v_add_u32_e32 v1, 0xfffff000, v16
	v_ashrrev_i32_e32 v1, 10, v1
	v_add_u32_e32 v1, 1, v1
	v_cmp_lt_i32_e32 vcc, s33, v16
	v_mov_b32_e32 v43, v153
	v_lshlrev_b32_e32 v104, 1, v70
	v_cndmask_b32_e32 v88, 0, v1, vcc
	v_add_co_u32_e32 v4, vcc, s4, v84
	s_brev_b32 s4, 64
	s_nop 0
	v_addc_co_u32_e32 v5, vcc, 0, v85, vcc
	global_load_dwordx2 v[186:187], v[4:5], off offset:512
	global_load_dwordx2 v[186:187], v[4:5], off offset:1024
	global_load_dwordx2 v[186:187], v[4:5], off offset:1536
	flat_load_dwordx2 v[6:7], v[4:5]
	v_mov_b32_e32 v105, v153
	v_lshlrev_b32_e32 v106, 1, v72
	v_mov_b32_e32 v107, v153
	v_ashrrev_i32_e32 v19, 31, v18
	v_ashrrev_i32_e32 v91, 31, v90
	v_lshlrev_b64 v[100:101], 11, v[18:19]
	v_ashrrev_i32_e32 v17, 31, v16
	v_ashrrev_i32_e32 v89, 31, v88
	s_waitcnt vmcnt(0) lgkmcnt(0)
	v_pk_mul_f32 v[14:15], v[14:15], 0.5 op_sel_hi:[1,0]
	v_pk_mul_f32 v[12:13], v[12:13], 0.5 op_sel_hi:[1,0]
	v_lshlrev_b32_e32 v20, 16, v6
	v_and_b32_e32 v21, 0xffff0000, v6
	v_add_co_u32_e32 v6, vcc, s4, v84
	v_lshlrev_b32_e32 v22, 16, v7
	v_and_b32_e32 v23, 0xffff0000, v7
	v_addc_co_u32_e32 v7, vcc, 0, v85, vcc
	flat_load_dwordx2 v[24:25], v[6:7]
	s_waitcnt vmcnt(0) lgkmcnt(0)
	v_lshlrev_b32_e32 v26, 16, v24
	v_and_b32_e32 v27, 0xffff0000, v24
	v_lshlrev_b32_e32 v24, 16, v25
	v_and_b32_e32 v25, 0xffff0000, v25
	v_pk_add_f32 v[20:21], v[20:21], v[26:27]
	v_pk_add_f32 v[22:23], v[22:23], v[24:25]
	v_pk_mul_f32 v[12:13], v[12:13], v[20:21]
	v_pk_mul_f32 v[14:15], v[14:15], v[22:23]
	v_pk_fma_f32 v[8:9], v[8:9], s[42:43], v[12:13] op_sel_hi:[1,0,1]
	v_pk_fma_f32 v[10:11], v[10:11], s[42:43], v[14:15] op_sel_hi:[1,0,1]
	v_mov_b32_e32 v14, v8
	v_pk_mov_b32 v[12:13], v[8:9], v[10:11] op_sel:[1,0]
	v_mov_b32_e32 v15, v11
	v_pk_add_f32 v[12:13], v[12:13], v[14:15]
	s_nop 0
	v_add_f32_e32 v1, v12, v13
	flat_load_dwordx4 v[12:15], v[86:87] offset:1024
	flat_load_dwordx4 v[20:23], v[2:3] offset:1024
	flat_load_dwordx2 v[24:25], v[4:5] offset:512
	flat_load_dwordx2 v[30:31], v[6:7] offset:512
	v_add_f32_e32 v28, 0, v1
	v_ashrrev_i32_e32 v1, 31, v0
	v_lshlrev_b64 v[96:97], 11, v[0:1]
	s_waitcnt vmcnt(0) lgkmcnt(0)
	v_pk_mul_f32 v[22:23], v[22:23], 0.5 op_sel_hi:[1,0]
	v_lshlrev_b32_e32 v26, 16, v24
	v_and_b32_e32 v27, 0xffff0000, v24
	v_lshlrev_b32_e32 v24, 16, v25
	v_and_b32_e32 v25, 0xffff0000, v25
	v_lshlrev_b32_e32 v32, 16, v30
	v_and_b32_e32 v33, 0xffff0000, v30
	v_lshlrev_b32_e32 v30, 16, v31
	v_and_b32_e32 v31, 0xffff0000, v31
	v_pk_mul_f32 v[20:21], v[20:21], 0.5 op_sel_hi:[1,0]
	v_pk_add_f32 v[26:27], v[26:27], v[32:33]
	v_pk_add_f32 v[24:25], v[24:25], v[30:31]
	v_pk_mul_f32 v[20:21], v[20:21], v[26:27]
	v_pk_mul_f32 v[22:23], v[22:23], v[24:25]
	v_pk_fma_f32 v[12:13], v[12:13], s[42:43], v[20:21] op_sel_hi:[1,0,1]
	v_pk_fma_f32 v[14:15], v[14:15], s[42:43], v[22:23] op_sel_hi:[1,0,1]
	v_mov_b32_e32 v22, v12
	v_pk_mov_b32 v[20:21], v[12:13], v[14:15] op_sel:[1,0]
	v_mov_b32_e32 v23, v15
	v_pk_add_f32 v[20:21], v[20:21], v[22:23]
	s_nop 0
	v_pk_add_f32 v[30:31], v[20:21], v[20:21] op_sel:[0,1] op_sel_hi:[1,0]
	flat_load_dwordx4 v[20:23], v[86:87] offset:2048
	flat_load_dwordx4 v[24:27], v[2:3] offset:2048
	flat_load_dwordx2 v[32:33], v[4:5] offset:1024
	flat_load_dwordx2 v[36:37], v[6:7] offset:1024
	s_waitcnt vmcnt(0) lgkmcnt(0)
	v_pk_mul_f32 v[26:27], v[26:27], 0.5 op_sel_hi:[1,0]
	v_lshlrev_b32_e32 v34, 16, v32
	v_and_b32_e32 v35, 0xffff0000, v32
	v_lshlrev_b32_e32 v32, 16, v33
	v_and_b32_e32 v33, 0xffff0000, v33
	v_lshlrev_b32_e32 v38, 16, v36
	v_and_b32_e32 v39, 0xffff0000, v36
	v_lshlrev_b32_e32 v36, 16, v37
	v_and_b32_e32 v37, 0xffff0000, v37
	v_pk_mul_f32 v[24:25], v[24:25], 0.5 op_sel_hi:[1,0]
	v_pk_add_f32 v[32:33], v[32:33], v[36:37]
	v_pk_add_f32 v[34:35], v[34:35], v[38:39]
	v_pk_mul_f32 v[26:27], v[26:27], v[32:33]
	v_pk_mul_f32 v[24:25], v[24:25], v[34:35]
	v_pk_fma_f32 v[22:23], v[22:23], s[42:43], v[26:27] op_sel_hi:[1,0,1]
	v_pk_fma_f32 v[20:21], v[20:21], s[42:43], v[24:25] op_sel_hi:[1,0,1]
	flat_load_dwordx4 v[24:27], v[86:87] offset:3072
	flat_load_dwordx4 v[32:35], v[2:3] offset:3072
	s_nop 0
	flat_load_dwordx2 v[2:3], v[4:5] offset:1536
	v_add_f32_e32 v36, v20, v21
	flat_load_dwordx2 v[6:7], v[6:7] offset:1536
	v_add_f32_e32 v38, v22, v23
	s_waitcnt vmcnt(0) lgkmcnt(0)
	v_pk_mul_f32 v[34:35], v[34:35], 0.5 op_sel_hi:[1,0]
	v_lshlrev_b32_e32 v4, 16, v2
	v_and_b32_e32 v5, 0xffff0000, v2
	v_lshlrev_b32_e32 v2, 16, v3
	v_and_b32_e32 v3, 0xffff0000, v3
	v_lshlrev_b32_e32 v40, 16, v6
	v_and_b32_e32 v41, 0xffff0000, v6
	v_lshlrev_b32_e32 v6, 16, v7
	v_and_b32_e32 v7, 0xffff0000, v7
	v_pk_mul_f32 v[32:33], v[32:33], 0.5 op_sel_hi:[1,0]
	v_pk_add_f32 v[2:3], v[2:3], v[6:7]
	v_pk_add_f32 v[4:5], v[4:5], v[40:41]
	v_pk_mul_f32 v[2:3], v[34:35], v[2:3]
	v_pk_mul_f32 v[4:5], v[32:33], v[4:5]
	v_pk_fma_f32 v[26:27], v[26:27], s[42:43], v[2:3] op_sel_hi:[1,0,1]
	v_pk_fma_f32 v[24:25], v[24:25], s[42:43], v[4:5] op_sel_hi:[1,0,1]
	v_mov_b32_e32 v37, v26
	v_mov_b32_e32 v29, v24
	v_mov_b32_e32 v31, v25
	v_mov_b32_e32 v39, v27
	v_lshl_add_u64 v[34:35], s[56:57], 0, v[96:97]
	v_pk_add_f32 v[2:3], v[28:29], v[30:31]
	v_pk_add_f32 v[4:5], v[36:37], v[38:39]
	v_lshl_add_u64 v[6:7], v[92:93], 0, s[28:29]
	v_lshl_add_u64 v[46:47], v[34:35], 0, s[8:9]
	v_pk_add_f32 v[2:3], v[2:3], v[4:5]
	v_mad_u64_u32 v[4:5], s[4:5], v6, s7, v[78:79]
	v_lshl_add_u64 v[48:49], v[34:35], 0, v[152:153]
	v_lshl_add_u64 v[36:37], v[46:47], 0, v[152:153]
	v_mad_i32_i24 v5, v7, s7, v5
	global_load_dwordx2 v[186:187], v[48:49], off offset:512
	global_load_dwordx2 v[186:187], v[48:49], off offset:1024
	global_load_dwordx2 v[186:187], v[48:49], off offset:1536
	flat_load_dwordx2 v[6:7], v[48:49]
	v_add_f32_e32 v120, v2, v3
	global_load_dwordx2 v[186:187], v[36:37], off offset:512
	global_load_dwordx2 v[186:187], v[36:37], off offset:1024
	global_load_dwordx2 v[186:187], v[36:37], off offset:1536
	flat_load_dwordx2 v[36:37], v[36:37]
	v_lshlrev_b64 v[2:3], 12, v[0:1]
	global_load_dwordx4 v[186:189], v[4:5], off offset:1024
	global_load_dwordx4 v[186:189], v[4:5], off offset:2048
	global_load_dwordx4 v[186:189], v[4:5], off offset:3072
	flat_load_dwordx4 v[28:31], v[4:5]
	v_lshl_add_u64 v[32:33], v[80:81], 0, v[2:3]
	global_load_dwordx4 v[186:189], v[32:33], off offset:1024
	global_load_dwordx4 v[186:189], v[32:33], off offset:2048
	global_load_dwordx4 v[186:189], v[32:33], off offset:3072
	flat_load_dwordx4 v[0:3], v[32:33]
	v_lshl_add_u64 v[44:45], v[46:47], 0, v[42:43]
	v_lshl_add_u64 v[52:53], v[46:47], 0, v[104:105]
	v_lshl_add_u64 v[46:47], v[46:47], 0, v[106:107]
	s_waitcnt vmcnt(0) lgkmcnt(0)
	v_lshlrev_b32_e32 v34, 16, v6
	v_and_b32_e32 v35, 0xffff0000, v6
	v_lshlrev_b32_e32 v6, 16, v7
	v_and_b32_e32 v7, 0xffff0000, v7
	v_lshlrev_b32_e32 v38, 16, v36
	v_and_b32_e32 v39, 0xffff0000, v36
	v_lshlrev_b32_e32 v36, 16, v37
	v_and_b32_e32 v37, 0xffff0000, v37
	v_pk_mul_f32 v[30:31], v[30:31], 0.5 op_sel_hi:[1,0]
	v_pk_mul_f32 v[28:29], v[28:29], 0.5 op_sel_hi:[1,0]
	v_pk_add_f32 v[34:35], v[34:35], v[38:39]
	v_pk_add_f32 v[6:7], v[6:7], v[36:37]
	v_pk_mul_f32 v[28:29], v[28:29], v[34:35]
	v_pk_mul_f32 v[6:7], v[30:31], v[6:7]
	v_pk_fma_f32 v[34:35], v[0:1], s[42:43], v[28:29] op_sel_hi:[1,0,1]
	v_pk_fma_f32 v[36:37], v[2:3], s[42:43], v[6:7] op_sel_hi:[1,0,1]
	v_mov_b32_e32 v2, v34
	v_pk_mov_b32 v[0:1], v[34:35], v[36:37] op_sel:[1,0]
	v_mov_b32_e32 v3, v37
	v_pk_add_f32 v[0:1], v[0:1], v[2:3]
	s_nop 0
	v_add_f32_e32 v0, v0, v1
	v_add_f32_e32 v40, 0, v0
	flat_load_dwordx4 v[0:3], v[32:33] offset:1024
	flat_load_dwordx4 v[28:31], v[4:5] offset:1024
	flat_load_dwordx2 v[6:7], v[48:49] offset:512
	s_waitcnt vmcnt(0) lgkmcnt(0)
	v_pk_mul_f32 v[30:31], v[30:31], 0.5 op_sel_hi:[1,0]
	flat_load_dwordx2 v[44:45], v[44:45]
	v_lshlrev_b32_e32 v38, 16, v6
	v_and_b32_e32 v39, 0xffff0000, v6
	v_lshlrev_b32_e32 v6, 16, v7
	v_and_b32_e32 v7, 0xffff0000, v7
	v_pk_mul_f32 v[28:29], v[28:29], 0.5 op_sel_hi:[1,0]
	s_waitcnt vmcnt(0) lgkmcnt(0)
	v_lshlrev_b32_e32 v50, 16, v44
	v_and_b32_e32 v51, 0xffff0000, v44
	v_lshlrev_b32_e32 v44, 16, v45
	v_and_b32_e32 v45, 0xffff0000, v45
	v_pk_add_f32 v[38:39], v[38:39], v[50:51]
	v_pk_add_f32 v[6:7], v[6:7], v[44:45]
	v_pk_mul_f32 v[28:29], v[28:29], v[38:39]
	v_pk_mul_f32 v[6:7], v[30:31], v[6:7]
	v_pk_fma_f32 v[38:39], v[0:1], s[42:43], v[28:29] op_sel_hi:[1,0,1]
	v_pk_fma_f32 v[60:61], v[2:3], s[42:43], v[6:7] op_sel_hi:[1,0,1]
	v_mov_b32_e32 v2, v38
	v_pk_mov_b32 v[0:1], v[38:39], v[60:61] op_sel:[1,0]
	v_mov_b32_e32 v3, v61
	v_pk_add_f32 v[0:1], v[0:1], v[2:3]
	s_nop 0
	v_pk_add_f32 v[44:45], v[0:1], v[0:1] op_sel:[0,1] op_sel_hi:[1,0]
	flat_load_dwordx4 v[0:3], v[32:33] offset:2048
	flat_load_dwordx4 v[28:31], v[4:5] offset:2048
	flat_load_dwordx2 v[6:7], v[48:49] offset:1024
	s_waitcnt vmcnt(0) lgkmcnt(0)
	v_pk_mul_f32 v[30:31], v[30:31], 0.5 op_sel_hi:[1,0]
	flat_load_dwordx2 v[52:53], v[52:53]
	v_lshlrev_b32_e32 v50, 16, v6
	v_and_b32_e32 v51, 0xffff0000, v6
	v_lshlrev_b32_e32 v6, 16, v7
	v_and_b32_e32 v7, 0xffff0000, v7
	v_pk_mul_f32 v[28:29], v[28:29], 0.5 op_sel_hi:[1,0]
	s_waitcnt vmcnt(0) lgkmcnt(0)
	v_lshlrev_b32_e32 v54, 16, v52
	v_and_b32_e32 v55, 0xffff0000, v52
	v_lshlrev_b32_e32 v52, 16, v53
	v_and_b32_e32 v53, 0xffff0000, v53
	v_pk_add_f32 v[6:7], v[6:7], v[52:53]
	v_pk_add_f32 v[50:51], v[50:51], v[54:55]
	v_pk_mul_f32 v[6:7], v[30:31], v[6:7]
	v_pk_mul_f32 v[28:29], v[28:29], v[50:51]
	v_pk_fma_f32 v[30:31], v[2:3], s[42:43], v[6:7] op_sel_hi:[1,0,1]
	v_pk_fma_f32 v[28:29], v[0:1], s[42:43], v[28:29] op_sel_hi:[1,0,1]
	flat_load_dwordx4 v[0:3], v[32:33] offset:3072
	s_nop 0
	flat_load_dwordx4 v[4:7], v[4:5] offset:3072
	s_nop 0
	flat_load_dwordx2 v[54:55], v[48:49] offset:1536
	v_add_f32_e32 v50, v28, v29
	flat_load_dwordx2 v[46:47], v[46:47]
	v_add_f32_e32 v52, v30, v31
	s_waitcnt vmcnt(0) lgkmcnt(0)
	v_pk_mul_f32 v[6:7], v[6:7], 0.5 op_sel_hi:[1,0]
	v_lshlrev_b32_e32 v48, 16, v54
	v_and_b32_e32 v49, 0xffff0000, v54
	v_lshlrev_b32_e32 v54, 16, v55
	v_and_b32_e32 v55, 0xffff0000, v55
	v_lshlrev_b32_e32 v56, 16, v46
	v_and_b32_e32 v57, 0xffff0000, v46
	v_lshlrev_b32_e32 v46, 16, v47
	v_and_b32_e32 v47, 0xffff0000, v47
	v_pk_mul_f32 v[4:5], v[4:5], 0.5 op_sel_hi:[1,0]
	v_pk_add_f32 v[46:47], v[54:55], v[46:47]
	v_pk_add_f32 v[48:49], v[48:49], v[56:57]
	v_pk_mul_f32 v[6:7], v[6:7], v[46:47]
	v_pk_mul_f32 v[4:5], v[4:5], v[48:49]
	v_pk_fma_f32 v[118:119], v[2:3], s[42:43], v[6:7] op_sel_hi:[1,0,1]
	v_pk_fma_f32 v[62:63], v[0:1], s[42:43], v[4:5] op_sel_hi:[1,0,1]
	v_mov_b32_e32 v51, v118
	v_mov_b32_e32 v41, v62
	v_mov_b32_e32 v45, v63
	v_mov_b32_e32 v53, v119
	v_pk_add_f32 v[0:1], v[40:41], v[44:45]
	v_pk_add_f32 v[2:3], v[50:51], v[52:53]
	v_lshl_add_u64 v[4:5], v[90:91], 0, s[28:29]
	v_pk_add_f32 v[0:1], v[0:1], v[2:3]
	v_mad_u64_u32 v[48:49], s[4:5], v4, s7, v[78:79]
	v_add_f32_e32 v121, v0, v1
	v_lshlrev_b64 v[0:1], 12, v[18:19]
	v_lshl_add_u64 v[18:19], s[56:57], 0, v[100:101]
	v_lshl_add_u64 v[46:47], v[18:19], 0, s[8:9]
	v_mad_i32_i24 v49, v5, s7, v49
	v_lshl_add_u64 v[18:19], v[18:19], 0, v[152:153]
	v_lshl_add_u64 v[52:53], v[46:47], 0, v[152:153]
	global_load_dwordx4 v[186:189], v[48:49], off offset:1024
	global_load_dwordx4 v[186:189], v[48:49], off offset:2048
	global_load_dwordx4 v[186:189], v[48:49], off offset:3072
	flat_load_dwordx4 v[4:7], v[48:49]
	global_load_dwordx2 v[186:187], v[18:19], off offset:512
	global_load_dwordx2 v[186:187], v[18:19], off offset:1024
	global_load_dwordx2 v[186:187], v[18:19], off offset:1536
	flat_load_dwordx2 v[44:45], v[18:19]
	v_lshl_add_u64 v[40:41], v[80:81], 0, v[0:1]
	global_load_dwordx2 v[186:187], v[52:53], off offset:512
	global_load_dwordx2 v[186:187], v[52:53], off offset:1024
	global_load_dwordx2 v[186:187], v[52:53], off offset:1536
	flat_load_dwordx2 v[52:53], v[52:53]
	v_lshl_add_u64 v[56:57], v[46:47], 0, v[42:43]
	global_load_dwordx4 v[186:189], v[40:41], off offset:1024
	global_load_dwordx4 v[186:189], v[40:41], off offset:2048
	global_load_dwordx4 v[186:189], v[40:41], off offset:3072
	flat_load_dwordx4 v[0:3], v[40:41]
	v_lshl_add_u64 v[108:109], v[46:47], 0, v[104:105]
	v_lshl_add_u64 v[46:47], v[46:47], 0, v[106:107]
	s_waitcnt vmcnt(0) lgkmcnt(0)
	v_pk_mul_f32 v[6:7], v[6:7], 0.5 op_sel_hi:[1,0]
	v_lshlrev_b32_e32 v50, 16, v44
	v_and_b32_e32 v51, 0xffff0000, v44
	v_lshlrev_b32_e32 v44, 16, v45
	v_and_b32_e32 v45, 0xffff0000, v45
	v_lshlrev_b32_e32 v54, 16, v52
	v_and_b32_e32 v55, 0xffff0000, v52
	v_lshlrev_b32_e32 v52, 16, v53
	v_and_b32_e32 v53, 0xffff0000, v53
	v_pk_mul_f32 v[4:5], v[4:5], 0.5 op_sel_hi:[1,0]
	v_pk_add_f32 v[50:51], v[50:51], v[54:55]
	v_pk_add_f32 v[44:45], v[44:45], v[52:53]
	v_pk_mul_f32 v[4:5], v[4:5], v[50:51]
	v_pk_mul_f32 v[6:7], v[6:7], v[44:45]
	v_pk_fma_f32 v[44:45], v[0:1], s[42:43], v[4:5] op_sel_hi:[1,0,1]
	v_pk_fma_f32 v[50:51], v[2:3], s[42:43], v[6:7] op_sel_hi:[1,0,1]
	v_mov_b32_e32 v2, v44
	v_pk_mov_b32 v[0:1], v[44:45], v[50:51] op_sel:[1,0]
	v_mov_b32_e32 v3, v51
	v_pk_add_f32 v[0:1], v[0:1], v[2:3]
	s_nop 0
	v_add_f32_e32 v0, v0, v1
	v_add_f32_e32 v98, 0, v0
	flat_load_dwordx4 v[0:3], v[40:41] offset:1024
	flat_load_dwordx4 v[4:7], v[48:49] offset:1024
	flat_load_dwordx2 v[52:53], v[18:19] offset:512
	s_waitcnt vmcnt(0) lgkmcnt(0)
	v_pk_mul_f32 v[6:7], v[6:7], 0.5 op_sel_hi:[1,0]
	flat_load_dwordx2 v[56:57], v[56:57]
	v_lshlrev_b32_e32 v54, 16, v52
	v_and_b32_e32 v55, 0xffff0000, v52
	v_lshlrev_b32_e32 v52, 16, v53
	v_and_b32_e32 v53, 0xffff0000, v53
	v_pk_mul_f32 v[4:5], v[4:5], 0.5 op_sel_hi:[1,0]
	s_waitcnt vmcnt(0) lgkmcnt(0)
	v_lshlrev_b32_e32 v58, 16, v56
	v_and_b32_e32 v59, 0xffff0000, v56
	v_lshlrev_b32_e32 v56, 16, v57
	v_and_b32_e32 v57, 0xffff0000, v57
	v_pk_add_f32 v[54:55], v[54:55], v[58:59]
	v_pk_add_f32 v[52:53], v[52:53], v[56:57]
	v_pk_mul_f32 v[4:5], v[4:5], v[54:55]
	v_pk_mul_f32 v[6:7], v[6:7], v[52:53]
	v_pk_fma_f32 v[56:57], v[0:1], s[42:43], v[4:5] op_sel_hi:[1,0,1]
	v_pk_fma_f32 v[58:59], v[2:3], s[42:43], v[6:7] op_sel_hi:[1,0,1]
	v_mov_b32_e32 v2, v56
	v_pk_mov_b32 v[0:1], v[56:57], v[58:59] op_sel:[1,0]
	v_mov_b32_e32 v3, v59
	v_pk_add_f32 v[0:1], v[0:1], v[2:3]
	s_nop 0
	v_pk_add_f32 v[102:103], v[0:1], v[0:1] op_sel:[0,1] op_sel_hi:[1,0]
	flat_load_dwordx4 v[0:3], v[40:41] offset:2048
	flat_load_dwordx4 v[4:7], v[48:49] offset:2048
	flat_load_dwordx2 v[52:53], v[18:19] offset:1024
	s_waitcnt vmcnt(0) lgkmcnt(0)
	v_pk_mul_f32 v[6:7], v[6:7], 0.5 op_sel_hi:[1,0]
	flat_load_dwordx2 v[108:109], v[108:109]
	v_lshlrev_b32_e32 v54, 16, v52
	v_and_b32_e32 v55, 0xffff0000, v52
	v_lshlrev_b32_e32 v52, 16, v53
	v_and_b32_e32 v53, 0xffff0000, v53
	v_pk_mul_f32 v[4:5], v[4:5], 0.5 op_sel_hi:[1,0]
	s_waitcnt vmcnt(0) lgkmcnt(0)
	v_lshlrev_b32_e32 v110, 16, v108
	v_and_b32_e32 v111, 0xffff0000, v108
	v_lshlrev_b32_e32 v108, 16, v109
	v_and_b32_e32 v109, 0xffff0000, v109
	v_pk_add_f32 v[52:53], v[52:53], v[108:109]
	v_pk_add_f32 v[54:55], v[54:55], v[110:111]
	v_pk_mul_f32 v[6:7], v[6:7], v[52:53]
	v_pk_mul_f32 v[4:5], v[4:5], v[54:55]
	v_pk_fma_f32 v[54:55], v[2:3], s[42:43], v[6:7] op_sel_hi:[1,0,1]
	v_pk_fma_f32 v[52:53], v[0:1], s[42:43], v[4:5] op_sel_hi:[1,0,1]
	flat_load_dwordx4 v[0:3], v[40:41] offset:3072
	flat_load_dwordx4 v[4:7], v[48:49] offset:3072
	s_nop 0
	flat_load_dwordx2 v[18:19], v[18:19] offset:1536
	v_add_f32_e32 v108, v52, v53
	flat_load_dwordx2 v[46:47], v[46:47]
	v_add_f32_e32 v110, v54, v55
	s_waitcnt vmcnt(0) lgkmcnt(0)
	v_pk_mul_f32 v[6:7], v[6:7], 0.5 op_sel_hi:[1,0]
	v_lshlrev_b32_e32 v48, 16, v18
	v_and_b32_e32 v49, 0xffff0000, v18
	v_lshlrev_b32_e32 v18, 16, v19
	v_and_b32_e32 v19, 0xffff0000, v19
	v_lshlrev_b32_e32 v112, 16, v46
	v_and_b32_e32 v113, 0xffff0000, v46
	v_lshlrev_b32_e32 v46, 16, v47
	v_and_b32_e32 v47, 0xffff0000, v47
	v_pk_mul_f32 v[4:5], v[4:5], 0.5 op_sel_hi:[1,0]
	v_pk_add_f32 v[18:19], v[18:19], v[46:47]
	v_pk_add_f32 v[46:47], v[48:49], v[112:113]
	v_pk_mul_f32 v[6:7], v[6:7], v[18:19]
	v_pk_mul_f32 v[4:5], v[4:5], v[46:47]
	v_pk_fma_f32 v[48:49], v[2:3], s[42:43], v[6:7] op_sel_hi:[1,0,1]
	v_pk_fma_f32 v[46:47], v[0:1], s[42:43], v[4:5] op_sel_hi:[1,0,1]
	v_mov_b32_e32 v109, v48
	v_mov_b32_e32 v99, v46
	v_mov_b32_e32 v103, v47
	v_mov_b32_e32 v111, v49
	v_pk_add_f32 v[0:1], v[98:99], v[102:103]
	v_pk_add_f32 v[2:3], v[108:109], v[110:111]
	v_lshlrev_b64 v[98:99], 11, v[16:17]
	v_pk_add_f32 v[0:1], v[0:1], v[2:3]
	v_lshl_add_u64 v[4:5], v[88:89], 0, s[28:29]
	v_add_f32_e32 v125, v0, v1
	v_lshlrev_b64 v[0:1], 12, v[16:17]
	v_lshl_add_u64 v[16:17], s[56:57], 0, v[98:99]
	v_lshl_add_u64 v[18:19], v[16:17], 0, s[8:9]
	v_mad_u64_u32 v[126:127], s[4:5], v4, s7, v[78:79]
	v_mad_i32_i24 v127, v5, s7, v127
	v_lshl_add_u64 v[16:17], v[16:17], 0, v[152:153]
	v_lshl_add_u64 v[112:113], v[18:19], 0, v[152:153]
	global_load_dwordx4 v[186:189], v[126:127], off offset:1024
	global_load_dwordx4 v[186:189], v[126:127], off offset:2048
	global_load_dwordx4 v[186:189], v[126:127], off offset:3072
	flat_load_dwordx4 v[4:7], v[126:127]
	global_load_dwordx2 v[186:187], v[16:17], off offset:512
	global_load_dwordx2 v[186:187], v[16:17], off offset:1024
	global_load_dwordx2 v[186:187], v[16:17], off offset:1536
	flat_load_dwordx2 v[108:109], v[16:17]
	v_lshl_add_u64 v[102:103], v[80:81], 0, v[0:1]
	global_load_dwordx2 v[186:187], v[112:113], off offset:512
	global_load_dwordx2 v[186:187], v[112:113], off offset:1024
	global_load_dwordx2 v[186:187], v[112:113], off offset:1536
	flat_load_dwordx2 v[112:113], v[112:113]
	v_lshl_add_u64 v[42:43], v[18:19], 0, v[42:43]
	global_load_dwordx4 v[186:189], v[102:103], off offset:1024
	global_load_dwordx4 v[186:189], v[102:103], off offset:2048
	global_load_dwordx4 v[186:189], v[102:103], off offset:3072
	flat_load_dwordx4 v[0:3], v[102:103]
	v_lshl_add_u64 v[104:105], v[18:19], 0, v[104:105]
	v_lshl_add_u64 v[18:19], v[18:19], 0, v[106:107]
	s_mov_b32 s4, 0x3727c5ac
	s_waitcnt vmcnt(0) lgkmcnt(0)
	v_pk_mul_f32 v[6:7], v[6:7], 0.5 op_sel_hi:[1,0]
	v_lshlrev_b32_e32 v110, 16, v108
	v_and_b32_e32 v111, 0xffff0000, v108
	v_lshlrev_b32_e32 v108, 16, v109
	v_and_b32_e32 v109, 0xffff0000, v109
	v_lshlrev_b32_e32 v114, 16, v112
	v_and_b32_e32 v115, 0xffff0000, v112
	v_lshlrev_b32_e32 v112, 16, v113
	v_and_b32_e32 v113, 0xffff0000, v113
	v_pk_mul_f32 v[4:5], v[4:5], 0.5 op_sel_hi:[1,0]
	v_pk_add_f32 v[110:111], v[110:111], v[114:115]
	v_pk_add_f32 v[108:109], v[108:109], v[112:113]
	v_pk_mul_f32 v[4:5], v[4:5], v[110:111]
	v_pk_mul_f32 v[6:7], v[6:7], v[108:109]
	v_pk_fma_f32 v[114:115], v[0:1], s[42:43], v[4:5] op_sel_hi:[1,0,1]
	v_pk_fma_f32 v[116:117], v[2:3], s[42:43], v[6:7] op_sel_hi:[1,0,1]
	v_mov_b32_e32 v2, v114
	v_pk_mov_b32 v[0:1], v[114:115], v[116:117] op_sel:[1,0]
	v_mov_b32_e32 v3, v117
	v_pk_add_f32 v[0:1], v[0:1], v[2:3]
	s_nop 0
	v_add_f32_e32 v0, v0, v1
	v_add_f32_e32 v128, 0, v0
	flat_load_dwordx4 v[0:3], v[102:103] offset:1024
	flat_load_dwordx4 v[4:7], v[126:127] offset:1024
	flat_load_dwordx2 v[108:109], v[16:17] offset:512
	s_waitcnt vmcnt(0) lgkmcnt(0)
	v_pk_mul_f32 v[6:7], v[6:7], 0.5 op_sel_hi:[1,0]
	flat_load_dwordx2 v[42:43], v[42:43]
	v_lshlrev_b32_e32 v110, 16, v108
	v_and_b32_e32 v111, 0xffff0000, v108
	v_lshlrev_b32_e32 v108, 16, v109
	v_and_b32_e32 v109, 0xffff0000, v109
	v_pk_mul_f32 v[4:5], v[4:5], 0.5 op_sel_hi:[1,0]
	s_waitcnt vmcnt(0) lgkmcnt(0)
	v_lshlrev_b32_e32 v112, 16, v42
	v_and_b32_e32 v113, 0xffff0000, v42
	v_lshlrev_b32_e32 v42, 16, v43
	v_and_b32_e32 v43, 0xffff0000, v43
	v_pk_add_f32 v[110:111], v[110:111], v[112:113]
	v_pk_add_f32 v[42:43], v[108:109], v[42:43]
	v_pk_mul_f32 v[4:5], v[4:5], v[110:111]
	v_pk_mul_f32 v[6:7], v[6:7], v[42:43]
	v_pk_fma_f32 v[42:43], v[0:1], s[42:43], v[4:5] op_sel_hi:[1,0,1]
	v_pk_fma_f32 v[112:113], v[2:3], s[42:43], v[6:7] op_sel_hi:[1,0,1]
	v_mov_b32_e32 v2, v42
	v_pk_mov_b32 v[0:1], v[42:43], v[112:113] op_sel:[1,0]
	v_mov_b32_e32 v3, v113
	v_pk_add_f32 v[0:1], v[0:1], v[2:3]
	s_nop 0
	v_pk_add_f32 v[130:131], v[0:1], v[0:1] op_sel:[0,1] op_sel_hi:[1,0]
	flat_load_dwordx4 v[0:3], v[102:103] offset:2048
	flat_load_dwordx4 v[4:7], v[126:127] offset:2048
	flat_load_dwordx2 v[108:109], v[16:17] offset:1024
	s_waitcnt vmcnt(0) lgkmcnt(0)
	v_pk_mul_f32 v[6:7], v[6:7], 0.5 op_sel_hi:[1,0]
	flat_load_dwordx2 v[104:105], v[104:105]
	v_lshlrev_b32_e32 v110, 16, v108
	v_and_b32_e32 v111, 0xffff0000, v108
	v_lshlrev_b32_e32 v108, 16, v109
	v_and_b32_e32 v109, 0xffff0000, v109
	v_pk_mul_f32 v[4:5], v[4:5], 0.5 op_sel_hi:[1,0]
	s_waitcnt vmcnt(0) lgkmcnt(0)
	v_lshlrev_b32_e32 v132, 16, v104
	v_and_b32_e32 v133, 0xffff0000, v104
	v_lshlrev_b32_e32 v104, 16, v105
	v_and_b32_e32 v105, 0xffff0000, v105
	v_pk_add_f32 v[104:105], v[108:109], v[104:105]
	v_pk_add_f32 v[108:109], v[110:111], v[132:133]
	v_pk_mul_f32 v[6:7], v[6:7], v[104:105]
	v_pk_mul_f32 v[4:5], v[4:5], v[108:109]
	v_pk_fma_f32 v[110:111], v[2:3], s[42:43], v[6:7] op_sel_hi:[1,0,1]
	v_pk_fma_f32 v[108:109], v[0:1], s[42:43], v[4:5] op_sel_hi:[1,0,1]
	flat_load_dwordx4 v[0:3], v[102:103] offset:3072
	flat_load_dwordx4 v[4:7], v[126:127] offset:3072
	s_nop 0
	flat_load_dwordx2 v[16:17], v[16:17] offset:1536
	v_add_f32_e32 v132, v108, v109
	flat_load_dwordx2 v[18:19], v[18:19]
	v_add_f32_e32 v134, v110, v111
	s_waitcnt vmcnt(0) lgkmcnt(0)
	v_pk_mul_f32 v[6:7], v[6:7], 0.5 op_sel_hi:[1,0]
	v_lshlrev_b32_e32 v104, 16, v16
	v_and_b32_e32 v105, 0xffff0000, v16
	v_lshlrev_b32_e32 v16, 16, v17
	v_and_b32_e32 v17, 0xffff0000, v17
	v_lshlrev_b32_e32 v106, 16, v18
	v_and_b32_e32 v107, 0xffff0000, v18
	v_lshlrev_b32_e32 v18, 16, v19
	v_and_b32_e32 v19, 0xffff0000, v19
	v_pk_mul_f32 v[4:5], v[4:5], 0.5 op_sel_hi:[1,0]
	v_pk_add_f32 v[16:17], v[16:17], v[18:19]
	v_pk_add_f32 v[18:19], v[104:105], v[106:107]
	v_pk_mul_f32 v[6:7], v[6:7], v[16:17]
	v_pk_mul_f32 v[4:5], v[4:5], v[18:19]
	v_pk_fma_f32 v[106:107], v[2:3], s[42:43], v[6:7] op_sel_hi:[1,0,1]
	v_pk_fma_f32 v[104:105], v[0:1], s[42:43], v[4:5] op_sel_hi:[1,0,1]
	v_mov_b32_e32 v133, v106
	v_mov_b32_e32 v129, v104
	v_mov_b32_e32 v131, v105
	v_mov_b32_e32 v135, v107
	v_pk_add_f32 v[0:1], v[128:129], v[130:131]
	v_pk_add_f32 v[2:3], v[132:133], v[134:135]
	ds_bpermute_b32 v18, v67, v121
	v_pk_add_f32 v[0:1], v[0:1], v[2:3]
	s_waitcnt lgkmcnt(0)
	v_add_f32_e32 v18, v121, v18
	v_add_f32_e32 v65, v0, v1
	ds_bpermute_b32 v0, v67, v120
	ds_bpermute_b32 v19, v69, v18
	s_waitcnt lgkmcnt(1)
	v_add_f32_e32 v0, v120, v0
	ds_bpermute_b32 v1, v69, v0
	s_waitcnt lgkmcnt(1)
	v_add_f32_e32 v18, v18, v19
	ds_bpermute_b32 v19, v71, v18
	s_waitcnt lgkmcnt(1)
	v_add_f32_e32 v0, v0, v1
	ds_bpermute_b32 v1, v71, v0
	s_waitcnt lgkmcnt(1)
	v_add_f32_e32 v18, v18, v19
	ds_bpermute_b32 v19, v73, v18
	s_waitcnt lgkmcnt(1)
	v_add_f32_e32 v0, v0, v1
	ds_bpermute_b32 v1, v73, v0
	s_waitcnt lgkmcnt(1)
	v_add_f32_e32 v18, v18, v19
	ds_bpermute_b32 v19, v123, v18
	s_waitcnt lgkmcnt(1)
	v_add_f32_e32 v0, v0, v1
	ds_bpermute_b32 v1, v123, v0
	s_waitcnt lgkmcnt(1)
	v_add_f32_e32 v18, v18, v19
	ds_bpermute_b32 v19, v124, v18
	s_waitcnt lgkmcnt(1)
	v_add_f32_e32 v0, v0, v1
	ds_bpermute_b32 v1, v124, v0
	s_waitcnt lgkmcnt(1)
	v_add_f32_e32 v122, v18, v19
	v_fmamk_f32 v35, v122, 0xba800000, v35
	v_fmac_f32_e32 v34, 0xba800000, v122
	v_fmamk_f32 v37, v122, 0xba800000, v37
	s_waitcnt lgkmcnt(0)
	v_add_f32_e32 v16, v0, v1
	v_fmamk_f32 v9, v16, 0xba800000, v9
	v_fmac_f32_e32 v8, 0xba800000, v16
	v_fmamk_f32 v11, v16, 0xba800000, v11
	v_fmac_f32_e32 v10, 0xba800000, v16
	v_pk_mul_f32 v[0:1], v[10:11], v[10:11]
	v_pk_mul_f32 v[2:3], v[8:9], v[8:9]
	v_fmamk_f32 v13, v16, 0xba800000, v13
	v_pk_mov_b32 v[4:5], v[2:3], v[0:1] op_sel:[1,0]
	v_mov_b32_e32 v3, v1
	v_pk_add_f32 v[0:1], v[4:5], v[2:3]
	v_fmac_f32_e32 v12, 0xba800000, v16
	v_fmamk_f32 v15, v16, 0xba800000, v15
	v_fmac_f32_e32 v14, 0xba800000, v16
	v_pk_add_f32 v[0:1], v[0:1], v[0:1] op_sel_hi:[0,1]
	v_pk_mul_f32 v[2:3], v[14:15], v[14:15]
	v_pk_mul_f32 v[4:5], v[12:13], v[12:13]
	v_fmac_f32_e32 v20, 0xba800000, v16
	v_pk_mov_b32 v[6:7], v[4:5], v[2:3] op_sel:[1,0]
	v_mov_b32_e32 v5, v3
	v_fmamk_f32 v21, v16, 0xba800000, v21
	v_fmac_f32_e32 v22, 0xba800000, v16
	v_mul_f32_e32 v0, v20, v20
	v_pk_add_f32 v[2:3], v[6:7], v[4:5]
	v_fmamk_f32 v23, v16, 0xba800000, v23
	v_pk_fma_f32 v[4:5], v[20:21], v[20:21], v[0:1] op_sel_hi:[1,1,0]
	v_mul_f32_e32 v0, v22, v22
	v_pk_add_f32 v[2:3], v[2:3], v[2:3] op_sel_hi:[0,1]
	v_pk_fma_f32 v[6:7], v[22:23], v[22:23], v[0:1] op_sel_hi:[1,1,0]
	v_fmamk_f32 v27, v16, 0xba800000, v27
	v_fmac_f32_e32 v26, 0xba800000, v16
	v_fmamk_f32 v25, v16, 0xba800000, v25
	v_fmac_f32_e32 v24, 0xba800000, v16
	v_mul_f32_e32 v4, v24, v24
	v_mul_f32_e32 v6, v25, v25
	v_mul_f32_e32 v0, v26, v26
	v_mul_f32_e32 v2, v27, v27
	v_pk_add_f32 v[4:5], v[4:5], v[6:7]
	v_pk_add_f32 v[0:1], v[0:1], v[2:3]
	v_fmac_f32_e32 v36, 0xba800000, v122
	v_pk_add_f32 v[16:17], v[4:5], v[0:1]
	v_mov_b64_e32 v[0:1], v[154:155]
	v_mov_b64_e32 v[2:3], v[156:157]
	v_mov_b64_e32 v[4:5], v[158:159]
	v_mov_b64_e32 v[6:7], v[160:161]
	v_pk_mul_f32 v[18:19], v[36:37], v[36:37]
	v_pk_mul_f32 v[120:121], v[34:35], v[34:35]
	v_fmamk_f32 v39, v122, 0xba800000, v39
	v_pk_mov_b32 v[126:127], v[120:121], v[18:19] op_sel:[1,0]
	v_mov_b32_e32 v121, v19
	v_pk_add_f32 v[18:19], v[126:127], v[120:121]
	v_fmac_f32_e32 v38, 0xba800000, v122
	v_fmamk_f32 v61, v122, 0xba800000, v61
	v_fmac_f32_e32 v60, 0xba800000, v122
	v_pk_add_f32 v[18:19], v[18:19], v[18:19] op_sel_hi:[0,1]
	v_pk_mul_f32 v[120:121], v[60:61], v[60:61]
	v_pk_mul_f32 v[126:127], v[38:39], v[38:39]
	v_fmac_f32_e32 v28, 0xba800000, v122
	v_pk_mov_b32 v[128:129], v[126:127], v[120:121] op_sel:[1,0]
	v_mov_b32_e32 v127, v121
	v_fmamk_f32 v29, v122, 0xba800000, v29
	v_fmac_f32_e32 v30, 0xba800000, v122
	v_mul_f32_e32 v18, v28, v28
	v_pk_add_f32 v[120:121], v[128:129], v[126:127]
	v_fmamk_f32 v31, v122, 0xba800000, v31
	v_pk_fma_f32 v[126:127], v[28:29], v[28:29], v[18:19] op_sel_hi:[1,1,0]
	v_mul_f32_e32 v18, v30, v30
	v_pk_add_f32 v[120:121], v[120:121], v[120:121] op_sel_hi:[0,1]
	v_pk_fma_f32 v[128:129], v[30:31], v[30:31], v[18:19] op_sel_hi:[1,1,0]
	v_fmamk_f32 v119, v122, 0xba800000, v119
	v_fmac_f32_e32 v118, 0xba800000, v122
	v_fmamk_f32 v63, v122, 0xba800000, v63
	v_fmac_f32_e32 v62, 0xba800000, v122
	v_mul_f32_e32 v126, v62, v62
	v_mul_f32_e32 v128, v63, v63
	v_mul_f32_e32 v18, v118, v118
	v_mul_f32_e32 v120, v119, v119
	v_pk_add_f32 v[126:127], v[126:127], v[128:129]
	v_pk_add_f32 v[18:19], v[18:19], v[120:121]
	v_mov_b32_e32 v121, v16
	v_pk_add_f32 v[18:19], v[126:127], v[18:19]
	s_nop 0
	v_mov_b32_e32 v120, v18
	v_mov_b32_e32 v16, v19
	v_pk_add_f32 v[16:17], v[120:121], v[16:17]
	ds_bpermute_b32 v19, v67, v17
	ds_bpermute_b32 v18, v67, v16
	v_mov_b64_e32 v[120:121], s[4:5]
	s_mov_b32 s4, 0x3a800000
	s_waitcnt lgkmcnt(0)
	v_pk_add_f32 v[16:17], v[16:17], v[18:19]
	ds_bpermute_b32 v19, v69, v17
	ds_bpermute_b32 v18, v69, v16
	s_waitcnt lgkmcnt(0)
	v_pk_add_f32 v[16:17], v[16:17], v[18:19]
	ds_bpermute_b32 v19, v71, v17
	ds_bpermute_b32 v18, v71, v16
	s_waitcnt lgkmcnt(0)
	v_pk_add_f32 v[16:17], v[16:17], v[18:19]
	ds_bpermute_b32 v19, v73, v17
	ds_bpermute_b32 v18, v73, v16
	s_waitcnt lgkmcnt(0)
	v_pk_add_f32 v[16:17], v[16:17], v[18:19]
	ds_bpermute_b32 v19, v123, v17
	ds_bpermute_b32 v18, v123, v16
	s_waitcnt lgkmcnt(0)
	v_pk_add_f32 v[16:17], v[16:17], v[18:19]
	ds_bpermute_b32 v19, v124, v17
	ds_bpermute_b32 v18, v124, v16
	s_waitcnt lgkmcnt(0)
	v_pk_add_f32 v[16:17], v[16:17], v[18:19]
	s_nop 0
	v_pk_fma_f32 v[126:127], v[16:17], s[4:5], v[120:121] op_sel_hi:[1,0,0]
	s_nop 0
	v_mul_f32_e32 v16, 0x4b800000, v127
	v_cmp_gt_f32_e64 s[8:9], s68, v127
	v_cmp_gt_f32_e32 vcc, s68, v126
	s_nop 0
	v_cndmask_b32_e64 v16, v127, v16, s[8:9]
	v_rsq_f32_e32 v16, v16
	s_nop 0
	v_mul_f32_e32 v17, 0x45800000, v16
	v_cndmask_b32_e64 v122, v16, v17, s[8:9]
	v_pk_mul_f32 v[8:9], v[8:9], v[122:123] op_sel_hi:[1,0]
	v_pk_mul_f32 v[10:11], v[10:11], v[122:123] op_sel_hi:[1,0]
	v_pk_fma_f32 v[16:17], v[0:1], v[8:9], v[4:5]
	v_pk_fma_f32 v[18:19], v[2:3], v[10:11], v[6:7]
	flat_store_dwordx4 v[86:87], v[16:19]
	v_mov_b64_e32 v[0:1], v[162:163]
	v_mov_b64_e32 v[2:3], v[164:165]
	v_mov_b64_e32 v[4:5], v[166:167]
	v_mov_b64_e32 v[6:7], v[168:169]
	v_pk_mul_f32 v[8:9], v[14:15], v[122:123] op_sel_hi:[1,0]
	v_pk_mul_f32 v[10:11], v[12:13], v[122:123] op_sel_hi:[1,0]
	v_pk_fma_f32 v[14:15], v[2:3], v[8:9], v[6:7]
	v_pk_fma_f32 v[12:13], v[0:1], v[10:11], v[4:5]
	flat_store_dwordx4 v[86:87], v[12:15] offset:1024
	v_mov_b64_e32 v[0:1], v[170:171]
	v_mov_b64_e32 v[2:3], v[172:173]
	v_mov_b64_e32 v[4:5], v[174:175]
	v_mov_b64_e32 v[6:7], v[176:177]
	v_pk_mul_f32 v[8:9], v[22:23], v[122:123] op_sel_hi:[1,0]
	v_pk_mul_f32 v[10:11], v[20:21], v[122:123] op_sel_hi:[1,0]
	v_pk_mul_f32 v[22:23], v[24:25], v[122:123] op_sel_hi:[1,0]
	v_pk_mul_f32 v[20:21], v[26:27], v[122:123] op_sel_hi:[1,0]
	v_pk_fma_f32 v[4:5], v[0:1], v[10:11], v[4:5]
	v_pk_fma_f32 v[6:7], v[2:3], v[8:9], v[6:7]
	flat_store_dwordx4 v[86:87], v[4:7] offset:2048
	v_mov_b64_e32 v[0:1], v[178:179]
	v_mov_b64_e32 v[2:3], v[180:181]
	v_mov_b64_e32 v[8:9], v[182:183]
	v_mov_b64_e32 v[10:11], v[184:185]
	v_pk_fma_f32 v[0:1], v[0:1], v[22:23], v[8:9]
	v_mul_f32_e32 v8, 0x4b800000, v126
	v_cndmask_b32_e32 v8, v126, v8, vcc
	v_rsq_f32_e32 v8, v8
	v_pk_fma_f32 v[2:3], v[2:3], v[20:21], v[10:11]
	flat_store_dwordx4 v[86:87], v[0:3] offset:3072
	v_mul_f32_e32 v9, 0x45800000, v8
	v_cndmask_b32_e32 v122, v8, v9, vcc
	v_mov_b64_e32 v[8:9], v[154:155]
	v_mov_b64_e32 v[10:11], v[156:157]
	v_mov_b64_e32 v[20:21], v[158:159]
	v_mov_b64_e32 v[22:23], v[160:161]
	v_pk_mul_f32 v[24:25], v[36:37], v[122:123] op_sel_hi:[1,0]
	v_pk_mul_f32 v[26:27], v[34:35], v[122:123] op_sel_hi:[1,0]
	v_pk_mul_f32 v[34:35], v[60:61], v[122:123] op_sel_hi:[1,0]
	v_pk_mul_f32 v[36:37], v[38:39], v[122:123] op_sel_hi:[1,0]
	v_pk_mul_f32 v[38:39], v[118:119], v[122:123] op_sel_hi:[1,0]
	v_pk_mul_f32 v[60:61], v[62:63], v[122:123] op_sel_hi:[1,0]
	ds_bpermute_b32 v62, v67, v65
	s_waitcnt lgkmcnt(0)
	v_add_f32_e32 v62, v65, v62
	ds_bpermute_b32 v63, v69, v62
	s_waitcnt lgkmcnt(0)
	v_add_f32_e32 v62, v62, v63
	ds_bpermute_b32 v63, v71, v62
	s_waitcnt lgkmcnt(0)
	v_add_f32_e32 v62, v62, v63
	ds_bpermute_b32 v63, v73, v62
	s_waitcnt lgkmcnt(0)
	v_add_f32_e32 v62, v62, v63
	ds_bpermute_b32 v63, v123, v62
	s_waitcnt lgkmcnt(0)
	v_add_f32_e32 v62, v62, v63
	ds_bpermute_b32 v63, v124, v62
	s_waitcnt lgkmcnt(0)
	v_add_f32_e32 v65, v62, v63
	v_fmamk_f32 v115, v65, 0xba800000, v115
	v_fmac_f32_e32 v114, 0xba800000, v65
	v_fmamk_f32 v117, v65, 0xba800000, v117
	v_fmac_f32_e32 v116, 0xba800000, v65
	v_pk_mul_f32 v[62:63], v[116:117], v[116:117]
	v_pk_mul_f32 v[118:119], v[114:115], v[114:115]
	v_fmamk_f32 v43, v65, 0xba800000, v43
	v_pk_mov_b32 v[126:127], v[118:119], v[62:63] op_sel:[1,0]
	v_mov_b32_e32 v119, v63
	v_pk_add_f32 v[62:63], v[126:127], v[118:119]
	v_fmac_f32_e32 v42, 0xba800000, v65
	v_fmamk_f32 v113, v65, 0xba800000, v113
	v_fmac_f32_e32 v112, 0xba800000, v65
	v_pk_add_f32 v[62:63], v[62:63], v[62:63] op_sel_hi:[0,1]
	v_pk_mul_f32 v[118:119], v[112:113], v[112:113]
	v_pk_mul_f32 v[126:127], v[42:43], v[42:43]
	v_fmac_f32_e32 v108, 0xba800000, v65
	v_pk_mov_b32 v[128:129], v[126:127], v[118:119] op_sel:[1,0]
	v_mov_b32_e32 v127, v119
	v_fmamk_f32 v109, v65, 0xba800000, v109
	v_fmac_f32_e32 v110, 0xba800000, v65
	v_mul_f32_e32 v62, v108, v108
	v_pk_add_f32 v[118:119], v[128:129], v[126:127]
	v_fmamk_f32 v111, v65, 0xba800000, v111
	v_pk_fma_f32 v[126:127], v[108:109], v[108:109], v[62:63] op_sel_hi:[1,1,0]
	v_mul_f32_e32 v62, v110, v110
	v_pk_add_f32 v[118:119], v[118:119], v[118:119] op_sel_hi:[0,1]
	v_pk_fma_f32 v[128:129], v[110:111], v[110:111], v[62:63] op_sel_hi:[1,1,0]
	v_fmamk_f32 v107, v65, 0xba800000, v107
	v_fmac_f32_e32 v106, 0xba800000, v65
	v_fmamk_f32 v105, v65, 0xba800000, v105
	v_fmac_f32_e32 v104, 0xba800000, v65
	v_mul_f32_e32 v126, v104, v104
	v_mul_f32_e32 v128, v105, v105
	v_mul_f32_e32 v62, v106, v106
	v_mul_f32_e32 v118, v107, v107
	v_pk_add_f32 v[126:127], v[126:127], v[128:129]
	v_pk_fma_f32 v[8:9], v[8:9], v[26:27], v[20:21]
	v_pk_fma_f32 v[10:11], v[10:11], v[24:25], v[22:23]
	flat_store_dwordx4 v[32:33], v[8:11]
	v_mov_b64_e32 v[20:21], v[162:163]
	v_mov_b64_e32 v[22:23], v[164:165]
	v_mov_b64_e32 v[24:25], v[166:167]
	v_mov_b64_e32 v[26:27], v[168:169]
	v_pk_add_f32 v[62:63], v[62:63], v[118:119]
	v_pk_fma_f32 v[20:21], v[20:21], v[36:37], v[24:25]
	v_pk_fma_f32 v[22:23], v[22:23], v[34:35], v[26:27]
	flat_store_dwordx4 v[32:33], v[20:23] offset:1024
	v_pk_mul_f32 v[34:35], v[30:31], v[122:123] op_sel_hi:[1,0]
	v_pk_mul_f32 v[36:37], v[28:29], v[122:123] op_sel_hi:[1,0]
	v_mov_b64_e32 v[24:25], v[170:171]
	v_mov_b64_e32 v[26:27], v[172:173]
	v_mov_b64_e32 v[28:29], v[174:175]
	v_mov_b64_e32 v[30:31], v[176:177]
	v_pk_add_f32 v[62:63], v[126:127], v[62:63]
	v_pk_fma_f32 v[28:29], v[24:25], v[36:37], v[28:29]
	v_pk_fma_f32 v[30:31], v[26:27], v[34:35], v[30:31]
	flat_store_dwordx4 v[32:33], v[28:31] offset:2048
	v_mov_b64_e32 v[24:25], v[178:179]
	v_mov_b64_e32 v[26:27], v[180:181]
	v_mov_b64_e32 v[34:35], v[182:183]
	v_mov_b64_e32 v[36:37], v[184:185]
	v_mov_b32_e32 v118, v62
	v_pk_fma_f32 v[24:25], v[24:25], v[60:61], v[34:35]
	v_pk_fma_f32 v[26:27], v[26:27], v[38:39], v[36:37]
	flat_store_dwordx4 v[32:33], v[24:27] offset:3072
	ds_bpermute_b32 v32, v67, v125
	s_waitcnt lgkmcnt(0)
	v_add_f32_e32 v32, v125, v32
	ds_bpermute_b32 v33, v69, v32
	s_waitcnt lgkmcnt(0)
	v_add_f32_e32 v32, v32, v33
	ds_bpermute_b32 v33, v71, v32
	s_waitcnt lgkmcnt(0)
	v_add_f32_e32 v32, v32, v33
	ds_bpermute_b32 v33, v73, v32
	s_waitcnt lgkmcnt(0)
	v_add_f32_e32 v32, v32, v33
	ds_bpermute_b32 v33, v123, v32
	s_waitcnt lgkmcnt(0)
	v_add_f32_e32 v32, v32, v33
	ds_bpermute_b32 v33, v124, v32
	s_waitcnt lgkmcnt(0)
	v_add_f32_e32 v60, v32, v33
	v_fmamk_f32 v45, v60, 0xba800000, v45
	v_fmac_f32_e32 v44, 0xba800000, v60
	v_fmamk_f32 v51, v60, 0xba800000, v51
	v_fmac_f32_e32 v50, 0xba800000, v60
	v_pk_mul_f32 v[32:33], v[50:51], v[50:51]
	v_pk_mul_f32 v[34:35], v[44:45], v[44:45]
	v_fmamk_f32 v57, v60, 0xba800000, v57
	v_pk_mov_b32 v[36:37], v[34:35], v[32:33] op_sel:[1,0]
	v_mov_b32_e32 v35, v33
	v_pk_add_f32 v[32:33], v[36:37], v[34:35]
	v_fmac_f32_e32 v56, 0xba800000, v60
	v_fmamk_f32 v59, v60, 0xba800000, v59
	v_fmac_f32_e32 v58, 0xba800000, v60
	v_pk_add_f32 v[32:33], v[32:33], v[32:33] op_sel_hi:[0,1]
	v_pk_mul_f32 v[34:35], v[58:59], v[58:59]
	v_pk_mul_f32 v[36:37], v[56:57], v[56:57]
	v_fmac_f32_e32 v52, 0xba800000, v60
	v_pk_mov_b32 v[38:39], v[36:37], v[34:35] op_sel:[1,0]
	v_mov_b32_e32 v37, v35
	v_fmamk_f32 v53, v60, 0xba800000, v53
	v_fmac_f32_e32 v54, 0xba800000, v60
	v_mul_f32_e32 v32, v52, v52
	v_pk_add_f32 v[34:35], v[38:39], v[36:37]
	v_fmamk_f32 v55, v60, 0xba800000, v55
	v_pk_fma_f32 v[36:37], v[52:53], v[52:53], v[32:33] op_sel_hi:[1,1,0]
	v_mul_f32_e32 v32, v54, v54
	v_pk_add_f32 v[34:35], v[34:35], v[34:35] op_sel_hi:[0,1]
	v_pk_fma_f32 v[38:39], v[54:55], v[54:55], v[32:33] op_sel_hi:[1,1,0]
	v_fmamk_f32 v49, v60, 0xba800000, v49
	v_fmac_f32_e32 v48, 0xba800000, v60
	v_fmamk_f32 v47, v60, 0xba800000, v47
	v_fmac_f32_e32 v46, 0xba800000, v60
	v_mul_f32_e32 v36, v46, v46
	v_mul_f32_e32 v38, v47, v47
	v_mul_f32_e32 v32, v48, v48
	v_mul_f32_e32 v34, v49, v49
	v_pk_add_f32 v[36:37], v[36:37], v[38:39]
	v_pk_add_f32 v[32:33], v[32:33], v[34:35]
	s_nop 0
	v_pk_add_f32 v[60:61], v[36:37], v[32:33]
	v_mov_b64_e32 v[32:33], v[154:155]
	v_mov_b64_e32 v[34:35], v[156:157]
	v_mov_b64_e32 v[36:37], v[158:159]
	v_mov_b64_e32 v[38:39], v[160:161]
	v_mov_b32_e32 v119, v60
	v_mov_b32_e32 v60, v63
	v_pk_add_f32 v[60:61], v[118:119], v[60:61]
	ds_bpermute_b32 v63, v67, v61
	ds_bpermute_b32 v62, v67, v60
	s_waitcnt lgkmcnt(0)
	v_pk_add_f32 v[60:61], v[60:61], v[62:63]
	ds_bpermute_b32 v63, v69, v61
	ds_bpermute_b32 v62, v69, v60
	s_waitcnt lgkmcnt(0)
	v_pk_add_f32 v[60:61], v[60:61], v[62:63]
	ds_bpermute_b32 v63, v71, v61
	ds_bpermute_b32 v62, v71, v60
	s_waitcnt lgkmcnt(0)
	v_pk_add_f32 v[60:61], v[60:61], v[62:63]
	ds_bpermute_b32 v63, v73, v61
	ds_bpermute_b32 v62, v73, v60
	s_waitcnt lgkmcnt(0)
	v_pk_add_f32 v[60:61], v[60:61], v[62:63]
	ds_bpermute_b32 v63, v123, v61
	ds_bpermute_b32 v62, v123, v60
	s_waitcnt lgkmcnt(0)
	v_pk_add_f32 v[60:61], v[60:61], v[62:63]
	ds_bpermute_b32 v63, v124, v61
	ds_bpermute_b32 v62, v124, v60
	s_waitcnt lgkmcnt(0)
	v_pk_add_f32 v[60:61], v[60:61], v[62:63]
	s_nop 0
	v_pk_fma_f32 v[118:119], v[60:61], s[4:5], v[120:121] op_sel_hi:[1,0,0]
	s_nop 0
	v_mul_f32_e32 v60, 0x4b800000, v119
	v_cmp_gt_f32_e64 s[8:9], s68, v119
	v_cmp_gt_f32_e32 vcc, s68, v118
	s_nop 0
	v_cndmask_b32_e64 v60, v119, v60, s[8:9]
	v_rsq_f32_e32 v60, v60
	s_nop 0
	v_mul_f32_e32 v61, 0x45800000, v60
	v_cndmask_b32_e64 v120, v60, v61, s[8:9]
	v_pk_mul_f32 v[50:51], v[50:51], v[120:121] op_sel_hi:[1,0]
	v_pk_mul_f32 v[44:45], v[44:45], v[120:121] op_sel_hi:[1,0]
	v_pk_mul_f32 v[46:47], v[46:47], v[120:121] op_sel_hi:[1,0]
	v_pk_fma_f32 v[60:61], v[32:33], v[44:45], v[36:37]
	v_pk_fma_f32 v[62:63], v[34:35], v[50:51], v[38:39]
	flat_store_dwordx4 v[40:41], v[60:63]
	v_mov_b64_e32 v[32:33], v[162:163]
	v_mov_b64_e32 v[34:35], v[164:165]
	v_mov_b64_e32 v[36:37], v[166:167]
	v_mov_b64_e32 v[38:39], v[168:169]
	v_pk_mul_f32 v[44:45], v[58:59], v[120:121] op_sel_hi:[1,0]
	v_pk_mul_f32 v[50:51], v[56:57], v[120:121] op_sel_hi:[1,0]
	v_pk_fma_f32 v[58:59], v[34:35], v[44:45], v[38:39]
	v_pk_fma_f32 v[56:57], v[32:33], v[50:51], v[36:37]
	flat_store_dwordx4 v[40:41], v[56:59] offset:1024
	v_mov_b64_e32 v[32:33], v[170:171]
	v_mov_b64_e32 v[34:35], v[172:173]
	v_mov_b64_e32 v[36:37], v[174:175]
	v_mov_b64_e32 v[38:39], v[176:177]
	v_pk_mul_f32 v[44:45], v[54:55], v[120:121] op_sel_hi:[1,0]
	v_pk_mul_f32 v[50:51], v[52:53], v[120:121] op_sel_hi:[1,0]
	v_pk_fma_f32 v[54:55], v[34:35], v[44:45], v[38:39]
	v_pk_fma_f32 v[52:53], v[32:33], v[50:51], v[36:37]
	flat_store_dwordx4 v[40:41], v[52:55] offset:2048
	v_mov_b64_e32 v[32:33], v[178:179]
	v_mov_b64_e32 v[34:35], v[180:181]
	v_mov_b64_e32 v[36:37], v[182:183]
	v_mov_b64_e32 v[38:39], v[184:185]
	v_pk_mul_f32 v[44:45], v[48:49], v[120:121] op_sel_hi:[1,0]
	v_pk_fma_f32 v[48:49], v[32:33], v[46:47], v[36:37]
	v_mul_f32_e32 v32, 0x4b800000, v118
	v_cndmask_b32_e32 v32, v118, v32, vcc
	v_rsq_f32_e32 v32, v32
	v_pk_fma_f32 v[50:51], v[34:35], v[44:45], v[38:39]
	flat_store_dwordx4 v[40:41], v[48:51] offset:3072
	v_mul_f32_e32 v33, 0x45800000, v32
	v_cndmask_b32_e32 v118, v32, v33, vcc
	v_mov_b64_e32 v[32:33], v[154:155]
	v_mov_b64_e32 v[34:35], v[156:157]
	v_mov_b64_e32 v[36:37], v[158:159]
	v_mov_b64_e32 v[38:39], v[160:161]
	v_pk_mul_f32 v[40:41], v[116:117], v[118:119] op_sel_hi:[1,0]
	v_pk_mul_f32 v[44:45], v[114:115], v[118:119] op_sel_hi:[1,0]
	v_pk_mul_f32 v[112:113], v[112:113], v[118:119] op_sel_hi:[1,0]
	v_pk_mul_f32 v[110:111], v[110:111], v[118:119] op_sel_hi:[1,0]
	v_pk_mul_f32 v[108:109], v[108:109], v[118:119] op_sel_hi:[1,0]
	s_andn2_b64 vcc, exec, s[14:15]
	v_pk_fma_f32 v[44:45], v[32:33], v[44:45], v[36:37]
	v_pk_fma_f32 v[46:47], v[34:35], v[40:41], v[38:39]
	flat_store_dwordx4 v[102:103], v[44:47]
	v_mov_b64_e32 v[32:33], v[162:163]
	v_mov_b64_e32 v[34:35], v[164:165]
	v_mov_b64_e32 v[36:37], v[166:167]
	v_mov_b64_e32 v[38:39], v[168:169]
	v_pk_mul_f32 v[40:41], v[42:43], v[118:119] op_sel_hi:[1,0]
	v_pk_fma_f32 v[42:43], v[34:35], v[112:113], v[38:39]
	v_pk_fma_f32 v[40:41], v[32:33], v[40:41], v[36:37]
	flat_store_dwordx4 v[102:103], v[40:43] offset:1024
	v_mov_b64_e32 v[32:33], v[170:171]
	v_mov_b64_e32 v[34:35], v[172:173]
	v_mov_b64_e32 v[36:37], v[174:175]
	v_mov_b64_e32 v[38:39], v[176:177]
	v_pk_fma_f32 v[36:37], v[32:33], v[108:109], v[36:37]
	v_pk_fma_f32 v[38:39], v[34:35], v[110:111], v[38:39]
	flat_store_dwordx4 v[102:103], v[36:39] offset:2048
	v_pk_mul_f32 v[108:109], v[106:107], v[118:119] op_sel_hi:[1,0]
	v_pk_mul_f32 v[110:111], v[104:105], v[118:119] op_sel_hi:[1,0]
	v_mov_b64_e32 v[32:33], v[178:179]
	v_mov_b64_e32 v[34:35], v[180:181]
	v_mov_b64_e32 v[104:105], v[182:183]
	v_mov_b64_e32 v[106:107], v[184:185]
	v_pk_fma_f32 v[32:33], v[32:33], v[110:111], v[104:105]
	v_pk_fma_f32 v[34:35], v[34:35], v[108:109], v[106:107]
	flat_store_dwordx4 v[102:103], v[32:35] offset:3072
	s_cbranch_vccnz .LBB0_224
	v_lshl_add_u64 v[102:103], v[94:95], 0, s[2:3]
	v_mov_b64_e32 v[94:95], s[60:61]
	v_mad_u64_u32 v[104:105], s[4:5], v102, s7, v[94:95]
	v_mad_i32_i24 v105, v103, s7, v105
	v_lshl_add_u64 v[110:111], v[104:105], 0, s[30:31]
	v_lshlrev_b32_e32 v152, 2, v66
	v_lshl_add_u64 v[112:113], v[104:105], 0, v[152:153]
	v_lshl_add_u64 v[106:107], v[110:111], 0, v[152:153]
	global_load_dwordx4 v[186:189], v[112:113], off offset:1024
	global_load_dwordx4 v[190:193], v[112:113], off offset:2048
	global_load_dwordx4 v[194:197], v[112:113], off offset:3072
	flat_load_dwordx4 v[102:105], v[112:113]
	s_nop 0
	global_load_dwordx4 v[198:201], v[106:107], off offset:1024
	global_load_dwordx4 v[202:205], v[106:107], off offset:2048
	global_load_dwordx4 v[224:227], v[106:107], off offset:3072
	flat_load_dwordx4 v[106:109], v[106:107]
	s_waitcnt vmcnt(0) lgkmcnt(0)
	v_pk_add_f32 v[108:109], v[108:109], 1.0 op_sel_hi:[1,0]
	v_pk_add_f32 v[106:107], v[106:107], 1.0 op_sel_hi:[1,0]
	v_pk_fma_f32 v[18:19], v[18:19], v[108:109], v[104:105]
	v_pk_fma_f32 v[16:17], v[16:17], v[106:107], v[102:103]
	s_nop 0
	v_cvt_pk_bf16_f32 v16, v16, v17
	v_cvt_pk_bf16_f32 v17, v18, v19
	flat_store_dwordx2 v[84:85], v[16:17]
	v_lshlrev_b32_e32 v16, 2, v68
	v_mov_b32_e32 v17, v153
	v_lshl_add_u64 v[18:19], v[110:111], 0, v[16:17]
	v_mov_b64_e32 v[102:103], v[186:187]
	v_mov_b64_e32 v[104:105], v[188:189]
	v_mov_b64_e32 v[106:107], v[198:199]
	v_mov_b64_e32 v[108:109], v[200:201]
	v_pk_add_f32 v[18:19], v[108:109], 1.0 op_sel_hi:[1,0]
	v_pk_add_f32 v[106:107], v[106:107], 1.0 op_sel_hi:[1,0]
	v_pk_fma_f32 v[14:15], v[14:15], v[18:19], v[104:105]
	v_pk_fma_f32 v[12:13], v[12:13], v[106:107], v[102:103]
	s_nop 0
	v_cvt_pk_bf16_f32 v12, v12, v13
	v_cvt_pk_bf16_f32 v13, v14, v15
	flat_store_dwordx2 v[84:85], v[12:13] offset:512
	v_lshlrev_b32_e32 v12, 2, v70
	v_mov_b32_e32 v13, v153
	v_lshl_add_u64 v[14:15], v[110:111], 0, v[12:13]
	v_mov_b64_e32 v[102:103], v[190:191]
	v_mov_b64_e32 v[104:105], v[192:193]
	v_mov_b64_e32 v[106:107], v[202:203]
	v_mov_b64_e32 v[108:109], v[204:205]
	v_pk_add_f32 v[14:15], v[108:109], 1.0 op_sel_hi:[1,0]
	v_pk_add_f32 v[18:19], v[106:107], 1.0 op_sel_hi:[1,0]
	v_pk_fma_f32 v[6:7], v[6:7], v[14:15], v[104:105]
	v_pk_fma_f32 v[4:5], v[4:5], v[18:19], v[102:103]
	s_nop 0
	v_cvt_pk_bf16_f32 v4, v4, v5
	v_cvt_pk_bf16_f32 v5, v6, v7
	flat_store_dwordx2 v[84:85], v[4:5] offset:1024
	v_lshlrev_b32_e32 v4, 2, v72
	v_mov_b32_e32 v5, v153
	v_lshl_add_u64 v[6:7], v[110:111], 0, v[4:5]
	v_mov_b64_e32 v[102:103], v[194:195]
	v_mov_b64_e32 v[104:105], v[196:197]
	v_mov_b64_e32 v[106:107], v[224:225]
	v_mov_b64_e32 v[108:109], v[226:227]
	v_pk_add_f32 v[6:7], v[108:109], 1.0 op_sel_hi:[1,0]
	v_pk_add_f32 v[14:15], v[106:107], 1.0 op_sel_hi:[1,0]
	v_pk_fma_f32 v[2:3], v[2:3], v[6:7], v[104:105]
	v_pk_fma_f32 v[0:1], v[0:1], v[14:15], v[102:103]
	s_nop 0
	v_cvt_pk_bf16_f32 v0, v0, v1
	v_cvt_pk_bf16_f32 v1, v2, v3
	flat_store_dwordx2 v[84:85], v[0:1] offset:1536
	v_lshl_add_u64 v[0:1], v[92:93], 0, s[2:3]
	v_mad_u64_u32 v[2:3], s[4:5], v0, s7, v[94:95]
	v_mad_i32_i24 v3, v1, s7, v3
	v_lshl_add_u64 v[0:1], v[2:3], 0, s[30:31]
	v_lshl_add_u64 v[2:3], v[2:3], 0, v[152:153]
	v_lshl_add_u64 v[6:7], v[0:1], 0, v[152:153]
	global_load_dwordx4 v[186:189], v[2:3], off offset:1024
	global_load_dwordx4 v[190:193], v[2:3], off offset:2048
	global_load_dwordx4 v[194:197], v[2:3], off offset:3072
	flat_load_dwordx4 v[102:105], v[2:3]
	global_load_dwordx4 v[198:201], v[6:7], off offset:1024
	global_load_dwordx4 v[202:205], v[6:7], off offset:2048
	global_load_dwordx4 v[224:227], v[6:7], off offset:3072
	flat_load_dwordx4 v[106:109], v[6:7]
	s_waitcnt vmcnt(0) lgkmcnt(0)
	v_pk_add_f32 v[6:7], v[108:109], 1.0 op_sel_hi:[1,0]
	v_pk_add_f32 v[14:15], v[106:107], 1.0 op_sel_hi:[1,0]
	v_pk_fma_f32 v[6:7], v[10:11], v[6:7], v[104:105]
	v_pk_fma_f32 v[8:9], v[8:9], v[14:15], v[102:103]
	v_lshl_add_u64 v[10:11], v[82:83], 0, v[96:97]
	v_cvt_pk_bf16_f32 v8, v8, v9
	v_cvt_pk_bf16_f32 v9, v6, v7
	flat_store_dwordx2 v[10:11], v[8:9]
	v_lshl_add_u64 v[14:15], v[0:1], 0, v[16:17]
	v_mov_b64_e32 v[6:7], v[186:187]
	v_mov_b64_e32 v[8:9], v[188:189]
	v_mov_b64_e32 v[102:103], v[198:199]
	v_mov_b64_e32 v[104:105], v[200:201]
	v_pk_add_f32 v[14:15], v[104:105], 1.0 op_sel_hi:[1,0]
	v_pk_add_f32 v[18:19], v[102:103], 1.0 op_sel_hi:[1,0]
	v_pk_fma_f32 v[8:9], v[22:23], v[14:15], v[8:9]
	v_pk_fma_f32 v[6:7], v[20:21], v[18:19], v[6:7]
	v_lshl_add_u64 v[14:15], v[0:1], 0, v[12:13]
	v_cvt_pk_bf16_f32 v6, v6, v7
	v_cvt_pk_bf16_f32 v7, v8, v9
	flat_store_dwordx2 v[10:11], v[6:7] offset:512
	v_mov_b64_e32 v[6:7], v[190:191]
	v_mov_b64_e32 v[8:9], v[192:193]
	v_lshl_add_u64 v[0:1], v[0:1], 0, v[4:5]
	v_mov_b64_e32 v[18:19], v[202:203]
	v_mov_b64_e32 v[20:21], v[204:205]
	v_pk_add_f32 v[14:15], v[20:21], 1.0 op_sel_hi:[1,0]
	v_pk_add_f32 v[18:19], v[18:19], 1.0 op_sel_hi:[1,0]
	v_pk_fma_f32 v[8:9], v[30:31], v[14:15], v[8:9]
	v_pk_fma_f32 v[6:7], v[28:29], v[18:19], v[6:7]
	s_nop 0
	v_cvt_pk_bf16_f32 v6, v6, v7
	v_cvt_pk_bf16_f32 v7, v8, v9
	flat_store_dwordx2 v[10:11], v[6:7] offset:1024
	v_mov_b64_e32 v[6:7], v[194:195]
	v_mov_b64_e32 v[8:9], v[196:197]
	s_nop 0
	v_mov_b64_e32 v[0:1], v[224:225]
	v_mov_b64_e32 v[2:3], v[226:227]
	v_pk_add_f32 v[2:3], v[2:3], 1.0 op_sel_hi:[1,0]
	v_pk_add_f32 v[0:1], v[0:1], 1.0 op_sel_hi:[1,0]
	v_pk_fma_f32 v[2:3], v[26:27], v[2:3], v[8:9]
	v_pk_fma_f32 v[0:1], v[24:25], v[0:1], v[6:7]
	s_nop 0
	v_cvt_pk_bf16_f32 v0, v0, v1
	v_cvt_pk_bf16_f32 v1, v2, v3
	flat_store_dwordx2 v[10:11], v[0:1] offset:1536
	v_lshl_add_u64 v[0:1], v[90:91], 0, s[2:3]
	v_mad_u64_u32 v[2:3], s[4:5], v0, s7, v[94:95]
	v_mad_i32_i24 v3, v1, s7, v3
	v_lshl_add_u64 v[0:1], v[2:3], 0, s[30:31]
	v_lshl_add_u64 v[2:3], v[2:3], 0, v[152:153]
	v_lshl_add_u64 v[10:11], v[0:1], 0, v[152:153]
	global_load_dwordx4 v[186:189], v[2:3], off offset:1024
	global_load_dwordx4 v[190:193], v[2:3], off offset:2048
	global_load_dwordx4 v[194:197], v[2:3], off offset:3072
	flat_load_dwordx4 v[6:9], v[2:3]
	global_load_dwordx4 v[198:201], v[10:11], off offset:1024
	global_load_dwordx4 v[202:205], v[10:11], off offset:2048
	global_load_dwordx4 v[224:227], v[10:11], off offset:3072
	flat_load_dwordx4 v[18:21], v[10:11]
	s_waitcnt vmcnt(0) lgkmcnt(0)
	v_pk_add_f32 v[10:11], v[20:21], 1.0 op_sel_hi:[1,0]
	v_pk_add_f32 v[14:15], v[18:19], 1.0 op_sel_hi:[1,0]
	v_pk_fma_f32 v[8:9], v[62:63], v[10:11], v[8:9]
	v_pk_fma_f32 v[6:7], v[60:61], v[14:15], v[6:7]
	v_lshl_add_u64 v[10:11], v[82:83], 0, v[100:101]
	v_cvt_pk_bf16_f32 v6, v6, v7
	v_cvt_pk_bf16_f32 v7, v8, v9
	flat_store_dwordx2 v[10:11], v[6:7]
	v_lshl_add_u64 v[14:15], v[0:1], 0, v[16:17]
	v_mov_b64_e32 v[6:7], v[186:187]
	v_mov_b64_e32 v[8:9], v[188:189]
	v_mov_b64_e32 v[18:19], v[198:199]
	v_mov_b64_e32 v[20:21], v[200:201]
	v_pk_add_f32 v[14:15], v[20:21], 1.0 op_sel_hi:[1,0]
	v_pk_add_f32 v[18:19], v[18:19], 1.0 op_sel_hi:[1,0]
	v_pk_fma_f32 v[8:9], v[58:59], v[14:15], v[8:9]
	v_pk_fma_f32 v[6:7], v[56:57], v[18:19], v[6:7]
	v_lshl_add_u64 v[14:15], v[0:1], 0, v[12:13]
	v_cvt_pk_bf16_f32 v6, v6, v7
	v_cvt_pk_bf16_f32 v7, v8, v9
	flat_store_dwordx2 v[10:11], v[6:7] offset:512
	v_mov_b64_e32 v[6:7], v[190:191]
	v_mov_b64_e32 v[8:9], v[192:193]
	v_lshl_add_u64 v[0:1], v[0:1], 0, v[4:5]
	v_mov_b64_e32 v[18:19], v[202:203]
	v_mov_b64_e32 v[20:21], v[204:205]
	v_pk_add_f32 v[14:15], v[20:21], 1.0 op_sel_hi:[1,0]
	v_pk_add_f32 v[18:19], v[18:19], 1.0 op_sel_hi:[1,0]
	v_pk_fma_f32 v[8:9], v[54:55], v[14:15], v[8:9]
	v_pk_fma_f32 v[6:7], v[52:53], v[18:19], v[6:7]
	s_nop 0
	v_cvt_pk_bf16_f32 v6, v6, v7
	v_cvt_pk_bf16_f32 v7, v8, v9
	flat_store_dwordx2 v[10:11], v[6:7] offset:1024
	v_mov_b64_e32 v[6:7], v[194:195]
	v_mov_b64_e32 v[8:9], v[196:197]
	s_nop 0
	v_mov_b64_e32 v[0:1], v[224:225]
	v_mov_b64_e32 v[2:3], v[226:227]
	v_pk_add_f32 v[2:3], v[2:3], 1.0 op_sel_hi:[1,0]
	v_pk_add_f32 v[0:1], v[0:1], 1.0 op_sel_hi:[1,0]
	v_pk_fma_f32 v[2:3], v[50:51], v[2:3], v[8:9]
	v_pk_fma_f32 v[0:1], v[48:49], v[0:1], v[6:7]
	s_nop 0
	v_cvt_pk_bf16_f32 v0, v0, v1
	v_cvt_pk_bf16_f32 v1, v2, v3
	flat_store_dwordx2 v[10:11], v[0:1] offset:1536
	v_lshl_add_u64 v[0:1], v[88:89], 0, s[2:3]
	v_mad_u64_u32 v[2:3], s[4:5], v0, s7, v[94:95]
	v_mad_i32_i24 v3, v1, s7, v3
	v_lshl_add_u64 v[0:1], v[2:3], 0, s[30:31]
	v_lshl_add_u64 v[2:3], v[2:3], 0, v[152:153]
	v_lshl_add_u64 v[10:11], v[0:1], 0, v[152:153]
	global_load_dwordx4 v[186:189], v[2:3], off offset:1024
	global_load_dwordx4 v[190:193], v[2:3], off offset:2048
	global_load_dwordx4 v[194:197], v[2:3], off offset:3072
	flat_load_dwordx4 v[6:9], v[2:3]
	global_load_dwordx4 v[198:201], v[10:11], off offset:1024
	global_load_dwordx4 v[202:205], v[10:11], off offset:2048
	global_load_dwordx4 v[224:227], v[10:11], off offset:3072
	flat_load_dwordx4 v[18:21], v[10:11]
	s_waitcnt vmcnt(0) lgkmcnt(0)
	v_pk_add_f32 v[10:11], v[20:21], 1.0 op_sel_hi:[1,0]
	v_pk_add_f32 v[14:15], v[18:19], 1.0 op_sel_hi:[1,0]
	v_pk_fma_f32 v[8:9], v[46:47], v[10:11], v[8:9]
	v_pk_fma_f32 v[6:7], v[44:45], v[14:15], v[6:7]
	v_lshl_add_u64 v[18:19], v[82:83], 0, v[98:99]
	v_cvt_pk_bf16_f32 v6, v6, v7
	v_cvt_pk_bf16_f32 v7, v8, v9
	flat_store_dwordx2 v[18:19], v[6:7]
	v_lshl_add_u64 v[10:11], v[0:1], 0, v[16:17]
	v_mov_b64_e32 v[6:7], v[186:187]
	v_mov_b64_e32 v[8:9], v[188:189]
	v_mov_b64_e32 v[14:15], v[198:199]
	v_mov_b64_e32 v[16:17], v[200:201]
	v_pk_add_f32 v[10:11], v[16:17], 1.0 op_sel_hi:[1,0]
	v_pk_add_f32 v[14:15], v[14:15], 1.0 op_sel_hi:[1,0]
	v_pk_fma_f32 v[8:9], v[42:43], v[10:11], v[8:9]
	v_pk_fma_f32 v[6:7], v[40:41], v[14:15], v[6:7]
	v_lshl_add_u64 v[10:11], v[0:1], 0, v[12:13]
	v_cvt_pk_bf16_f32 v6, v6, v7
	v_cvt_pk_bf16_f32 v7, v8, v9
	flat_store_dwordx2 v[18:19], v[6:7] offset:512
	v_mov_b64_e32 v[6:7], v[190:191]
	v_mov_b64_e32 v[8:9], v[192:193]
	v_lshl_add_u64 v[0:1], v[0:1], 0, v[4:5]
	v_mov_b64_e32 v[10:11], v[202:203]
	v_mov_b64_e32 v[12:13], v[204:205]
	v_pk_add_f32 v[12:13], v[12:13], 1.0 op_sel_hi:[1,0]
	v_pk_add_f32 v[10:11], v[10:11], 1.0 op_sel_hi:[1,0]
	v_pk_fma_f32 v[8:9], v[38:39], v[12:13], v[8:9]
	v_pk_fma_f32 v[6:7], v[36:37], v[10:11], v[6:7]
	s_nop 0
	v_cvt_pk_bf16_f32 v6, v6, v7
	v_cvt_pk_bf16_f32 v7, v8, v9
	flat_store_dwordx2 v[18:19], v[6:7] offset:1024
	v_mov_b64_e32 v[6:7], v[194:195]
	v_mov_b64_e32 v[8:9], v[196:197]
	s_nop 0
	v_mov_b64_e32 v[0:1], v[224:225]
	v_mov_b64_e32 v[2:3], v[226:227]
	v_pk_add_f32 v[2:3], v[2:3], 1.0 op_sel_hi:[1,0]
	v_pk_add_f32 v[0:1], v[0:1], 1.0 op_sel_hi:[1,0]
	v_pk_fma_f32 v[2:3], v[34:35], v[2:3], v[8:9]
	v_pk_fma_f32 v[0:1], v[32:33], v[0:1], v[6:7]
	s_nop 0
	v_cvt_pk_bf16_f32 v0, v0, v1
	v_cvt_pk_bf16_f32 v1, v2, v3
	flat_store_dwordx2 v[18:19], v[0:1] offset:1536
	s_branch .LBB0_224
